# non-temporal (nt) hint on read-once streaming loads: weight-conversion tile loads at the attention tail, rmsnorm row loads (layer and final), out-projection residual loads
# baseline (speedup 1.0000x reference)
; template <bool F32OUT>
; DI void rmsnorm_rows(const float* X, const float* __restrict__ g, void* outp, int nrows, unsigned char* __restrict__ out8 = nullptr) {
;   int tidx = threadIdx.x; asm volatile("" : "+v"(tidx));
;   const int lane = tidx & 63, gw = blockIdx.x * 8 + (tidx >> 6), nw = gridDim.x * 8;
;   for (int row = gw; row < nrows; row += nw) {
;     const f32x4* xr = (const f32x4*)(X + (size_t)row * 2048);
;     f32x4 v[8];
;     float ss = 0.f;
; #pragma unroll
;     for (int i = 0; i < 8; ++i) { v[i] = xr[lane + 64 * i]; ss += v[i][0] * v[i][0] + v[i][1] * v[i][1] + v[i][2] * v[i][2] + v[i][3] * v[i][3]; }
;     ss = wave_sum(ss);
;     const float r = rsqrtf(ss * (1.f / 2048.f) + 1e-6f);
; #pragma unroll
;     for (int i = 0; i < 8; ++i) {
;       const f32x4 gg = ((const f32x4*)g)[lane + 64 * i];
;       f32x4 o = {v[i][0] * r * gg[0], v[i][1] * r * gg[1], v[i][2] * r * gg[2], v[i][3] * r * gg[3]};
;       if (F32OUT) ((f32x4*)((float*)outp + (size_t)row * 2048))[lane + 64 * i] = o;
;       else { u32x2 pk = {pk2(o[0], o[1]), pk2(o[2], o[3])}; ((u32x2*)((u16*)outp + (size_t)row * 2048))[lane + 64 * i] = pk; }
;       if (!F32OUT && out8) ((unsigned*)(out8 + (size_t)row * 2048))[lane + 64 * i] = pk4_fp8(o[0] * H_SCALE, o[1] * H_SCALE, o[2] * H_SCALE, o[3] * H_SCALE);
;     }
.LBB0_39:
	global_load_dwordx4 v[76:79], v[68:69], off offset:-4096 nt
	global_load_dwordx4 v[58:61], v[68:69], off offset:-3072 nt
	global_load_dwordx4 v[54:57], v[68:69], off offset:-2048 nt
	global_load_dwordx4 v[50:53], v[68:69], off offset:-1024 nt
	global_load_dwordx4 v[46:49], v[68:69], off nt
	global_load_dwordx4 v[42:45], v[68:69], off offset:1024 nt
	global_load_dwordx4 v[38:41], v[68:69], off offset:2048 nt
	global_load_dwordx4 v[34:37], v[68:69], off offset:3072 nt
	s_waitcnt vmcnt(7)
	v_mul_f32_e32 v0, v77, v77
	s_waitcnt vmcnt(6)
	v_mul_f32_e32 v63, v59, v59
	s_waitcnt vmcnt(5)
	v_mul_f32_e32 v96, v55, v55
	v_fmac_f32_e32 v0, v76, v76
	v_fmac_f32_e32 v63, v58, v58
	s_waitcnt vmcnt(4)
	v_mul_f32_e32 v97, v51, v51
	s_waitcnt vmcnt(3)
	v_mov_b32_e32 v72, v47
	s_waitcnt vmcnt(2)
	v_mov_b32_e32 v73, v43
	v_fmac_f32_e32 v96, v54, v54
	v_fmac_f32_e32 v0, v78, v78
	v_fmac_f32_e32 v63, v60, v60
	v_mov_b32_e32 v70, v46
	v_mov_b32_e32 v71, v42
	v_fmac_f32_e32 v97, v50, v50
	v_pk_mul_f32 v[72:73], v[72:73], v[72:73]
	v_fmac_f32_e32 v96, v56, v56
	v_fmac_f32_e32 v0, v79, v79
	v_fmac_f32_e32 v63, v61, v61
	v_mov_b32_e32 v74, v48
	v_mov_b32_e32 v75, v44
	s_waitcnt vmcnt(1)
	v_mov_b32_e32 v90, v39
	s_waitcnt vmcnt(0)
	v_mov_b32_e32 v91, v35
	v_fmac_f32_e32 v97, v52, v52
	v_pk_fma_f32 v[70:71], v[70:71], v[70:71], v[72:73]
	v_fmac_f32_e32 v96, v57, v57
	v_add_f32_e32 v0, v0, v63
	v_mov_b32_e32 v86, v49
	v_mov_b32_e32 v87, v45
	v_mov_b32_e32 v88, v38
	v_mov_b32_e32 v89, v34
	v_pk_mul_f32 v[90:91], v[90:91], v[90:91]
	v_fmac_f32_e32 v97, v53, v53
	v_pk_fma_f32 v[70:71], v[74:75], v[74:75], v[70:71]
	v_add_f32_e32 v0, v0, v96
	v_mov_b32_e32 v92, v40
	v_mov_b32_e32 v93, v36
	v_pk_fma_f32 v[72:73], v[88:89], v[88:89], v[90:91]
	v_pk_fma_f32 v[70:71], v[86:87], v[86:87], v[70:71]
	v_add_f32_e32 v0, v0, v97
	v_mov_b32_e32 v94, v41
	v_mov_b32_e32 v95, v37
	v_pk_fma_f32 v[72:73], v[92:93], v[92:93], v[72:73]
	v_add_f32_e32 v0, v0, v70
	v_pk_fma_f32 v[72:73], v[94:95], v[94:95], v[72:73]
	v_add_f32_e32 v0, v0, v71
	v_add_f32_e32 v0, v0, v72
	v_add_f32_e32 v0, v0, v73
	v_lshl_add_u64 v[70:71], s[82:83], 0, v[64:65]
	v_cndmask_b32_e64 v73, 0, 1, s[22:23]
	v_add_co_u32_e32 v72, vcc, 0x6000000, v70
	v_cmp_ne_u32_e64 s[0:1], 1, v73
	v_addc_co_u32_e32 v73, vcc, 0, v71, vcc
	s_andn2_b64 vcc, exec, s[22:23]
	s_nop 1
	v_add_f32_dpp v0, v0, v0 quad_perm:[1,0,3,2] row_mask:0xf bank_mask:0xf
	s_nop 1
	v_add_f32_dpp v0, v0, v0 quad_perm:[2,3,0,1] row_mask:0xf bank_mask:0xf
	s_nop 1
	v_add_f32_dpp v0, v0, v0 row_half_mirror row_mask:0xf bank_mask:0xf
	s_nop 1
	v_add_f32_dpp v0, v0, v0 row_mirror row_mask:0xf bank_mask:0xf
	v_mov_b32_e32 v63, v0
	s_nop 1
	v_permlane16_swap_b32_e32 v63, v0
	v_add_f32_e32 v0, v0, v63
	v_mov_b32_e32 v63, v0
	s_nop 1
	v_permlane32_swap_b32_e32 v63, v0
	v_add_f32_e32 v0, v0, v63
	v_fmamk_f32 v0, v0, 0x3a000000, v178
	v_mul_f32_e32 v63, 0x4b800000, v0
	v_cmp_gt_f32_e64 s[8:9], s86, v0
	s_nop 1
	v_cndmask_b32_e64 v0, v0, v63, s[8:9]
	v_rsq_f32_e32 v0, v0
	s_nop 0
	v_mul_f32_e32 v63, 0x45800000, v0
	v_cndmask_b32_e64 v74, v0, v63, s[8:9]
	v_pk_mul_f32 v[76:77], v[76:77], v[74:75] op_sel_hi:[1,0]
	v_pk_mul_f32 v[86:87], v[78:79], v[74:75] op_sel_hi:[1,0]
	v_pk_mul_f32 v[78:79], v[2:3], v[76:77]
	v_pk_mul_f32 v[76:77], v[4:5], v[86:87]
	v_cvt_pk_bf16_f32 v86, v78, v79
	v_cvt_pk_bf16_f32 v87, v76, v77
	global_store_dwordx2 v[72:73], v[86:87], off
	v_lshl_add_u64 v[72:73], s[82:83], 0, v[66:67]
	s_cbranch_vccnz .LBB0_41
	v_mul_f32_e32 v0, 0x41800000, v78
	v_mul_f32_e32 v63, 0x41800000, v79
	v_mul_f32_e32 v75, 0x41800000, v76
	v_med3_f32 v0, v0, s93, v223
	v_med3_f32 v63, v63, s93, v223
	v_mov_b32_e32 v76, v1
	v_cvt_pk_fp8_f32 v76, v0, v63
	v_mul_f32_e32 v0, 0x41800000, v77
	v_med3_f32 v63, v75, s93, v223
	v_med3_f32 v0, v0, s93, v223
	v_cvt_pk_fp8_f32 v76, v63, v0 op_sel:[0,0,1]
	global_store_dword v[72:73], v76, off

;     ...
;   for (int t = blockIdx.x; t < ntk * ntn; t += gridDim.x) {
;     const int tk = t % ntk, tn = t / ntk, k0 = tk * 64, n0 = tn * 64;
;     __syncthreads();
; #pragma unroll
;     for (int i = 0; i < 2; ++i) {
;       const int id = tid + 512 * i, kr = id >> 4, n4 = (id & 15) * 4;
;       f32x4 v = {0.f, 0.f, 0.f, 0.f};
;       const int nd = n0 + n4, nsrc = (nvalid < 0) ? nd : (nd < csplit ? nd + coff1 : nd + coff2);
;       if (nd < ((nvalid < 0) ? N : nvalid)) v = *(const f32x4*)(W + (size_t)(k0 + kr) * N + nsrc);
;       tile[kr * 65 + n4 + 0] = v[0]; tile[kr * 65 + n4 + 1] = v[1]; tile[kr * 65 + n4 + 2] = v[2]; tile[kr * 65 + n4 + 3] = v[3];
;     }
.Lcw0_top:
	s_mov_b32 s100, s13
	s_mov_b32 s101, s12
	s_mul_hi_i32 s10, s100, 0x2aaaaaab
	s_lshr_b32 s11, s10, 31
	s_ashr_i32 s10, s10, 3
	s_add_i32 s10, s10, s11
	s_lshl_b32 s14, s10, 6
	s_mul_i32 s15, s10, 0xfffff400
	v_or_b32_e32 v10, s14, v12
	s_movk_i32 s10, 0x800
	v_cmp_gt_i32_e32 vcc, s10, v10
	v_mov_b32_e32 v98, 0
	v_mov_b32_e32 v99, 0
	v_mov_b32_e32 v100, 0
	v_mov_b32_e32 v101, 0
	v_mov_b32_e32 v102, 0
	v_mov_b32_e32 v103, 0
	v_mov_b32_e32 v104, 0
	v_mov_b32_e32 v105, 0
	s_and_saveexec_b64 s[10:11], vcc
	s_add_i32 s16, s15, s101
	v_add_u32_e32 v118, s16, v14
	v_add_u32_e32 v122, s16, v15
	v_ashrrev_i32_e32 v11, 31, v10
	v_ashrrev_i32_e32 v119, 31, v118
	v_ashrrev_i32_e32 v123, 31, v122
	v_lshl_add_u64 v[116:117], v[10:11], 2, s[0:1]
	v_lshlrev_b64 v[118:119], 13, v[118:119]
	v_lshlrev_b64 v[122:123], 13, v[122:123]
	v_lshl_add_u64 v[118:119], v[116:117], 0, v[118:119]
	v_lshl_add_u64 v[116:117], v[116:117], 0, v[122:123]
	global_load_dwordx4 v[98:101], v[118:119], off nt
	s_nop 0
	global_load_dwordx4 v[102:105], v[116:117], off nt
	s_or_b64 exec, exec, s[10:11]
	s_add_i32 s100, s100, s33
	s_add_i32 s101, s101, s92
	s_cmpk_lt_i32 s100, 0x600
	s_cselect_b32 s100, s100, s13
	s_cselect_b32 s101, s101, s12
	s_mul_hi_i32 s10, s100, 0x2aaaaaab
	s_lshr_b32 s11, s10, 31
	s_ashr_i32 s10, s10, 3
	s_add_i32 s10, s10, s11
	s_lshl_b32 s14, s10, 6
	s_mul_i32 s15, s10, 0xfffff400
	v_or_b32_e32 v10, s14, v12
	s_movk_i32 s10, 0x800
	v_cmp_gt_i32_e32 vcc, s10, v10
	v_mov_b32_e32 v106, 0
	v_mov_b32_e32 v107, 0
	v_mov_b32_e32 v108, 0
	v_mov_b32_e32 v109, 0
	v_mov_b32_e32 v110, 0
	v_mov_b32_e32 v111, 0
	v_mov_b32_e32 v112, 0
	v_mov_b32_e32 v113, 0
	s_and_saveexec_b64 s[10:11], vcc
	s_add_i32 s16, s15, s101
	v_add_u32_e32 v118, s16, v14
	v_add_u32_e32 v122, s16, v15
	v_ashrrev_i32_e32 v11, 31, v10
	v_ashrrev_i32_e32 v119, 31, v118
	v_ashrrev_i32_e32 v123, 31, v122
	v_lshl_add_u64 v[116:117], v[10:11], 2, s[0:1]
	v_lshlrev_b64 v[118:119], 13, v[118:119]
	v_lshlrev_b64 v[122:123], 13, v[122:123]
	v_lshl_add_u64 v[118:119], v[116:117], 0, v[118:119]
	v_lshl_add_u64 v[116:117], v[116:117], 0, v[122:123]
	global_load_dwordx4 v[106:109], v[118:119], off nt
	s_nop 0
	global_load_dwordx4 v[110:113], v[116:117], off nt
	s_or_b64 exec, exec, s[10:11]
	s_add_i32 s100, s100, s33
	s_add_i32 s101, s101, s92
	s_cmpk_lt_i32 s100, 0x600
	s_cselect_b32 s100, s100, s13
	s_cselect_b32 s101, s101, s12
	s_mul_hi_i32 s10, s100, 0x2aaaaaab
	s_lshr_b32 s11, s10, 31
	s_ashr_i32 s10, s10, 3
	s_add_i32 s10, s10, s11
	s_lshl_b32 s14, s10, 6
	s_mul_i32 s15, s10, 0xfffff400
	v_or_b32_e32 v10, s14, v12
	s_movk_i32 s10, 0x800
	v_cmp_gt_i32_e32 vcc, s10, v10
	v_mov_b32_e32 v208, 0
	v_mov_b32_e32 v209, 0
	v_mov_b32_e32 v210, 0
	v_mov_b32_e32 v211, 0
	v_mov_b32_e32 v212, 0
	v_mov_b32_e32 v213, 0
	v_mov_b32_e32 v214, 0
	v_mov_b32_e32 v215, 0
	s_and_saveexec_b64 s[10:11], vcc
	s_add_i32 s16, s15, s101
	v_add_u32_e32 v118, s16, v14
	v_add_u32_e32 v122, s16, v15
	v_ashrrev_i32_e32 v11, 31, v10
	v_ashrrev_i32_e32 v119, 31, v118
	v_ashrrev_i32_e32 v123, 31, v122
	v_lshl_add_u64 v[116:117], v[10:11], 2, s[0:1]
	v_lshlrev_b64 v[118:119], 13, v[118:119]
	v_lshlrev_b64 v[122:123], 13, v[122:123]
	v_lshl_add_u64 v[118:119], v[116:117], 0, v[118:119]
	v_lshl_add_u64 v[116:117], v[116:117], 0, v[122:123]
	global_load_dwordx4 v[208:211], v[118:119], off nt
	s_nop 0
	global_load_dwordx4 v[212:215], v[116:117], off nt
	s_or_b64 exec, exec, s[10:11]
	s_mul_hi_i32 s10, s13, 0x2aaaaaab
	s_lshr_b32 s11, s10, 31
	s_ashr_i32 s10, s10, 3
	s_add_i32 s10, s10, s11
	s_lshl_b32 s14, s10, 6
	s_mul_i32 s15, s10, 0xfffff400
	v_or_b32_e32 v10, s14, v12
	s_movk_i32 s10, 0x800
	v_cmp_gt_i32_e32 vcc, s10, v10
	s_waitcnt lgkmcnt(0)
	s_barrier
	s_waitcnt vmcnt(4)
	ds_write2_b32 v16, v98, v99 offset1:1
	ds_write2_b32 v16, v100, v101 offset0:2 offset1:3
	ds_write2_b32 v17, v102, v103 offset1:1
	ds_write2_b32 v17, v104, v105 offset0:2 offset1:3
	s_waitcnt lgkmcnt(0)
	s_barrier
;     ...
;     __syncthreads();
;     {
;       const int n = tid >> 3, c = tid & 7;
;       bool rot = false;
;       if (PERM == 1) rot = (n0 == rot_n0);
;       if (PERM == 2) rot = ((tn % 3) == 2);
;       const int ns = rot ? ((n >> 1) + 32 * (n & 1)) : n;
;       if (FP8) {
;         float f[8];
; #pragma unroll
;         for (int j = 0; j < 8; ++j) f[j] = tile[(c * 8 + j) * 65 + ns] * wscale;
;         u32x2 o = {pk4_fp8(f[0], f[1], f[2], f[3]), pk4_fp8(f[4], f[5], f[6], f[7])};
;         *(u32x2*)((unsigned char*)Wt + (size_t)(n0 + n) * K + k0 + c * 8) = o;
	ds_read2_b32 v[2:3], v18 offset1:65
	ds_read2_b32 v[4:5], v18 offset0:130 offset1:195
	s_add_i32 s10, s12, s15
	s_ashr_i32 s11, s10, 31
	s_add_i32 s13, s13, s33
	s_waitcnt lgkmcnt(1)
	v_mul_f32_e32 v8, 0x43800000, v2
	v_add_u32_e32 v2, 0x400, v18
	ds_read2_b32 v[6:7], v2 offset0:4 offset1:69
	v_mul_f32_e32 v9, 0x43800000, v3
	ds_read2_b32 v[2:3], v2 offset0:134 offset1:199
	s_waitcnt lgkmcnt(2)
	v_mul_f32_e32 v4, 0x43800000, v4
	v_mul_f32_e32 v5, 0x43800000, v5
	s_waitcnt lgkmcnt(1)
	v_mul_f32_e32 v6, 0x43800000, v6
	v_mul_f32_e32 v7, 0x43800000, v7
	s_waitcnt lgkmcnt(0)
	v_mul_f32_e32 v10, 0x43800000, v2
	v_mul_f32_e32 v11, 0x43800000, v3
	v_med3_f32 v3, v8, s93, v223
	v_med3_f32 v8, v9, s93, v223
	v_mov_b32_e32 v2, v1
	v_cvt_pk_fp8_f32 v2, v3, v8
	v_med3_f32 v6, v6, s93, v223
	v_med3_f32 v7, v7, s93, v223
	v_mov_b32_e32 v3, v1
	v_cvt_pk_fp8_f32 v3, v6, v7
	v_med3_f32 v4, v4, s93, v223
	v_med3_f32 v5, v5, s93, v223
	v_cvt_pk_fp8_f32 v2, v4, v5 op_sel:[0,0,1]
	v_med3_f32 v4, v10, s93, v223
	v_med3_f32 v5, v11, s93, v223
	v_cvt_pk_fp8_f32 v3, v4, v5 op_sel:[0,0,1]
	v_add_u32_e32 v6, s14, v13
	v_mov_b64_e32 v[4:5], s[18:19]
	v_mad_i64_i32 v[4:5], s[14:15], v6, s34, v[4:5]
	v_lshl_add_u64 v[4:5], v[4:5], 0, s[10:11]
	s_add_i32 s12, s12, s92
	v_lshl_add_u64 v[4:5], v[4:5], 0, v[0:1]
	s_cmpk_lt_i32 s13, 0x600
	global_store_dwordx2 v[4:5], v[2:3], off
	s_cbranch_scc0 .Lcw0_x1
	s_mul_hi_i32 s10, s13, 0x2aaaaaab
	s_lshr_b32 s11, s10, 31
	s_ashr_i32 s10, s10, 3
	s_add_i32 s10, s10, s11
	s_lshl_b32 s14, s10, 6
	s_mul_i32 s15, s10, 0xfffff400
	v_or_b32_e32 v10, s14, v12
	s_movk_i32 s10, 0x800
	v_cmp_gt_i32_e32 vcc, s10, v10
	s_waitcnt lgkmcnt(0)
	s_barrier
	s_waitcnt vmcnt(3)
	ds_write2_b32 v16, v106, v107 offset1:1
	ds_write2_b32 v16, v108, v109 offset0:2 offset1:3
	ds_write2_b32 v17, v110, v111 offset1:1
	ds_write2_b32 v17, v112, v113 offset0:2 offset1:3
	s_waitcnt lgkmcnt(0)
	s_barrier
	ds_read2_b32 v[2:3], v18 offset1:65
	ds_read2_b32 v[4:5], v18 offset0:130 offset1:195
	s_add_i32 s10, s12, s15
	s_ashr_i32 s11, s10, 31
	s_add_i32 s13, s13, s33
	s_waitcnt lgkmcnt(1)
	v_mul_f32_e32 v8, 0x43800000, v2
	v_add_u32_e32 v2, 0x400, v18
	ds_read2_b32 v[6:7], v2 offset0:4 offset1:69
	v_mul_f32_e32 v9, 0x43800000, v3
	ds_read2_b32 v[2:3], v2 offset0:134 offset1:199
	s_waitcnt lgkmcnt(2)
	v_mul_f32_e32 v4, 0x43800000, v4
	v_mul_f32_e32 v5, 0x43800000, v5
	s_waitcnt lgkmcnt(1)
	v_mul_f32_e32 v6, 0x43800000, v6
	v_mul_f32_e32 v7, 0x43800000, v7
	s_waitcnt lgkmcnt(0)
	v_mul_f32_e32 v10, 0x43800000, v2
	v_mul_f32_e32 v11, 0x43800000, v3
	v_med3_f32 v3, v8, s93, v223
	v_med3_f32 v8, v9, s93, v223
	v_mov_b32_e32 v2, v1
	v_cvt_pk_fp8_f32 v2, v3, v8
	v_med3_f32 v6, v6, s93, v223
	v_med3_f32 v7, v7, s93, v223
	v_mov_b32_e32 v3, v1
	v_cvt_pk_fp8_f32 v3, v6, v7
	v_med3_f32 v4, v4, s93, v223
	v_med3_f32 v5, v5, s93, v223
	v_cvt_pk_fp8_f32 v2, v4, v5 op_sel:[0,0,1]
	v_med3_f32 v4, v10, s93, v223
	v_med3_f32 v5, v11, s93, v223
	v_cvt_pk_fp8_f32 v3, v4, v5 op_sel:[0,0,1]
	v_add_u32_e32 v6, s14, v13
	v_mov_b64_e32 v[4:5], s[18:19]
	v_mad_i64_i32 v[4:5], s[14:15], v6, s34, v[4:5]
	v_lshl_add_u64 v[4:5], v[4:5], 0, s[10:11]
	s_add_i32 s12, s12, s92
	v_lshl_add_u64 v[4:5], v[4:5], 0, v[0:1]
	s_cmpk_lt_i32 s13, 0x600
	global_store_dwordx2 v[4:5], v[2:3], off
	s_cbranch_scc0 .Lcw0_x2
	s_mul_hi_i32 s10, s13, 0x2aaaaaab
	s_lshr_b32 s11, s10, 31
	s_ashr_i32 s10, s10, 3
	s_add_i32 s10, s10, s11
	s_lshl_b32 s14, s10, 6
	s_mul_i32 s15, s10, 0xfffff400
	v_or_b32_e32 v10, s14, v12
	s_movk_i32 s10, 0x800
	v_cmp_gt_i32_e32 vcc, s10, v10
	s_waitcnt lgkmcnt(0)
	s_barrier
	s_waitcnt vmcnt(2)
	ds_write2_b32 v16, v208, v209 offset1:1
	ds_write2_b32 v16, v210, v211 offset0:2 offset1:3
	ds_write2_b32 v17, v212, v213 offset1:1
	ds_write2_b32 v17, v214, v215 offset0:2 offset1:3
	s_waitcnt lgkmcnt(0)
	s_barrier
	ds_read2_b32 v[2:3], v18 offset1:65
	ds_read2_b32 v[4:5], v18 offset0:130 offset1:195
	s_add_i32 s10, s12, s15
	s_ashr_i32 s11, s10, 31
	s_add_i32 s13, s13, s33
	s_waitcnt lgkmcnt(1)
	v_mul_f32_e32 v8, 0x43800000, v2
	v_add_u32_e32 v2, 0x400, v18
	ds_read2_b32 v[6:7], v2 offset0:4 offset1:69
	v_mul_f32_e32 v9, 0x43800000, v3
	ds_read2_b32 v[2:3], v2 offset0:134 offset1:199
	s_waitcnt lgkmcnt(2)
	v_mul_f32_e32 v4, 0x43800000, v4
	v_mul_f32_e32 v5, 0x43800000, v5
	s_waitcnt lgkmcnt(1)
	v_mul_f32_e32 v6, 0x43800000, v6
	v_mul_f32_e32 v7, 0x43800000, v7
	s_waitcnt lgkmcnt(0)
	v_mul_f32_e32 v10, 0x43800000, v2
	v_mul_f32_e32 v11, 0x43800000, v3
	v_med3_f32 v3, v8, s93, v223
	v_med3_f32 v8, v9, s93, v223
	v_mov_b32_e32 v2, v1
	v_cvt_pk_fp8_f32 v2, v3, v8
	v_med3_f32 v6, v6, s93, v223
	v_med3_f32 v7, v7, s93, v223
	v_mov_b32_e32 v3, v1
	v_cvt_pk_fp8_f32 v3, v6, v7
	v_med3_f32 v4, v4, s93, v223
	v_med3_f32 v5, v5, s93, v223
	v_cvt_pk_fp8_f32 v2, v4, v5 op_sel:[0,0,1]
	v_med3_f32 v4, v10, s93, v223
	v_med3_f32 v5, v11, s93, v223
	v_cvt_pk_fp8_f32 v3, v4, v5 op_sel:[0,0,1]
	v_add_u32_e32 v6, s14, v13
	v_mov_b64_e32 v[4:5], s[18:19]
	v_mad_i64_i32 v[4:5], s[14:15], v6, s34, v[4:5]
	v_lshl_add_u64 v[4:5], v[4:5], 0, s[10:11]
	s_add_i32 s12, s12, s92
	v_lshl_add_u64 v[4:5], v[4:5], 0, v[0:1]
	s_cmpk_lt_i32 s13, 0x600
	global_store_dwordx2 v[4:5], v[2:3], off
	s_cbranch_scc0 .LBB0_1425
	s_branch .Lcw0_top

;     ...
;   for (int t = blockIdx.x; t < ntk * ntn; t += gridDim.x) {
;     const int tk = t % ntk, tn = t / ntk, k0 = tk * 64, n0 = tn * 64;
;     __syncthreads();
; #pragma unroll
;     for (int i = 0; i < 2; ++i) {
;       const int id = tid + 512 * i, kr = id >> 4, n4 = (id & 15) * 4;
;       f32x4 v = {0.f, 0.f, 0.f, 0.f};
;       const int nd = n0 + n4, nsrc = (nvalid < 0) ? nd : (nd < csplit ? nd + coff1 : nd + coff2);
;       if (nd < ((nvalid < 0) ? N : nvalid)) v = *(const f32x4*)(W + (size_t)(k0 + kr) * N + nsrc);
;       tile[kr * 65 + n4 + 0] = v[0]; tile[kr * 65 + n4 + 1] = v[1]; tile[kr * 65 + n4 + 2] = v[2]; tile[kr * 65 + n4 + 3] = v[3];
;     }
.Lcw1_top:
	s_mov_b32 s100, s13
	s_mov_b32 s101, s12
	s_ashr_i32 s10, s100, 31
	s_lshr_b32 s10, s10, 27
	s_add_i32 s10, s100, s10
	s_ashr_i32 s10, s10, 5
	s_lshl_b32 s15, s10, 6
	s_lshl_b32 s11, s10, 11
	v_or_b32_e32 v18, s15, v10
	s_movk_i32 s10, 0x1250
	s_sub_i32 s16, 0, s11
	v_cmp_gt_i32_e32 vcc, s10, v18
	v_mov_b32_e32 v98, 0
	v_mov_b32_e32 v99, 0
	v_mov_b32_e32 v100, 0
	v_mov_b32_e32 v101, 0
	v_mov_b32_e32 v102, 0
	v_mov_b32_e32 v103, 0
	v_mov_b32_e32 v104, 0
	v_mov_b32_e32 v105, 0
	s_and_saveexec_b64 s[10:11], vcc
	s_movk_i32 s17, 0x650
	v_cmp_gt_i32_e32 vcc, s17, v18
	v_mov_b32_e32 v116, 0xc00
	v_readlane_b32 s36, v250, 26
	v_cndmask_b32_e32 v116, v116, v235, vcc
	s_add_i32 s17, s16, s101
	v_readlane_b32 s42, v250, 32
	v_readlane_b32 s43, v250, 33
	v_add_u32_e32 v116, v116, v18
	v_add_u32_e32 v117, s17, v13
	v_mov_b64_e32 v[118:119], s[42:43]
	s_movk_i32 s23, 0x7940
	v_mad_i64_i32 v[122:123], s[18:19], v117, s23, v[118:119]
	v_ashrrev_i32_e32 v117, 31, v116
	v_add_u32_e32 v124, s17, v14
	v_lshlrev_b64 v[116:117], 2, v[116:117]
	v_mad_i64_i32 v[118:119], s[18:19], v124, s23, v[118:119]
	v_lshl_add_u64 v[122:123], v[122:123], 0, v[116:117]
	v_lshl_add_u64 v[116:117], v[118:119], 0, v[116:117]
	global_load_dwordx4 v[98:101], v[122:123], off nt
	s_nop 0
	global_load_dwordx4 v[102:105], v[116:117], off nt
	v_readlane_b32 s42, v254, 30
	v_readlane_b32 s37, v250, 27
	v_readlane_b32 s38, v250, 28
	v_readlane_b32 s39, v250, 29
	v_readlane_b32 s40, v250, 30
	v_readlane_b32 s41, v250, 31
	v_readlane_b32 s44, v250, 34
	v_readlane_b32 s45, v250, 35
	v_readlane_b32 s46, v250, 36
	v_readlane_b32 s47, v250, 37
	v_readlane_b32 s48, v250, 38
	v_readlane_b32 s49, v250, 39
	v_readlane_b32 s50, v250, 40
	v_readlane_b32 s51, v250, 41
	v_readlane_b32 s43, v254, 31
	s_or_b64 exec, exec, s[10:11]
	s_add_i32 s100, s100, s33
	s_add_i32 s101, s101, s92
	s_cmpk_lt_i32 s100, 0x980
	s_cselect_b32 s100, s100, s13
	s_cselect_b32 s101, s101, s12
	s_ashr_i32 s10, s100, 31
	s_lshr_b32 s10, s10, 27
	s_add_i32 s10, s100, s10
	s_ashr_i32 s10, s10, 5
	s_lshl_b32 s15, s10, 6
	s_lshl_b32 s11, s10, 11
	v_or_b32_e32 v18, s15, v10
	s_movk_i32 s10, 0x1250
	s_sub_i32 s16, 0, s11
	v_cmp_gt_i32_e32 vcc, s10, v18
	v_mov_b32_e32 v106, 0
	v_mov_b32_e32 v107, 0
	v_mov_b32_e32 v108, 0
	v_mov_b32_e32 v109, 0
	v_mov_b32_e32 v110, 0
	v_mov_b32_e32 v111, 0
	v_mov_b32_e32 v112, 0
	v_mov_b32_e32 v113, 0
	s_and_saveexec_b64 s[10:11], vcc
	s_movk_i32 s17, 0x650
	v_cmp_gt_i32_e32 vcc, s17, v18
	v_mov_b32_e32 v116, 0xc00
	v_readlane_b32 s36, v250, 26
	v_cndmask_b32_e32 v116, v116, v235, vcc
	s_add_i32 s17, s16, s101
	v_readlane_b32 s42, v250, 32
	v_readlane_b32 s43, v250, 33
	v_add_u32_e32 v116, v116, v18
	v_add_u32_e32 v117, s17, v13
	v_mov_b64_e32 v[118:119], s[42:43]
	s_movk_i32 s23, 0x7940
	v_mad_i64_i32 v[122:123], s[18:19], v117, s23, v[118:119]
	v_ashrrev_i32_e32 v117, 31, v116
	v_add_u32_e32 v124, s17, v14
	v_lshlrev_b64 v[116:117], 2, v[116:117]
	v_mad_i64_i32 v[118:119], s[18:19], v124, s23, v[118:119]
	v_lshl_add_u64 v[122:123], v[122:123], 0, v[116:117]
	v_lshl_add_u64 v[116:117], v[118:119], 0, v[116:117]
	global_load_dwordx4 v[106:109], v[122:123], off nt
	s_nop 0
	global_load_dwordx4 v[110:113], v[116:117], off nt
	v_readlane_b32 s42, v254, 30
	v_readlane_b32 s37, v250, 27
	v_readlane_b32 s38, v250, 28
	v_readlane_b32 s39, v250, 29
	v_readlane_b32 s40, v250, 30
	v_readlane_b32 s41, v250, 31
	v_readlane_b32 s44, v250, 34
	v_readlane_b32 s45, v250, 35
	v_readlane_b32 s46, v250, 36
	v_readlane_b32 s47, v250, 37
	v_readlane_b32 s48, v250, 38
	v_readlane_b32 s49, v250, 39
	v_readlane_b32 s50, v250, 40
	v_readlane_b32 s51, v250, 41
	v_readlane_b32 s43, v254, 31
	s_or_b64 exec, exec, s[10:11]
	s_add_i32 s100, s100, s33
	s_add_i32 s101, s101, s92
	s_cmpk_lt_i32 s100, 0x980
	s_cselect_b32 s100, s100, s13
	s_cselect_b32 s101, s101, s12
	s_ashr_i32 s10, s100, 31
	s_lshr_b32 s10, s10, 27
	s_add_i32 s10, s100, s10
	s_ashr_i32 s10, s10, 5
	s_lshl_b32 s15, s10, 6
	s_lshl_b32 s11, s10, 11
	v_or_b32_e32 v18, s15, v10
	s_movk_i32 s10, 0x1250
	s_sub_i32 s16, 0, s11
	v_cmp_gt_i32_e32 vcc, s10, v18
	v_mov_b32_e32 v208, 0
	v_mov_b32_e32 v209, 0
	v_mov_b32_e32 v210, 0
	v_mov_b32_e32 v211, 0
	v_mov_b32_e32 v212, 0
	v_mov_b32_e32 v213, 0
	v_mov_b32_e32 v214, 0
	v_mov_b32_e32 v215, 0
	s_and_saveexec_b64 s[10:11], vcc
	s_movk_i32 s17, 0x650
	v_cmp_gt_i32_e32 vcc, s17, v18
	v_mov_b32_e32 v116, 0xc00
	v_readlane_b32 s36, v250, 26
	v_cndmask_b32_e32 v116, v116, v235, vcc
	s_add_i32 s17, s16, s101
	v_readlane_b32 s42, v250, 32
	v_readlane_b32 s43, v250, 33
	v_add_u32_e32 v116, v116, v18
	v_add_u32_e32 v117, s17, v13
	v_mov_b64_e32 v[118:119], s[42:43]
	s_movk_i32 s23, 0x7940
	v_mad_i64_i32 v[122:123], s[18:19], v117, s23, v[118:119]
	v_ashrrev_i32_e32 v117, 31, v116
	v_add_u32_e32 v124, s17, v14
	v_lshlrev_b64 v[116:117], 2, v[116:117]
	v_mad_i64_i32 v[118:119], s[18:19], v124, s23, v[118:119]
	v_lshl_add_u64 v[122:123], v[122:123], 0, v[116:117]
	v_lshl_add_u64 v[116:117], v[118:119], 0, v[116:117]
	global_load_dwordx4 v[208:211], v[122:123], off nt
	s_nop 0
	global_load_dwordx4 v[212:215], v[116:117], off nt
	v_readlane_b32 s42, v254, 30
	v_readlane_b32 s37, v250, 27
	v_readlane_b32 s38, v250, 28
	v_readlane_b32 s39, v250, 29
	v_readlane_b32 s40, v250, 30
	v_readlane_b32 s41, v250, 31
	v_readlane_b32 s44, v250, 34
	v_readlane_b32 s45, v250, 35
	v_readlane_b32 s46, v250, 36
	v_readlane_b32 s47, v250, 37
	v_readlane_b32 s48, v250, 38
	v_readlane_b32 s49, v250, 39
	v_readlane_b32 s50, v250, 40
	v_readlane_b32 s51, v250, 41
	v_readlane_b32 s43, v254, 31
	s_or_b64 exec, exec, s[10:11]
	s_ashr_i32 s10, s13, 31
	s_lshr_b32 s10, s10, 27
	s_add_i32 s10, s13, s10
	s_ashr_i32 s10, s10, 5
	s_lshl_b32 s15, s10, 6
	s_lshl_b32 s11, s10, 11
	v_or_b32_e32 v18, s15, v10
	s_movk_i32 s10, 0x1250
	s_sub_i32 s16, 0, s11
	v_cmp_gt_i32_e32 vcc, s10, v18
	s_waitcnt lgkmcnt(0)
	s_barrier
;     ...
;     __syncthreads();
;     {
;       const int n = tid >> 3, c = tid & 7;
;       bool rot = false;
;       if (PERM == 1) rot = (n0 == rot_n0);
;       if (PERM == 2) rot = ((tn % 3) == 2);
;       const int ns = rot ? ((n >> 1) + 32 * (n & 1)) : n;
;       if (FP8) {
;         float f[8];
; #pragma unroll
;         for (int j = 0; j < 8; ++j) f[j] = tile[(c * 8 + j) * 65 + ns] * wscale;
;         u32x2 o = {pk4_fp8(f[0], f[1], f[2], f[3]), pk4_fp8(f[4], f[5], f[6], f[7])};
;         *(u32x2*)((unsigned char*)Wt + (size_t)(n0 + n) * K + k0 + c * 8) = o;
;       } else {
;         u32x4 o;
; #pragma unroll
;         for (int j = 0; j < 4; ++j) o[j] = pk2(tile[(c * 8 + 2 * j) * 65 + ns], tile[(c * 8 + 2 * j + 1) * 65 + ns]);
;         *(u32x4*)(Wt + (size_t)(n0 + n) * K + k0 + c * 8) = o;
;       }
	s_waitcnt vmcnt(4)
	ds_write2_b32 v16, v98, v99 offset1:1
	ds_write2_b32 v16, v100, v101 offset0:2 offset1:3
	ds_write2_b32 v17, v102, v103 offset1:1
	ds_write2_b32 v17, v104, v105 offset0:2 offset1:3
	s_waitcnt lgkmcnt(0)
	s_barrier
	ds_read2_b32 v[2:3], v12 offset1:130
	ds_read2_b32 v[4:5], v15 offset0:65 offset1:195
	v_add_u32_e32 v6, 0x400, v15
	ds_read2_b32 v[6:7], v6 offset0:69 offset1:199
	s_add_i32 s10, s12, s16
	v_readlane_b32 s16, v253, 15
	s_waitcnt lgkmcnt(1)
	v_cvt_pk_bf16_f32 v2, v2, v4
	v_add_u32_e32 v4, 0x400, v12
	v_cvt_pk_bf16_f32 v3, v3, v5
	ds_read2_b32 v[4:5], v4 offset0:4 offset1:134
	v_readlane_b32 s17, v253, 16
	s_ashr_i32 s11, s10, 31
	s_add_i32 s13, s13, s33
	s_add_i32 s12, s12, s92
	s_waitcnt lgkmcnt(0)
	v_cvt_pk_bf16_f32 v4, v4, v6
	v_add_u32_e32 v6, s15, v11
	v_cvt_pk_bf16_f32 v5, v5, v7
	v_ashrrev_i32_e32 v7, 31, v6
	v_lshlrev_b64 v[6:7], 12, v[6:7]
	v_lshl_add_u64 v[6:7], s[16:17], 0, v[6:7]
	v_lshl_add_u64 v[6:7], s[10:11], 1, v[6:7]
	v_lshl_add_u64 v[6:7], v[6:7], 0, v[0:1]
	s_cmpk_lt_i32 s13, 0x980
	global_store_dwordx4 v[6:7], v[2:5], off
	s_cbranch_scc0 .Lcw1_x1
	s_ashr_i32 s10, s13, 31
	s_lshr_b32 s10, s10, 27
	s_add_i32 s10, s13, s10
	s_ashr_i32 s10, s10, 5
	s_lshl_b32 s15, s10, 6
	s_lshl_b32 s11, s10, 11
	v_or_b32_e32 v18, s15, v10
	s_movk_i32 s10, 0x1250
	s_sub_i32 s16, 0, s11
	v_cmp_gt_i32_e32 vcc, s10, v18
	s_waitcnt lgkmcnt(0)
	s_barrier
	s_waitcnt vmcnt(3)
	ds_write2_b32 v16, v106, v107 offset1:1
	ds_write2_b32 v16, v108, v109 offset0:2 offset1:3
	ds_write2_b32 v17, v110, v111 offset1:1
	ds_write2_b32 v17, v112, v113 offset0:2 offset1:3
	s_waitcnt lgkmcnt(0)
	s_barrier
	ds_read2_b32 v[2:3], v12 offset1:130
	ds_read2_b32 v[4:5], v15 offset0:65 offset1:195
	v_add_u32_e32 v6, 0x400, v15
	ds_read2_b32 v[6:7], v6 offset0:69 offset1:199
	s_add_i32 s10, s12, s16
	v_readlane_b32 s16, v253, 15
	s_waitcnt lgkmcnt(1)
	v_cvt_pk_bf16_f32 v2, v2, v4
	v_add_u32_e32 v4, 0x400, v12
	v_cvt_pk_bf16_f32 v3, v3, v5
	ds_read2_b32 v[4:5], v4 offset0:4 offset1:134
	v_readlane_b32 s17, v253, 16
	s_ashr_i32 s11, s10, 31
	s_add_i32 s13, s13, s33
	s_add_i32 s12, s12, s92
	s_waitcnt lgkmcnt(0)
	v_cvt_pk_bf16_f32 v4, v4, v6
	v_add_u32_e32 v6, s15, v11
	v_cvt_pk_bf16_f32 v5, v5, v7
	v_ashrrev_i32_e32 v7, 31, v6
	v_lshlrev_b64 v[6:7], 12, v[6:7]
	v_lshl_add_u64 v[6:7], s[16:17], 0, v[6:7]
	v_lshl_add_u64 v[6:7], s[10:11], 1, v[6:7]
	v_lshl_add_u64 v[6:7], v[6:7], 0, v[0:1]
	s_cmpk_lt_i32 s13, 0x980
	global_store_dwordx4 v[6:7], v[2:5], off
	s_cbranch_scc0 .Lcw1_x2
	s_ashr_i32 s10, s13, 31
	s_lshr_b32 s10, s10, 27
	s_add_i32 s10, s13, s10
	s_ashr_i32 s10, s10, 5
	s_lshl_b32 s15, s10, 6
	s_lshl_b32 s11, s10, 11
	v_or_b32_e32 v18, s15, v10
	s_movk_i32 s10, 0x1250
	s_sub_i32 s16, 0, s11
	v_cmp_gt_i32_e32 vcc, s10, v18
	s_waitcnt lgkmcnt(0)
	s_barrier
	s_waitcnt vmcnt(2)
	ds_write2_b32 v16, v208, v209 offset1:1
	ds_write2_b32 v16, v210, v211 offset0:2 offset1:3
	ds_write2_b32 v17, v212, v213 offset1:1
	ds_write2_b32 v17, v214, v215 offset0:2 offset1:3
	s_waitcnt lgkmcnt(0)
	s_barrier
	ds_read2_b32 v[2:3], v12 offset1:130
	ds_read2_b32 v[4:5], v15 offset0:65 offset1:195
	v_add_u32_e32 v6, 0x400, v15
	ds_read2_b32 v[6:7], v6 offset0:69 offset1:199
	s_add_i32 s10, s12, s16
	v_readlane_b32 s16, v253, 15
	s_waitcnt lgkmcnt(1)
	v_cvt_pk_bf16_f32 v2, v2, v4
	v_add_u32_e32 v4, 0x400, v12
	v_cvt_pk_bf16_f32 v3, v3, v5
	ds_read2_b32 v[4:5], v4 offset0:4 offset1:134
	v_readlane_b32 s17, v253, 16
	s_ashr_i32 s11, s10, 31
	s_add_i32 s13, s13, s33
	s_add_i32 s12, s12, s92
	s_waitcnt lgkmcnt(0)
	v_cvt_pk_bf16_f32 v4, v4, v6
	v_add_u32_e32 v6, s15, v11
	v_cvt_pk_bf16_f32 v5, v5, v7
	v_ashrrev_i32_e32 v7, 31, v6
	v_lshlrev_b64 v[6:7], 12, v[6:7]
	v_lshl_add_u64 v[6:7], s[16:17], 0, v[6:7]
	v_lshl_add_u64 v[6:7], s[10:11], 1, v[6:7]
	v_lshl_add_u64 v[6:7], v[6:7], 0, v[0:1]
	s_cmpk_lt_i32 s13, 0x980
	global_store_dwordx4 v[6:7], v[2:5], off
	s_cbranch_scc0 .LBB0_1437
	s_branch .Lcw1_top

;     ...
;   for (int t = blockIdx.x; t < ntk * ntn; t += gridDim.x) {
;     const int tk = t % ntk, tn = t / ntk, k0 = tk * 64, n0 = tn * 64;
;     __syncthreads();
; #pragma unroll
;     for (int i = 0; i < 2; ++i) {
;       const int id = tid + 512 * i, kr = id >> 4, n4 = (id & 15) * 4;
;       f32x4 v = {0.f, 0.f, 0.f, 0.f};
;       const int nd = n0 + n4, nsrc = (nvalid < 0) ? nd : (nd < csplit ? nd + coff1 : nd + coff2);
;       if (nd < ((nvalid < 0) ? N : nvalid)) v = *(const f32x4*)(W + (size_t)(k0 + kr) * N + nsrc);
;       tile[kr * 65 + n4 + 0] = v[0]; tile[kr * 65 + n4 + 1] = v[1]; tile[kr * 65 + n4 + 2] = v[2]; tile[kr * 65 + n4 + 3] = v[3];
;     }
.Lcw2_top:
	s_mov_b32 s100, s13
	s_mov_b32 s101, s12
	s_ashr_i32 s10, s100, 31
	s_lshr_b32 s10, s10, 27
	s_add_i32 s10, s100, s10
	s_ashr_i32 s10, s10, 5
	s_lshl_b32 s15, s10, 6
	s_lshl_b32 s11, s10, 11
	v_or_b32_e32 v17, s15, v10
	s_sub_i32 s16, 0, s11
	v_cmp_gt_i32_e32 vcc, s34, v17
	v_mov_b32_e32 v98, 0
	v_mov_b32_e32 v99, 0
	v_mov_b32_e32 v100, 0
	v_mov_b32_e32 v101, 0
	v_mov_b32_e32 v102, 0
	v_mov_b32_e32 v103, 0
	v_mov_b32_e32 v104, 0
	v_mov_b32_e32 v105, 0
	s_and_saveexec_b64 s[10:11], vcc
	s_movk_i32 s17, 0x800
	v_cmp_gt_i32_e32 vcc, s17, v17
	v_mov_b32_e32 v116, 0x650
	v_readlane_b32 s36, v250, 26
	v_cndmask_b32_e64 v116, v116, 0, vcc
	v_add_u32_e32 v116, v116, v17
	v_ashrrev_i32_e32 v117, 31, v116
	v_readlane_b32 s42, v250, 32
	v_readlane_b32 s43, v250, 33
	s_add_i32 s17, s16, s101
	v_add_u32_e32 v118, s17, v12
	v_lshl_add_u64 v[116:117], v[116:117], 2, s[42:43]
	s_movk_i32 s23, 0x7940
	v_add_u32_e32 v122, s17, v13
	v_mad_i64_i32 v[118:119], s[18:19], v118, s23, v[116:117]
	v_mad_i64_i32 v[116:117], s[18:19], v122, s23, v[116:117]
	global_load_dwordx4 v[98:101], v[118:119], off nt
	s_nop 0
	global_load_dwordx4 v[102:105], v[116:117], off nt
	v_readlane_b32 s42, v254, 30
	v_readlane_b32 s37, v250, 27
	v_readlane_b32 s38, v250, 28
	v_readlane_b32 s39, v250, 29
	v_readlane_b32 s40, v250, 30
	v_readlane_b32 s41, v250, 31
	v_readlane_b32 s44, v250, 34
	v_readlane_b32 s45, v250, 35
	v_readlane_b32 s46, v250, 36
	v_readlane_b32 s47, v250, 37
	v_readlane_b32 s48, v250, 38
	v_readlane_b32 s49, v250, 39
	v_readlane_b32 s50, v250, 40
	v_readlane_b32 s51, v250, 41
	v_readlane_b32 s43, v254, 31
	s_or_b64 exec, exec, s[10:11]
	s_add_i32 s100, s100, s33
	s_add_i32 s101, s101, s92
	s_cmpk_lt_i32 s100, 0x600
	s_cselect_b32 s100, s100, s13
	s_cselect_b32 s101, s101, s12
	s_ashr_i32 s10, s100, 31
	s_lshr_b32 s10, s10, 27
	s_add_i32 s10, s100, s10
	s_ashr_i32 s10, s10, 5
	s_lshl_b32 s15, s10, 6
	s_lshl_b32 s11, s10, 11
	v_or_b32_e32 v17, s15, v10
	s_sub_i32 s16, 0, s11
	v_cmp_gt_i32_e32 vcc, s34, v17
	v_mov_b32_e32 v106, 0
	v_mov_b32_e32 v107, 0
	v_mov_b32_e32 v108, 0
	v_mov_b32_e32 v109, 0
	v_mov_b32_e32 v110, 0
	v_mov_b32_e32 v111, 0
	v_mov_b32_e32 v112, 0
	v_mov_b32_e32 v113, 0
	s_and_saveexec_b64 s[10:11], vcc
	s_movk_i32 s17, 0x800
	v_cmp_gt_i32_e32 vcc, s17, v17
	v_mov_b32_e32 v116, 0x650
	v_readlane_b32 s36, v250, 26
	v_cndmask_b32_e64 v116, v116, 0, vcc
	v_add_u32_e32 v116, v116, v17
	v_ashrrev_i32_e32 v117, 31, v116
	v_readlane_b32 s42, v250, 32
	v_readlane_b32 s43, v250, 33
	s_add_i32 s17, s16, s101
	v_add_u32_e32 v118, s17, v12
	v_lshl_add_u64 v[116:117], v[116:117], 2, s[42:43]
	s_movk_i32 s23, 0x7940
	v_add_u32_e32 v122, s17, v13
	v_mad_i64_i32 v[118:119], s[18:19], v118, s23, v[116:117]
	v_mad_i64_i32 v[116:117], s[18:19], v122, s23, v[116:117]
	global_load_dwordx4 v[106:109], v[118:119], off nt
	s_nop 0
	global_load_dwordx4 v[110:113], v[116:117], off nt
	v_readlane_b32 s42, v254, 30
	v_readlane_b32 s37, v250, 27
	v_readlane_b32 s38, v250, 28
	v_readlane_b32 s39, v250, 29
	v_readlane_b32 s40, v250, 30
	v_readlane_b32 s41, v250, 31
	v_readlane_b32 s44, v250, 34
	v_readlane_b32 s45, v250, 35
	v_readlane_b32 s46, v250, 36
	v_readlane_b32 s47, v250, 37
	v_readlane_b32 s48, v250, 38
	v_readlane_b32 s49, v250, 39
	v_readlane_b32 s50, v250, 40
	v_readlane_b32 s51, v250, 41
	v_readlane_b32 s43, v254, 31
	s_or_b64 exec, exec, s[10:11]
	s_add_i32 s100, s100, s33
	s_add_i32 s101, s101, s92
	s_cmpk_lt_i32 s100, 0x600
	s_cselect_b32 s100, s100, s13
	s_cselect_b32 s101, s101, s12
	s_ashr_i32 s10, s100, 31
	s_lshr_b32 s10, s10, 27
	s_add_i32 s10, s100, s10
	s_ashr_i32 s10, s10, 5
	s_lshl_b32 s15, s10, 6
	s_lshl_b32 s11, s10, 11
	v_or_b32_e32 v17, s15, v10
	s_sub_i32 s16, 0, s11
	v_cmp_gt_i32_e32 vcc, s34, v17
	v_mov_b32_e32 v208, 0
	v_mov_b32_e32 v209, 0
	v_mov_b32_e32 v210, 0
	v_mov_b32_e32 v211, 0
	v_mov_b32_e32 v212, 0
	v_mov_b32_e32 v213, 0
	v_mov_b32_e32 v214, 0
	v_mov_b32_e32 v215, 0
	s_and_saveexec_b64 s[10:11], vcc
	s_movk_i32 s17, 0x800
	v_cmp_gt_i32_e32 vcc, s17, v17
	v_mov_b32_e32 v116, 0x650
	v_readlane_b32 s36, v250, 26
	v_cndmask_b32_e64 v116, v116, 0, vcc
	v_add_u32_e32 v116, v116, v17
	v_ashrrev_i32_e32 v117, 31, v116
	v_readlane_b32 s42, v250, 32
	v_readlane_b32 s43, v250, 33
	s_add_i32 s17, s16, s101
	v_add_u32_e32 v118, s17, v12
	v_lshl_add_u64 v[116:117], v[116:117], 2, s[42:43]
	s_movk_i32 s23, 0x7940
	v_add_u32_e32 v122, s17, v13
	v_mad_i64_i32 v[118:119], s[18:19], v118, s23, v[116:117]
	v_mad_i64_i32 v[116:117], s[18:19], v122, s23, v[116:117]
	global_load_dwordx4 v[208:211], v[118:119], off nt
	s_nop 0
	global_load_dwordx4 v[212:215], v[116:117], off nt
	v_readlane_b32 s42, v254, 30
	v_readlane_b32 s37, v250, 27
	v_readlane_b32 s38, v250, 28
	v_readlane_b32 s39, v250, 29
	v_readlane_b32 s40, v250, 30
	v_readlane_b32 s41, v250, 31
	v_readlane_b32 s44, v250, 34
	v_readlane_b32 s45, v250, 35
	v_readlane_b32 s46, v250, 36
	v_readlane_b32 s47, v250, 37
	v_readlane_b32 s48, v250, 38
	v_readlane_b32 s49, v250, 39
	v_readlane_b32 s50, v250, 40
	v_readlane_b32 s51, v250, 41
	v_readlane_b32 s43, v254, 31
	s_or_b64 exec, exec, s[10:11]
	s_ashr_i32 s10, s13, 31
	s_lshr_b32 s10, s10, 27
	s_add_i32 s10, s13, s10
	s_ashr_i32 s10, s10, 5
	s_lshl_b32 s15, s10, 6
	s_lshl_b32 s11, s10, 11
	v_or_b32_e32 v17, s15, v10
	s_sub_i32 s16, 0, s11
	v_cmp_gt_i32_e32 vcc, s34, v17
	s_waitcnt lgkmcnt(0)
	s_barrier
;     ...
;     __syncthreads();
;     {
;       const int n = tid >> 3, c = tid & 7;
;       bool rot = false;
;       if (PERM == 1) rot = (n0 == rot_n0);
;       if (PERM == 2) rot = ((tn % 3) == 2);
;       const int ns = rot ? ((n >> 1) + 32 * (n & 1)) : n;
;       if (FP8) {
;         float f[8];
; #pragma unroll
;         for (int j = 0; j < 8; ++j) f[j] = tile[(c * 8 + j) * 65 + ns] * wscale;
;         u32x2 o = {pk4_fp8(f[0], f[1], f[2], f[3]), pk4_fp8(f[4], f[5], f[6], f[7])};
;         *(u32x2*)((unsigned char*)Wt + (size_t)(n0 + n) * K + k0 + c * 8) = o;
	s_waitcnt vmcnt(4)
	ds_write2_b32 v14, v98, v99 offset1:1
	ds_write2_b32 v14, v100, v101 offset0:2 offset1:3
	ds_write2_b32 v15, v102, v103 offset1:1
	ds_write2_b32 v15, v104, v105 offset0:2 offset1:3
	s_waitcnt lgkmcnt(0)
	s_barrier
	ds_read2_b32 v[2:3], v16 offset1:65
	ds_read2_b32 v[4:5], v16 offset0:130 offset1:195
	s_add_i32 s10, s12, s16
	s_ashr_i32 s11, s10, 31
	s_add_i32 s13, s13, s33
	s_waitcnt lgkmcnt(1)
	v_mul_f32_e32 v8, 0x43800000, v2
	v_add_u32_e32 v2, 0x400, v16
	ds_read2_b32 v[6:7], v2 offset0:4 offset1:69
	v_mul_f32_e32 v9, 0x43800000, v3
	ds_read2_b32 v[2:3], v2 offset0:134 offset1:199
	s_waitcnt lgkmcnt(2)
	v_mul_f32_e32 v4, 0x43800000, v4
	v_mul_f32_e32 v5, 0x43800000, v5
	s_waitcnt lgkmcnt(1)
	v_mul_f32_e32 v6, 0x43800000, v6
	v_mul_f32_e32 v7, 0x43800000, v7
	s_waitcnt lgkmcnt(0)
	v_mul_f32_e32 v17, 0x43800000, v2
	v_mul_f32_e32 v18, 0x43800000, v3
	v_med3_f32 v3, v8, s93, v223
	v_med3_f32 v8, v9, s93, v223
	v_mov_b32_e32 v2, v1
	v_cvt_pk_fp8_f32 v2, v3, v8
	v_med3_f32 v6, v6, s93, v223
	v_med3_f32 v7, v7, s93, v223
	v_mov_b32_e32 v3, v1
	v_cvt_pk_fp8_f32 v3, v6, v7
	v_med3_f32 v4, v4, s93, v223
	v_med3_f32 v5, v5, s93, v223
	v_cvt_pk_fp8_f32 v2, v4, v5 op_sel:[0,0,1]
	v_med3_f32 v4, v17, s93, v223
	v_med3_f32 v5, v18, s93, v223
	v_cvt_pk_fp8_f32 v3, v4, v5 op_sel:[0,0,1]
	v_add_u32_e32 v4, s15, v11
	v_ashrrev_i32_e32 v5, 31, v4
	v_lshlrev_b64 v[4:5], 11, v[4:5]
	v_lshl_add_u64 v[4:5], s[6:7], 0, v[4:5]
	v_lshl_add_u64 v[4:5], v[4:5], 0, s[10:11]
	s_add_i32 s12, s12, s92
	v_lshl_add_u64 v[4:5], v[4:5], 0, v[0:1]
	s_cmpk_gt_i32 s13, 0x5ff
	global_store_dwordx2 v[4:5], v[2:3], off
	s_cbranch_scc1 .Lcw2_x1
	s_ashr_i32 s10, s13, 31
	s_lshr_b32 s10, s10, 27
	s_add_i32 s10, s13, s10
	s_ashr_i32 s10, s10, 5
	s_lshl_b32 s15, s10, 6
	s_lshl_b32 s11, s10, 11
	v_or_b32_e32 v17, s15, v10
	s_sub_i32 s16, 0, s11
	v_cmp_gt_i32_e32 vcc, s34, v17
	s_waitcnt lgkmcnt(0)
	s_barrier
	s_waitcnt vmcnt(3)
	ds_write2_b32 v14, v106, v107 offset1:1
	ds_write2_b32 v14, v108, v109 offset0:2 offset1:3
	ds_write2_b32 v15, v110, v111 offset1:1
	ds_write2_b32 v15, v112, v113 offset0:2 offset1:3
	s_waitcnt lgkmcnt(0)
	s_barrier
	ds_read2_b32 v[2:3], v16 offset1:65
	ds_read2_b32 v[4:5], v16 offset0:130 offset1:195
	s_add_i32 s10, s12, s16
	s_ashr_i32 s11, s10, 31
	s_add_i32 s13, s13, s33
	s_waitcnt lgkmcnt(1)
	v_mul_f32_e32 v8, 0x43800000, v2
	v_add_u32_e32 v2, 0x400, v16
	ds_read2_b32 v[6:7], v2 offset0:4 offset1:69
	v_mul_f32_e32 v9, 0x43800000, v3
	ds_read2_b32 v[2:3], v2 offset0:134 offset1:199
	s_waitcnt lgkmcnt(2)
	v_mul_f32_e32 v4, 0x43800000, v4
	v_mul_f32_e32 v5, 0x43800000, v5
	s_waitcnt lgkmcnt(1)
	v_mul_f32_e32 v6, 0x43800000, v6
	v_mul_f32_e32 v7, 0x43800000, v7
	s_waitcnt lgkmcnt(0)
	v_mul_f32_e32 v17, 0x43800000, v2
	v_mul_f32_e32 v18, 0x43800000, v3
	v_med3_f32 v3, v8, s93, v223
	v_med3_f32 v8, v9, s93, v223
	v_mov_b32_e32 v2, v1
	v_cvt_pk_fp8_f32 v2, v3, v8
	v_med3_f32 v6, v6, s93, v223
	v_med3_f32 v7, v7, s93, v223
	v_mov_b32_e32 v3, v1
	v_cvt_pk_fp8_f32 v3, v6, v7
	v_med3_f32 v4, v4, s93, v223
	v_med3_f32 v5, v5, s93, v223
	v_cvt_pk_fp8_f32 v2, v4, v5 op_sel:[0,0,1]
	v_med3_f32 v4, v17, s93, v223
	v_med3_f32 v5, v18, s93, v223
	v_cvt_pk_fp8_f32 v3, v4, v5 op_sel:[0,0,1]
	v_add_u32_e32 v4, s15, v11
	v_ashrrev_i32_e32 v5, 31, v4
	v_lshlrev_b64 v[4:5], 11, v[4:5]
	v_lshl_add_u64 v[4:5], s[6:7], 0, v[4:5]
	v_lshl_add_u64 v[4:5], v[4:5], 0, s[10:11]
	s_add_i32 s12, s12, s92
	v_lshl_add_u64 v[4:5], v[4:5], 0, v[0:1]
	s_cmpk_gt_i32 s13, 0x5ff
	global_store_dwordx2 v[4:5], v[2:3], off
	s_cbranch_scc1 .Lcw2_x2
	s_ashr_i32 s10, s13, 31
	s_lshr_b32 s10, s10, 27
	s_add_i32 s10, s13, s10
	s_ashr_i32 s10, s10, 5
	s_lshl_b32 s15, s10, 6
	s_lshl_b32 s11, s10, 11
	v_or_b32_e32 v17, s15, v10
	s_sub_i32 s16, 0, s11
	v_cmp_gt_i32_e32 vcc, s34, v17
	s_waitcnt lgkmcnt(0)
	s_barrier
	s_waitcnt vmcnt(2)
	ds_write2_b32 v14, v208, v209 offset1:1
	ds_write2_b32 v14, v210, v211 offset0:2 offset1:3
	ds_write2_b32 v15, v212, v213 offset1:1
	ds_write2_b32 v15, v214, v215 offset0:2 offset1:3
	s_waitcnt lgkmcnt(0)
	s_barrier
	ds_read2_b32 v[2:3], v16 offset1:65
	ds_read2_b32 v[4:5], v16 offset0:130 offset1:195
	s_add_i32 s10, s12, s16
	s_ashr_i32 s11, s10, 31
	s_add_i32 s13, s13, s33
	s_waitcnt lgkmcnt(1)
	v_mul_f32_e32 v8, 0x43800000, v2
	v_add_u32_e32 v2, 0x400, v16
	ds_read2_b32 v[6:7], v2 offset0:4 offset1:69
	v_mul_f32_e32 v9, 0x43800000, v3
	ds_read2_b32 v[2:3], v2 offset0:134 offset1:199
	s_waitcnt lgkmcnt(2)
	v_mul_f32_e32 v4, 0x43800000, v4
	v_mul_f32_e32 v5, 0x43800000, v5
	s_waitcnt lgkmcnt(1)
	v_mul_f32_e32 v6, 0x43800000, v6
	v_mul_f32_e32 v7, 0x43800000, v7
	s_waitcnt lgkmcnt(0)
	v_mul_f32_e32 v17, 0x43800000, v2
	v_mul_f32_e32 v18, 0x43800000, v3
	v_med3_f32 v3, v8, s93, v223
	v_med3_f32 v8, v9, s93, v223
	v_mov_b32_e32 v2, v1
	v_cvt_pk_fp8_f32 v2, v3, v8
	v_med3_f32 v6, v6, s93, v223
	v_med3_f32 v7, v7, s93, v223
	v_mov_b32_e32 v3, v1
	v_cvt_pk_fp8_f32 v3, v6, v7
	v_med3_f32 v4, v4, s93, v223
	v_med3_f32 v5, v5, s93, v223
	v_cvt_pk_fp8_f32 v2, v4, v5 op_sel:[0,0,1]
	v_med3_f32 v4, v17, s93, v223
	v_med3_f32 v5, v18, s93, v223
	v_cvt_pk_fp8_f32 v3, v4, v5 op_sel:[0,0,1]
	v_add_u32_e32 v4, s15, v11
	v_ashrrev_i32_e32 v5, 31, v4
	v_lshlrev_b64 v[4:5], 11, v[4:5]
	v_lshl_add_u64 v[4:5], s[6:7], 0, v[4:5]
	v_lshl_add_u64 v[4:5], v[4:5], 0, s[10:11]
	s_add_i32 s12, s12, s92
	v_lshl_add_u64 v[4:5], v[4:5], 0, v[0:1]
	s_cmpk_gt_i32 s13, 0x5ff
	global_store_dwordx2 v[4:5], v[2:3], off
	s_cbranch_scc1 .LBB0_1442
	s_branch .Lcw2_top

;     ...
;   for (int t = blockIdx.x; t < ntk * ntn; t += gridDim.x) {
;     const int tk = t % ntk, tn = t / ntk, k0 = tk * 64, n0 = tn * 64;
;     __syncthreads();
; #pragma unroll
;     for (int i = 0; i < 2; ++i) {
;       const int id = tid + 512 * i, kr = id >> 4, n4 = (id & 15) * 4;
;       f32x4 v = {0.f, 0.f, 0.f, 0.f};
;       const int nd = n0 + n4, nsrc = (nvalid < 0) ? nd : (nd < csplit ? nd + coff1 : nd + coff2);
;       if (nd < ((nvalid < 0) ? N : nvalid)) v = *(const f32x4*)(W + (size_t)(k0 + kr) * N + nsrc);
;       tile[kr * 65 + n4 + 0] = v[0]; tile[kr * 65 + n4 + 1] = v[1]; tile[kr * 65 + n4 + 2] = v[2]; tile[kr * 65 + n4 + 3] = v[3];
;     }
.Lcw3_top:
	s_mov_b32 s100, s11
	s_mov_b32 s101, s10
	s_ashr_i32 s0, s100, 31
	s_lshr_b32 s0, s0, 27
	s_add_i32 s0, s100, s0
	s_ashr_i32 s0, s0, 5
	s_lshl_b32 s12, s0, 6
	s_lshl_b32 s1, s0, 11
	v_or_b32_e32 v18, s12, v10
	s_movk_i32 s0, 0xe00
	s_sub_i32 s13, 0, s1
	v_cmp_gt_i32_e32 vcc, s0, v18
	v_mov_b32_e32 v98, 0
	v_mov_b32_e32 v99, 0
	v_mov_b32_e32 v100, 0
	v_mov_b32_e32 v101, 0
	v_mov_b32_e32 v102, 0
	v_mov_b32_e32 v103, 0
	v_mov_b32_e32 v104, 0
	v_mov_b32_e32 v105, 0
	s_and_saveexec_b64 s[0:1], vcc
	s_movk_i32 s14, 0x200
	v_cmp_gt_i32_e32 vcc, s14, v18
	v_mov_b32_e32 v116, 0xc00
	v_readlane_b32 s36, v250, 26
	v_cndmask_b32_e32 v116, v116, v235, vcc
	s_add_i32 s16, s13, s101
	v_readlane_b32 s44, v250, 34
	v_readlane_b32 s45, v250, 35
	v_add_u32_e32 v116, v116, v18
	v_add_u32_e32 v117, s16, v13
	v_mov_b64_e32 v[118:119], s[44:45]
	v_mad_i64_i32 v[122:123], s[14:15], v117, s22, v[118:119]
	v_ashrrev_i32_e32 v117, 31, v116
	v_add_u32_e32 v124, s16, v14
	v_lshlrev_b64 v[116:117], 2, v[116:117]
	v_mad_i64_i32 v[118:119], s[14:15], v124, s22, v[118:119]
	v_lshl_add_u64 v[122:123], v[122:123], 0, v[116:117]
	v_lshl_add_u64 v[116:117], v[118:119], 0, v[116:117]
	global_load_dwordx4 v[98:101], v[122:123], off nt
	s_nop 0
	global_load_dwordx4 v[102:105], v[116:117], off nt
	v_readlane_b32 s42, v250, 32
	v_readlane_b32 s43, v250, 33
	v_readlane_b32 s42, v254, 30
	v_readlane_b32 s37, v250, 27
	v_readlane_b32 s38, v250, 28
	v_readlane_b32 s39, v250, 29
	v_readlane_b32 s40, v250, 30
	v_readlane_b32 s41, v250, 31
	v_readlane_b32 s46, v250, 36
	v_readlane_b32 s47, v250, 37
	v_readlane_b32 s48, v250, 38
	v_readlane_b32 s49, v250, 39
	v_readlane_b32 s50, v250, 40
	v_readlane_b32 s51, v250, 41
	v_readlane_b32 s43, v254, 31
	s_or_b64 exec, exec, s[0:1]
	s_add_i32 s100, s100, s33
	s_add_i32 s101, s101, s92
	s_cmpk_lt_i32 s100, 0x700
	s_cselect_b32 s100, s100, s11
	s_cselect_b32 s101, s101, s10
	s_ashr_i32 s0, s100, 31
	s_lshr_b32 s0, s0, 27
	s_add_i32 s0, s100, s0
	s_ashr_i32 s0, s0, 5
	s_lshl_b32 s12, s0, 6
	s_lshl_b32 s1, s0, 11
	v_or_b32_e32 v18, s12, v10
	s_movk_i32 s0, 0xe00
	s_sub_i32 s13, 0, s1
	v_cmp_gt_i32_e32 vcc, s0, v18
	v_mov_b32_e32 v106, 0
	v_mov_b32_e32 v107, 0
	v_mov_b32_e32 v108, 0
	v_mov_b32_e32 v109, 0
	v_mov_b32_e32 v110, 0
	v_mov_b32_e32 v111, 0
	v_mov_b32_e32 v112, 0
	v_mov_b32_e32 v113, 0
	s_and_saveexec_b64 s[0:1], vcc
	s_movk_i32 s14, 0x200
	v_cmp_gt_i32_e32 vcc, s14, v18
	v_mov_b32_e32 v116, 0xc00
	v_readlane_b32 s36, v250, 26
	v_cndmask_b32_e32 v116, v116, v235, vcc
	s_add_i32 s16, s13, s101
	v_readlane_b32 s44, v250, 34
	v_readlane_b32 s45, v250, 35
	v_add_u32_e32 v116, v116, v18
	v_add_u32_e32 v117, s16, v13
	v_mov_b64_e32 v[118:119], s[44:45]
	v_mad_i64_i32 v[122:123], s[14:15], v117, s22, v[118:119]
	v_ashrrev_i32_e32 v117, 31, v116
	v_add_u32_e32 v124, s16, v14
	v_lshlrev_b64 v[116:117], 2, v[116:117]
	v_mad_i64_i32 v[118:119], s[14:15], v124, s22, v[118:119]
	v_lshl_add_u64 v[122:123], v[122:123], 0, v[116:117]
	v_lshl_add_u64 v[116:117], v[118:119], 0, v[116:117]
	global_load_dwordx4 v[106:109], v[122:123], off nt
	s_nop 0
	global_load_dwordx4 v[110:113], v[116:117], off nt
	v_readlane_b32 s42, v250, 32
	v_readlane_b32 s43, v250, 33
	v_readlane_b32 s42, v254, 30
	v_readlane_b32 s37, v250, 27
	v_readlane_b32 s38, v250, 28
	v_readlane_b32 s39, v250, 29
	v_readlane_b32 s40, v250, 30
	v_readlane_b32 s41, v250, 31
	v_readlane_b32 s46, v250, 36
	v_readlane_b32 s47, v250, 37
	v_readlane_b32 s48, v250, 38
	v_readlane_b32 s49, v250, 39
	v_readlane_b32 s50, v250, 40
	v_readlane_b32 s51, v250, 41
	v_readlane_b32 s43, v254, 31
	s_or_b64 exec, exec, s[0:1]
	s_add_i32 s100, s100, s33
	s_add_i32 s101, s101, s92
	s_cmpk_lt_i32 s100, 0x700
	s_cselect_b32 s100, s100, s11
	s_cselect_b32 s101, s101, s10
	s_ashr_i32 s0, s100, 31
	s_lshr_b32 s0, s0, 27
	s_add_i32 s0, s100, s0
	s_ashr_i32 s0, s0, 5
	s_lshl_b32 s12, s0, 6
	s_lshl_b32 s1, s0, 11
	v_or_b32_e32 v18, s12, v10
	s_movk_i32 s0, 0xe00
	s_sub_i32 s13, 0, s1
	v_cmp_gt_i32_e32 vcc, s0, v18
	v_mov_b32_e32 v208, 0
	v_mov_b32_e32 v209, 0
	v_mov_b32_e32 v210, 0
	v_mov_b32_e32 v211, 0
	v_mov_b32_e32 v212, 0
	v_mov_b32_e32 v213, 0
	v_mov_b32_e32 v214, 0
	v_mov_b32_e32 v215, 0
	s_and_saveexec_b64 s[0:1], vcc
	s_movk_i32 s14, 0x200
	v_cmp_gt_i32_e32 vcc, s14, v18
	v_mov_b32_e32 v116, 0xc00
	v_readlane_b32 s36, v250, 26
	v_cndmask_b32_e32 v116, v116, v235, vcc
	s_add_i32 s16, s13, s101
	v_readlane_b32 s44, v250, 34
	v_readlane_b32 s45, v250, 35
	v_add_u32_e32 v116, v116, v18
	v_add_u32_e32 v117, s16, v13
	v_mov_b64_e32 v[118:119], s[44:45]
	v_mad_i64_i32 v[122:123], s[14:15], v117, s22, v[118:119]
	v_ashrrev_i32_e32 v117, 31, v116
	v_add_u32_e32 v124, s16, v14
	v_lshlrev_b64 v[116:117], 2, v[116:117]
	v_mad_i64_i32 v[118:119], s[14:15], v124, s22, v[118:119]
	v_lshl_add_u64 v[122:123], v[122:123], 0, v[116:117]
	v_lshl_add_u64 v[116:117], v[118:119], 0, v[116:117]
	global_load_dwordx4 v[208:211], v[122:123], off nt
	s_nop 0
	global_load_dwordx4 v[212:215], v[116:117], off nt
	v_readlane_b32 s42, v250, 32
	v_readlane_b32 s43, v250, 33
	v_readlane_b32 s42, v254, 30
	v_readlane_b32 s37, v250, 27
	v_readlane_b32 s38, v250, 28
	v_readlane_b32 s39, v250, 29
	v_readlane_b32 s40, v250, 30
	v_readlane_b32 s41, v250, 31
	v_readlane_b32 s46, v250, 36
	v_readlane_b32 s47, v250, 37
	v_readlane_b32 s48, v250, 38
	v_readlane_b32 s49, v250, 39
	v_readlane_b32 s50, v250, 40
	v_readlane_b32 s51, v250, 41
	v_readlane_b32 s43, v254, 31
	s_or_b64 exec, exec, s[0:1]
	s_ashr_i32 s0, s11, 31
	s_lshr_b32 s0, s0, 27
	s_add_i32 s0, s11, s0
	s_ashr_i32 s0, s0, 5
	s_lshl_b32 s12, s0, 6
	s_lshl_b32 s1, s0, 11
	v_or_b32_e32 v18, s12, v10
	s_movk_i32 s0, 0xe00
	s_sub_i32 s13, 0, s1
	v_cmp_gt_i32_e32 vcc, s0, v18
	s_waitcnt lgkmcnt(0)
	s_barrier
;     ...
;     __syncthreads();
;     {
;       const int n = tid >> 3, c = tid & 7;
;       bool rot = false;
;       if (PERM == 1) rot = (n0 == rot_n0);
;       if (PERM == 2) rot = ((tn % 3) == 2);
;       const int ns = rot ? ((n >> 1) + 32 * (n & 1)) : n;
;       if (FP8) {
;         float f[8];
; #pragma unroll
;         for (int j = 0; j < 8; ++j) f[j] = tile[(c * 8 + j) * 65 + ns] * wscale;
;         u32x2 o = {pk4_fp8(f[0], f[1], f[2], f[3]), pk4_fp8(f[4], f[5], f[6], f[7])};
;         *(u32x2*)((unsigned char*)Wt + (size_t)(n0 + n) * K + k0 + c * 8) = o;
;       } else {
;         u32x4 o;
; #pragma unroll
;         for (int j = 0; j < 4; ++j) o[j] = pk2(tile[(c * 8 + 2 * j) * 65 + ns], tile[(c * 8 + 2 * j + 1) * 65 + ns]);
;         *(u32x4*)(Wt + (size_t)(n0 + n) * K + k0 + c * 8) = o;
;       }
	s_waitcnt vmcnt(4)
	ds_write2_b32 v16, v98, v99 offset1:1
	ds_write2_b32 v16, v100, v101 offset0:2 offset1:3
	ds_write2_b32 v17, v102, v103 offset1:1
	ds_write2_b32 v17, v104, v105 offset0:2 offset1:3
	s_waitcnt lgkmcnt(0)
	s_barrier
	ds_read2_b32 v[2:3], v12 offset1:130
	ds_read2_b32 v[4:5], v15 offset0:65 offset1:195
	v_add_u32_e32 v6, 0x400, v15
	ds_read2_b32 v[6:7], v6 offset0:69 offset1:199
	s_add_i32 s0, s10, s13
	s_ashr_i32 s1, s0, 31
	s_waitcnt lgkmcnt(1)
	v_cvt_pk_bf16_f32 v2, v2, v4
	v_add_u32_e32 v4, 0x400, v12
	v_cvt_pk_bf16_f32 v3, v3, v5
	ds_read2_b32 v[4:5], v4 offset0:4 offset1:134
	s_add_i32 s11, s11, s33
	s_add_i32 s10, s10, s92
	s_cmpk_lt_i32 s11, 0x700
	s_waitcnt lgkmcnt(0)
	v_cvt_pk_bf16_f32 v4, v4, v6
	v_add_u32_e32 v6, s12, v11
	v_cvt_pk_bf16_f32 v5, v5, v7
	v_ashrrev_i32_e32 v7, 31, v6
	v_readlane_b32 s12, v253, 15
	v_lshlrev_b64 v[6:7], 12, v[6:7]
	v_readlane_b32 s13, v253, 16
	s_nop 1
	v_lshl_add_u64 v[6:7], s[12:13], 0, v[6:7]
	v_lshl_add_u64 v[6:7], s[0:1], 1, v[6:7]
	v_lshl_add_u64 v[6:7], v[6:7], 0, v[0:1]
	global_store_dwordx4 v[6:7], v[2:5], off
	s_cbranch_scc0 .Lcw3_x1
	s_ashr_i32 s0, s11, 31
	s_lshr_b32 s0, s0, 27
	s_add_i32 s0, s11, s0
	s_ashr_i32 s0, s0, 5
	s_lshl_b32 s12, s0, 6
	s_lshl_b32 s1, s0, 11
	v_or_b32_e32 v18, s12, v10
	s_movk_i32 s0, 0xe00
	s_sub_i32 s13, 0, s1
	v_cmp_gt_i32_e32 vcc, s0, v18
	s_waitcnt lgkmcnt(0)
	s_barrier
	s_waitcnt vmcnt(3)
	ds_write2_b32 v16, v106, v107 offset1:1
	ds_write2_b32 v16, v108, v109 offset0:2 offset1:3
	ds_write2_b32 v17, v110, v111 offset1:1
	ds_write2_b32 v17, v112, v113 offset0:2 offset1:3
	s_waitcnt lgkmcnt(0)
	s_barrier
	ds_read2_b32 v[2:3], v12 offset1:130
	ds_read2_b32 v[4:5], v15 offset0:65 offset1:195
	v_add_u32_e32 v6, 0x400, v15
	ds_read2_b32 v[6:7], v6 offset0:69 offset1:199
	s_add_i32 s0, s10, s13
	s_ashr_i32 s1, s0, 31
	s_waitcnt lgkmcnt(1)
	v_cvt_pk_bf16_f32 v2, v2, v4
	v_add_u32_e32 v4, 0x400, v12
	v_cvt_pk_bf16_f32 v3, v3, v5
	ds_read2_b32 v[4:5], v4 offset0:4 offset1:134
	s_add_i32 s11, s11, s33
	s_add_i32 s10, s10, s92
	s_cmpk_lt_i32 s11, 0x700
	s_waitcnt lgkmcnt(0)
	v_cvt_pk_bf16_f32 v4, v4, v6
	v_add_u32_e32 v6, s12, v11
	v_cvt_pk_bf16_f32 v5, v5, v7
	v_ashrrev_i32_e32 v7, 31, v6
	v_readlane_b32 s12, v253, 15
	v_lshlrev_b64 v[6:7], 12, v[6:7]
	v_readlane_b32 s13, v253, 16
	s_nop 1
	v_lshl_add_u64 v[6:7], s[12:13], 0, v[6:7]
	v_lshl_add_u64 v[6:7], s[0:1], 1, v[6:7]
	v_lshl_add_u64 v[6:7], v[6:7], 0, v[0:1]
	global_store_dwordx4 v[6:7], v[2:5], off
	s_cbranch_scc0 .Lcw3_x2
	s_ashr_i32 s0, s11, 31
	s_lshr_b32 s0, s0, 27
	s_add_i32 s0, s11, s0
	s_ashr_i32 s0, s0, 5
	s_lshl_b32 s12, s0, 6
	s_lshl_b32 s1, s0, 11
	v_or_b32_e32 v18, s12, v10
	s_movk_i32 s0, 0xe00
	s_sub_i32 s13, 0, s1
	v_cmp_gt_i32_e32 vcc, s0, v18
	s_waitcnt lgkmcnt(0)
	s_barrier
	s_waitcnt vmcnt(2)
	ds_write2_b32 v16, v208, v209 offset1:1
	ds_write2_b32 v16, v210, v211 offset0:2 offset1:3
	ds_write2_b32 v17, v212, v213 offset1:1
	ds_write2_b32 v17, v214, v215 offset0:2 offset1:3
	s_waitcnt lgkmcnt(0)
	s_barrier
	ds_read2_b32 v[2:3], v12 offset1:130
	ds_read2_b32 v[4:5], v15 offset0:65 offset1:195
	v_add_u32_e32 v6, 0x400, v15
	ds_read2_b32 v[6:7], v6 offset0:69 offset1:199
	s_add_i32 s0, s10, s13
	s_ashr_i32 s1, s0, 31
	s_waitcnt lgkmcnt(1)
	v_cvt_pk_bf16_f32 v2, v2, v4
	v_add_u32_e32 v4, 0x400, v12
	v_cvt_pk_bf16_f32 v3, v3, v5
	ds_read2_b32 v[4:5], v4 offset0:4 offset1:134
	s_add_i32 s11, s11, s33
	s_add_i32 s10, s10, s92
	s_cmpk_lt_i32 s11, 0x700
	s_waitcnt lgkmcnt(0)
	v_cvt_pk_bf16_f32 v4, v4, v6
	v_add_u32_e32 v6, s12, v11
	v_cvt_pk_bf16_f32 v5, v5, v7
	v_ashrrev_i32_e32 v7, 31, v6
	v_readlane_b32 s12, v253, 15
	v_lshlrev_b64 v[6:7], 12, v[6:7]
	v_readlane_b32 s13, v253, 16
	s_nop 1
	v_lshl_add_u64 v[6:7], s[12:13], 0, v[6:7]
	v_lshl_add_u64 v[6:7], s[0:1], 1, v[6:7]
	v_lshl_add_u64 v[6:7], v[6:7], 0, v[0:1]
	global_store_dwordx4 v[6:7], v[2:5], off
	s_cbranch_scc0 .LBB0_1450
	s_branch .Lcw3_top

;     ...
;   for (int t = blockIdx.x; t < ntk * ntn; t += gridDim.x) {
;     const int tk = t % ntk, tn = t / ntk, k0 = tk * 64, n0 = tn * 64;
;     __syncthreads();
; #pragma unroll
;     for (int i = 0; i < 2; ++i) {
;       const int id = tid + 512 * i, kr = id >> 4, n4 = (id & 15) * 4;
;       f32x4 v = {0.f, 0.f, 0.f, 0.f};
;       const int nd = n0 + n4, nsrc = (nvalid < 0) ? nd : (nd < csplit ? nd + coff1 : nd + coff2);
;       if (nd < ((nvalid < 0) ? N : nvalid)) v = *(const f32x4*)(W + (size_t)(k0 + kr) * N + nsrc);
;       tile[kr * 65 + n4 + 0] = v[0]; tile[kr * 65 + n4 + 1] = v[1]; tile[kr * 65 + n4 + 2] = v[2]; tile[kr * 65 + n4 + 3] = v[3];
;     }
.Lcw4_top:
	s_mov_b32 s100, s9
	s_mov_b32 s101, s8
	s_ashr_i32 s0, s100, 31
	s_lshr_b32 s0, s0, 27
	s_add_i32 s0, s100, s0
	s_ashr_i32 s0, s0, 5
	s_lshl_b32 s10, s0, 6
	s_lshl_b32 s1, s0, 11
	v_or_b32_e32 v17, s10, v10
	s_sub_i32 s11, 0, s1
	v_cmp_gt_i32_e32 vcc, s34, v17
	v_mov_b32_e32 v98, 0
	v_mov_b32_e32 v99, 0
	v_mov_b32_e32 v100, 0
	v_mov_b32_e32 v101, 0
	v_mov_b32_e32 v102, 0
	v_mov_b32_e32 v103, 0
	v_mov_b32_e32 v104, 0
	v_mov_b32_e32 v105, 0
	s_and_saveexec_b64 s[0:1], vcc
	s_movk_i32 s12, 0x800
	v_cmp_gt_i32_e32 vcc, s12, v17
	v_mov_b32_e32 v116, 0x200
	v_readlane_b32 s36, v250, 26
	v_cndmask_b32_e64 v116, v116, 0, vcc
	v_add_u32_e32 v116, v116, v17
	v_ashrrev_i32_e32 v117, 31, v116
	v_readlane_b32 s44, v250, 34
	v_readlane_b32 s45, v250, 35
	s_add_i32 s14, s11, s101
	v_add_u32_e32 v118, s14, v12
	v_lshl_add_u64 v[116:117], v[116:117], 2, s[44:45]
	v_add_u32_e32 v122, s14, v13
	v_mad_i64_i32 v[118:119], s[12:13], v118, s22, v[116:117]
	v_mad_i64_i32 v[116:117], s[12:13], v122, s22, v[116:117]
	global_load_dwordx4 v[98:101], v[118:119], off nt
	s_nop 0
	global_load_dwordx4 v[102:105], v[116:117], off nt
	v_readlane_b32 s42, v250, 32
	v_readlane_b32 s43, v250, 33
	v_readlane_b32 s42, v254, 30
	v_readlane_b32 s37, v250, 27
	v_readlane_b32 s38, v250, 28
	v_readlane_b32 s39, v250, 29
	v_readlane_b32 s40, v250, 30
	v_readlane_b32 s41, v250, 31
	v_readlane_b32 s46, v250, 36
	v_readlane_b32 s47, v250, 37
	v_readlane_b32 s48, v250, 38
	v_readlane_b32 s49, v250, 39
	v_readlane_b32 s50, v250, 40
	v_readlane_b32 s51, v250, 41
	v_readlane_b32 s43, v254, 31
	s_or_b64 exec, exec, s[0:1]
	s_add_i32 s100, s100, s33
	s_add_i32 s101, s101, s92
	s_cmpk_lt_i32 s100, 0x600
	s_cselect_b32 s100, s100, s9
	s_cselect_b32 s101, s101, s8
	s_ashr_i32 s0, s100, 31
	s_lshr_b32 s0, s0, 27
	s_add_i32 s0, s100, s0
	s_ashr_i32 s0, s0, 5
	s_lshl_b32 s10, s0, 6
	s_lshl_b32 s1, s0, 11
	v_or_b32_e32 v17, s10, v10
	s_sub_i32 s11, 0, s1
	v_cmp_gt_i32_e32 vcc, s34, v17
	v_mov_b32_e32 v106, 0
	v_mov_b32_e32 v107, 0
	v_mov_b32_e32 v108, 0
	v_mov_b32_e32 v109, 0
	v_mov_b32_e32 v110, 0
	v_mov_b32_e32 v111, 0
	v_mov_b32_e32 v112, 0
	v_mov_b32_e32 v113, 0
	s_and_saveexec_b64 s[0:1], vcc
	s_movk_i32 s12, 0x800
	v_cmp_gt_i32_e32 vcc, s12, v17
	v_mov_b32_e32 v116, 0x200
	v_readlane_b32 s36, v250, 26
	v_cndmask_b32_e64 v116, v116, 0, vcc
	v_add_u32_e32 v116, v116, v17
	v_ashrrev_i32_e32 v117, 31, v116
	v_readlane_b32 s44, v250, 34
	v_readlane_b32 s45, v250, 35
	s_add_i32 s14, s11, s101
	v_add_u32_e32 v118, s14, v12
	v_lshl_add_u64 v[116:117], v[116:117], 2, s[44:45]
	v_add_u32_e32 v122, s14, v13
	v_mad_i64_i32 v[118:119], s[12:13], v118, s22, v[116:117]
	v_mad_i64_i32 v[116:117], s[12:13], v122, s22, v[116:117]
	global_load_dwordx4 v[106:109], v[118:119], off nt
	s_nop 0
	global_load_dwordx4 v[110:113], v[116:117], off nt
	v_readlane_b32 s42, v250, 32
	v_readlane_b32 s43, v250, 33
	v_readlane_b32 s42, v254, 30
	v_readlane_b32 s37, v250, 27
	v_readlane_b32 s38, v250, 28
	v_readlane_b32 s39, v250, 29
	v_readlane_b32 s40, v250, 30
	v_readlane_b32 s41, v250, 31
	v_readlane_b32 s46, v250, 36
	v_readlane_b32 s47, v250, 37
	v_readlane_b32 s48, v250, 38
	v_readlane_b32 s49, v250, 39
	v_readlane_b32 s50, v250, 40
	v_readlane_b32 s51, v250, 41
	v_readlane_b32 s43, v254, 31
	s_or_b64 exec, exec, s[0:1]
	s_add_i32 s100, s100, s33
	s_add_i32 s101, s101, s92
	s_cmpk_lt_i32 s100, 0x600
	s_cselect_b32 s100, s100, s9
	s_cselect_b32 s101, s101, s8
	s_ashr_i32 s0, s100, 31
	s_lshr_b32 s0, s0, 27
	s_add_i32 s0, s100, s0
	s_ashr_i32 s0, s0, 5
	s_lshl_b32 s10, s0, 6
	s_lshl_b32 s1, s0, 11
	v_or_b32_e32 v17, s10, v10
	s_sub_i32 s11, 0, s1
	v_cmp_gt_i32_e32 vcc, s34, v17
	v_mov_b32_e32 v208, 0
	v_mov_b32_e32 v209, 0
	v_mov_b32_e32 v210, 0
	v_mov_b32_e32 v211, 0
	v_mov_b32_e32 v212, 0
	v_mov_b32_e32 v213, 0
	v_mov_b32_e32 v214, 0
	v_mov_b32_e32 v215, 0
	s_and_saveexec_b64 s[0:1], vcc
	s_movk_i32 s12, 0x800
	v_cmp_gt_i32_e32 vcc, s12, v17
	v_mov_b32_e32 v116, 0x200
	v_readlane_b32 s36, v250, 26
	v_cndmask_b32_e64 v116, v116, 0, vcc
	v_add_u32_e32 v116, v116, v17
	v_ashrrev_i32_e32 v117, 31, v116
	v_readlane_b32 s44, v250, 34
	v_readlane_b32 s45, v250, 35
	s_add_i32 s14, s11, s101
	v_add_u32_e32 v118, s14, v12
	v_lshl_add_u64 v[116:117], v[116:117], 2, s[44:45]
	v_add_u32_e32 v122, s14, v13
	v_mad_i64_i32 v[118:119], s[12:13], v118, s22, v[116:117]
	v_mad_i64_i32 v[116:117], s[12:13], v122, s22, v[116:117]
	global_load_dwordx4 v[208:211], v[118:119], off nt
	s_nop 0
	global_load_dwordx4 v[212:215], v[116:117], off nt
	v_readlane_b32 s42, v250, 32
	v_readlane_b32 s43, v250, 33
	v_readlane_b32 s42, v254, 30
	v_readlane_b32 s37, v250, 27
	v_readlane_b32 s38, v250, 28
	v_readlane_b32 s39, v250, 29
	v_readlane_b32 s40, v250, 30
	v_readlane_b32 s41, v250, 31
	v_readlane_b32 s46, v250, 36
	v_readlane_b32 s47, v250, 37
	v_readlane_b32 s48, v250, 38
	v_readlane_b32 s49, v250, 39
	v_readlane_b32 s50, v250, 40
	v_readlane_b32 s51, v250, 41
	v_readlane_b32 s43, v254, 31
	s_or_b64 exec, exec, s[0:1]
	s_ashr_i32 s0, s9, 31
	s_lshr_b32 s0, s0, 27
	s_add_i32 s0, s9, s0
	s_ashr_i32 s0, s0, 5
	s_lshl_b32 s10, s0, 6
	s_lshl_b32 s1, s0, 11
	v_or_b32_e32 v17, s10, v10
	s_sub_i32 s11, 0, s1
	v_cmp_gt_i32_e32 vcc, s34, v17
	s_waitcnt lgkmcnt(0)
	s_barrier
;     ...
;     __syncthreads();
;     {
;       const int n = tid >> 3, c = tid & 7;
;       bool rot = false;
;       if (PERM == 1) rot = (n0 == rot_n0);
;       if (PERM == 2) rot = ((tn % 3) == 2);
;       const int ns = rot ? ((n >> 1) + 32 * (n & 1)) : n;
;       if (FP8) {
;         float f[8];
; #pragma unroll
;         for (int j = 0; j < 8; ++j) f[j] = tile[(c * 8 + j) * 65 + ns] * wscale;
;         u32x2 o = {pk4_fp8(f[0], f[1], f[2], f[3]), pk4_fp8(f[4], f[5], f[6], f[7])};
;         *(u32x2*)((unsigned char*)Wt + (size_t)(n0 + n) * K + k0 + c * 8) = o;
	s_waitcnt vmcnt(4)
	ds_write2_b32 v14, v98, v99 offset1:1
	ds_write2_b32 v14, v100, v101 offset0:2 offset1:3
	ds_write2_b32 v15, v102, v103 offset1:1
	ds_write2_b32 v15, v104, v105 offset0:2 offset1:3
	s_waitcnt lgkmcnt(0)
	s_barrier
	ds_read2_b32 v[2:3], v16 offset1:65
	ds_read2_b32 v[4:5], v16 offset0:130 offset1:195
	s_add_i32 s0, s8, s11
	s_ashr_i32 s1, s0, 31
	s_add_i32 s9, s9, s33
	s_waitcnt lgkmcnt(1)
	v_mul_f32_e32 v8, 0x43800000, v2
	v_add_u32_e32 v2, 0x400, v16
	ds_read2_b32 v[6:7], v2 offset0:4 offset1:69
	v_mul_f32_e32 v9, 0x43800000, v3
	ds_read2_b32 v[2:3], v2 offset0:134 offset1:199
	s_waitcnt lgkmcnt(2)
	v_mul_f32_e32 v4, 0x43800000, v4
	v_mul_f32_e32 v5, 0x43800000, v5
	s_waitcnt lgkmcnt(1)
	v_mul_f32_e32 v6, 0x43800000, v6
	v_mul_f32_e32 v7, 0x43800000, v7
	s_waitcnt lgkmcnt(0)
	v_mul_f32_e32 v17, 0x43800000, v2
	v_mul_f32_e32 v18, 0x43800000, v3
	v_med3_f32 v3, v8, s93, v223
	v_med3_f32 v8, v9, s93, v223
	v_mov_b32_e32 v2, v1
	v_cvt_pk_fp8_f32 v2, v3, v8
	v_med3_f32 v6, v6, s93, v223
	v_med3_f32 v7, v7, s93, v223
	v_mov_b32_e32 v3, v1
	v_cvt_pk_fp8_f32 v3, v6, v7
	v_med3_f32 v4, v4, s93, v223
	v_med3_f32 v5, v5, s93, v223
	v_cvt_pk_fp8_f32 v2, v4, v5 op_sel:[0,0,1]
	v_med3_f32 v4, v17, s93, v223
	v_med3_f32 v5, v18, s93, v223
	v_cvt_pk_fp8_f32 v3, v4, v5 op_sel:[0,0,1]
	v_add_u32_e32 v4, s10, v11
	v_ashrrev_i32_e32 v5, 31, v4
	v_lshlrev_b64 v[4:5], 11, v[4:5]
	v_lshl_add_u64 v[4:5], s[6:7], 0, v[4:5]
	v_lshl_add_u64 v[4:5], v[4:5], 0, s[0:1]
	s_add_i32 s8, s8, s92
	v_lshl_add_u64 v[4:5], v[4:5], 0, v[0:1]
	s_cmpk_gt_i32 s9, 0x5ff
	global_store_dwordx2 v[4:5], v[2:3], off
	s_cbranch_scc1 .Lcw4_x1
	s_ashr_i32 s0, s9, 31
	s_lshr_b32 s0, s0, 27
	s_add_i32 s0, s9, s0
	s_ashr_i32 s0, s0, 5
	s_lshl_b32 s10, s0, 6
	s_lshl_b32 s1, s0, 11
	v_or_b32_e32 v17, s10, v10
	s_sub_i32 s11, 0, s1
	v_cmp_gt_i32_e32 vcc, s34, v17
	s_waitcnt lgkmcnt(0)
	s_barrier
	s_waitcnt vmcnt(3)
	ds_write2_b32 v14, v106, v107 offset1:1
	ds_write2_b32 v14, v108, v109 offset0:2 offset1:3
	ds_write2_b32 v15, v110, v111 offset1:1
	ds_write2_b32 v15, v112, v113 offset0:2 offset1:3
	s_waitcnt lgkmcnt(0)
	s_barrier
	ds_read2_b32 v[2:3], v16 offset1:65
	ds_read2_b32 v[4:5], v16 offset0:130 offset1:195
	s_add_i32 s0, s8, s11
	s_ashr_i32 s1, s0, 31
	s_add_i32 s9, s9, s33
	s_waitcnt lgkmcnt(1)
	v_mul_f32_e32 v8, 0x43800000, v2
	v_add_u32_e32 v2, 0x400, v16
	ds_read2_b32 v[6:7], v2 offset0:4 offset1:69
	v_mul_f32_e32 v9, 0x43800000, v3
	ds_read2_b32 v[2:3], v2 offset0:134 offset1:199
	s_waitcnt lgkmcnt(2)
	v_mul_f32_e32 v4, 0x43800000, v4
	v_mul_f32_e32 v5, 0x43800000, v5
	s_waitcnt lgkmcnt(1)
	v_mul_f32_e32 v6, 0x43800000, v6
	v_mul_f32_e32 v7, 0x43800000, v7
	s_waitcnt lgkmcnt(0)
	v_mul_f32_e32 v17, 0x43800000, v2
	v_mul_f32_e32 v18, 0x43800000, v3
	v_med3_f32 v3, v8, s93, v223
	v_med3_f32 v8, v9, s93, v223
	v_mov_b32_e32 v2, v1
	v_cvt_pk_fp8_f32 v2, v3, v8
	v_med3_f32 v6, v6, s93, v223
	v_med3_f32 v7, v7, s93, v223
	v_mov_b32_e32 v3, v1
	v_cvt_pk_fp8_f32 v3, v6, v7
	v_med3_f32 v4, v4, s93, v223
	v_med3_f32 v5, v5, s93, v223
	v_cvt_pk_fp8_f32 v2, v4, v5 op_sel:[0,0,1]
	v_med3_f32 v4, v17, s93, v223
	v_med3_f32 v5, v18, s93, v223
	v_cvt_pk_fp8_f32 v3, v4, v5 op_sel:[0,0,1]
	v_add_u32_e32 v4, s10, v11
	v_ashrrev_i32_e32 v5, 31, v4
	v_lshlrev_b64 v[4:5], 11, v[4:5]
	v_lshl_add_u64 v[4:5], s[6:7], 0, v[4:5]
	v_lshl_add_u64 v[4:5], v[4:5], 0, s[0:1]
	s_add_i32 s8, s8, s92
	v_lshl_add_u64 v[4:5], v[4:5], 0, v[0:1]
	s_cmpk_gt_i32 s9, 0x5ff
	global_store_dwordx2 v[4:5], v[2:3], off
	s_cbranch_scc1 .Lcw4_x2
	s_ashr_i32 s0, s9, 31
	s_lshr_b32 s0, s0, 27
	s_add_i32 s0, s9, s0
	s_ashr_i32 s0, s0, 5
	s_lshl_b32 s10, s0, 6
	s_lshl_b32 s1, s0, 11
	v_or_b32_e32 v17, s10, v10
	s_sub_i32 s11, 0, s1
	v_cmp_gt_i32_e32 vcc, s34, v17
	s_waitcnt lgkmcnt(0)
	s_barrier
	s_waitcnt vmcnt(2)
	ds_write2_b32 v14, v208, v209 offset1:1
	ds_write2_b32 v14, v210, v211 offset0:2 offset1:3
	ds_write2_b32 v15, v212, v213 offset1:1
	ds_write2_b32 v15, v214, v215 offset0:2 offset1:3
	s_waitcnt lgkmcnt(0)
	s_barrier
	ds_read2_b32 v[2:3], v16 offset1:65
	ds_read2_b32 v[4:5], v16 offset0:130 offset1:195
	s_add_i32 s0, s8, s11
	s_ashr_i32 s1, s0, 31
	s_add_i32 s9, s9, s33
	s_waitcnt lgkmcnt(1)
	v_mul_f32_e32 v8, 0x43800000, v2
	v_add_u32_e32 v2, 0x400, v16
	ds_read2_b32 v[6:7], v2 offset0:4 offset1:69
	v_mul_f32_e32 v9, 0x43800000, v3
	ds_read2_b32 v[2:3], v2 offset0:134 offset1:199
	s_waitcnt lgkmcnt(2)
	v_mul_f32_e32 v4, 0x43800000, v4
	v_mul_f32_e32 v5, 0x43800000, v5
	s_waitcnt lgkmcnt(1)
	v_mul_f32_e32 v6, 0x43800000, v6
	v_mul_f32_e32 v7, 0x43800000, v7
	s_waitcnt lgkmcnt(0)
	v_mul_f32_e32 v17, 0x43800000, v2
	v_mul_f32_e32 v18, 0x43800000, v3
	v_med3_f32 v3, v8, s93, v223
	v_med3_f32 v8, v9, s93, v223
	v_mov_b32_e32 v2, v1
	v_cvt_pk_fp8_f32 v2, v3, v8
	v_med3_f32 v6, v6, s93, v223
	v_med3_f32 v7, v7, s93, v223
	v_mov_b32_e32 v3, v1
	v_cvt_pk_fp8_f32 v3, v6, v7
	v_med3_f32 v4, v4, s93, v223
	v_med3_f32 v5, v5, s93, v223
	v_cvt_pk_fp8_f32 v2, v4, v5 op_sel:[0,0,1]
	v_med3_f32 v4, v17, s93, v223
	v_med3_f32 v5, v18, s93, v223
	v_cvt_pk_fp8_f32 v3, v4, v5 op_sel:[0,0,1]
	v_add_u32_e32 v4, s10, v11
	v_ashrrev_i32_e32 v5, 31, v4
	v_lshlrev_b64 v[4:5], 11, v[4:5]
	v_lshl_add_u64 v[4:5], s[6:7], 0, v[4:5]
	v_lshl_add_u64 v[4:5], v[4:5], 0, s[0:1]
	s_add_i32 s8, s8, s92
	v_lshl_add_u64 v[4:5], v[4:5], 0, v[0:1]
	s_cmpk_gt_i32 s9, 0x5ff
	global_store_dwordx2 v[4:5], v[2:3], off
	s_cbranch_scc1 .LBB0_1455
	s_branch .Lcw4_top

;     ...
;   for (int t = blockIdx.x; t < ntk * ntn; t += gridDim.x) {
;     const int tk = t % ntk, tn = t / ntk, k0 = tk * 64, n0 = tn * 64;
;     __syncthreads();
; #pragma unroll
;     for (int i = 0; i < 2; ++i) {
;       const int id = tid + 512 * i, kr = id >> 4, n4 = (id & 15) * 4;
;       f32x4 v = {0.f, 0.f, 0.f, 0.f};
;       const int nd = n0 + n4, nsrc = (nvalid < 0) ? nd : (nd < csplit ? nd + coff1 : nd + coff2);
;       if (nd < ((nvalid < 0) ? N : nvalid)) v = *(const f32x4*)(W + (size_t)(k0 + kr) * N + nsrc);
;       tile[kr * 65 + n4 + 0] = v[0]; tile[kr * 65 + n4 + 1] = v[1]; tile[kr * 65 + n4 + 2] = v[2]; tile[kr * 65 + n4 + 3] = v[3];
;     }
;     __syncthreads();
.Lcw5_top:
	s_mov_b32 s100, s11
	s_mov_b32 s101, s10
	s_ashr_i32 s8, s100, 31
	s_lshr_b32 s8, s8, 27
	s_add_i32 s8, s100, s8
	s_ashr_i32 s8, s8, 5
	s_lshl_b32 s12, s8, 6
	s_lshl_b32 s9, s8, 11
	v_or_b32_e32 v18, s12, v10
	s_movk_i32 s8, 0xe40
	s_sub_i32 s13, 0, s9
	v_cmp_gt_i32_e32 vcc, s8, v18
	v_mov_b32_e32 v98, 0
	v_mov_b32_e32 v99, 0
	v_mov_b32_e32 v100, 0
	v_mov_b32_e32 v101, 0
	v_mov_b32_e32 v102, 0
	v_mov_b32_e32 v103, 0
	v_mov_b32_e32 v104, 0
	v_mov_b32_e32 v105, 0
	s_and_saveexec_b64 s[8:9], vcc
	s_movk_i32 s14, 0x240
	v_cmp_gt_i32_e32 vcc, s14, v18
	s_add_i32 s16, s13, s101
	v_add_u32_e32 v118, s16, v12
	v_cndmask_b32_e32 v116, v224, v225, vcc
	v_add_u32_e32 v116, v116, v18
	v_ashrrev_i32_e32 v117, 31, v116
	v_lshl_add_u64 v[116:117], v[116:117], 2, s[0:1]
	s_movk_i32 s17, 0x6100
	v_add_u32_e32 v122, s16, v14
	v_mad_i64_i32 v[118:119], s[14:15], v118, s17, v[116:117]
	v_mad_i64_i32 v[116:117], s[14:15], v122, s17, v[116:117]
	global_load_dwordx4 v[98:101], v[118:119], off nt
	s_nop 0
	global_load_dwordx4 v[102:105], v[116:117], off nt
	s_or_b64 exec, exec, s[8:9]
	s_add_i32 s100, s100, s33
	s_add_i32 s101, s101, s92
	s_cmpk_lt_i32 s100, 0x780
	s_cselect_b32 s100, s100, s11
	s_cselect_b32 s101, s101, s10
	s_ashr_i32 s8, s100, 31
	s_lshr_b32 s8, s8, 27
	s_add_i32 s8, s100, s8
	s_ashr_i32 s8, s8, 5
	s_lshl_b32 s12, s8, 6
	s_lshl_b32 s9, s8, 11
	v_or_b32_e32 v18, s12, v10
	s_movk_i32 s8, 0xe40
	s_sub_i32 s13, 0, s9
	v_cmp_gt_i32_e32 vcc, s8, v18
	v_mov_b32_e32 v106, 0
	v_mov_b32_e32 v107, 0
	v_mov_b32_e32 v108, 0
	v_mov_b32_e32 v109, 0
	v_mov_b32_e32 v110, 0
	v_mov_b32_e32 v111, 0
	v_mov_b32_e32 v112, 0
	v_mov_b32_e32 v113, 0
	s_and_saveexec_b64 s[8:9], vcc
	s_movk_i32 s14, 0x240
	v_cmp_gt_i32_e32 vcc, s14, v18
	s_add_i32 s16, s13, s101
	v_add_u32_e32 v118, s16, v12
	v_cndmask_b32_e32 v116, v224, v225, vcc
	v_add_u32_e32 v116, v116, v18
	v_ashrrev_i32_e32 v117, 31, v116
	v_lshl_add_u64 v[116:117], v[116:117], 2, s[0:1]
	s_movk_i32 s17, 0x6100
	v_add_u32_e32 v122, s16, v14
	v_mad_i64_i32 v[118:119], s[14:15], v118, s17, v[116:117]
	v_mad_i64_i32 v[116:117], s[14:15], v122, s17, v[116:117]
	global_load_dwordx4 v[106:109], v[118:119], off nt
	s_nop 0
	global_load_dwordx4 v[110:113], v[116:117], off nt
	s_or_b64 exec, exec, s[8:9]
	s_add_i32 s100, s100, s33
	s_add_i32 s101, s101, s92
	s_cmpk_lt_i32 s100, 0x780
	s_cselect_b32 s100, s100, s11
	s_cselect_b32 s101, s101, s10
	s_ashr_i32 s8, s100, 31
	s_lshr_b32 s8, s8, 27
	s_add_i32 s8, s100, s8
	s_ashr_i32 s8, s8, 5
	s_lshl_b32 s12, s8, 6
	s_lshl_b32 s9, s8, 11
	v_or_b32_e32 v18, s12, v10
	s_movk_i32 s8, 0xe40
	s_sub_i32 s13, 0, s9
	v_cmp_gt_i32_e32 vcc, s8, v18
	v_mov_b32_e32 v208, 0
	v_mov_b32_e32 v209, 0
	v_mov_b32_e32 v210, 0
	v_mov_b32_e32 v211, 0
	v_mov_b32_e32 v212, 0
	v_mov_b32_e32 v213, 0
	v_mov_b32_e32 v214, 0
	v_mov_b32_e32 v215, 0
	s_and_saveexec_b64 s[8:9], vcc
	s_movk_i32 s14, 0x240
	v_cmp_gt_i32_e32 vcc, s14, v18
	s_add_i32 s16, s13, s101
	v_add_u32_e32 v118, s16, v12
	v_cndmask_b32_e32 v116, v224, v225, vcc
	v_add_u32_e32 v116, v116, v18
	v_ashrrev_i32_e32 v117, 31, v116
	v_lshl_add_u64 v[116:117], v[116:117], 2, s[0:1]
	s_movk_i32 s17, 0x6100
	v_add_u32_e32 v122, s16, v14
	v_mad_i64_i32 v[118:119], s[14:15], v118, s17, v[116:117]
	v_mad_i64_i32 v[116:117], s[14:15], v122, s17, v[116:117]
	global_load_dwordx4 v[208:211], v[118:119], off nt
	s_nop 0
	global_load_dwordx4 v[212:215], v[116:117], off nt
	s_or_b64 exec, exec, s[8:9]
	s_ashr_i32 s8, s11, 31
	s_lshr_b32 s8, s8, 27
	s_add_i32 s8, s11, s8
	s_ashr_i32 s8, s8, 5
	s_lshl_b32 s12, s8, 6
	s_lshl_b32 s9, s8, 11
	v_or_b32_e32 v18, s12, v10
	s_movk_i32 s8, 0xe40
	s_sub_i32 s13, 0, s9
	v_cmp_gt_i32_e32 vcc, s8, v18
	s_waitcnt lgkmcnt(0)
	s_barrier
	s_add_i32 s8, s10, s13
	s_and_b32 s9, s11, 0xffffffe0
	s_cmpk_eq_i32 s9, 0x100
	s_cselect_b64 vcc, -1, 0
	s_waitcnt vmcnt(4)
	ds_write2_b32 v16, v98, v99 offset1:1
	ds_write2_b32 v16, v100, v101 offset0:2 offset1:3
	ds_write2_b32 v17, v102, v103 offset1:1
	ds_write2_b32 v17, v104, v105 offset0:2 offset1:3
	v_cndmask_b32_e32 v2, v11, v13, vcc
	v_lshl_add_u32 v6, v2, 2, v15
	s_waitcnt lgkmcnt(0)
	s_barrier
;     ...
;       const int n = tid >> 3, c = tid & 7;
;       bool rot = false;
;       if (PERM == 1) rot = (n0 == rot_n0);
;       if (PERM == 2) rot = ((tn % 3) == 2);
;       const int ns = rot ? ((n >> 1) + 32 * (n & 1)) : n;
;       if (FP8) {
;         float f[8];
; #pragma unroll
;         for (int j = 0; j < 8; ++j) f[j] = tile[(c * 8 + j) * 65 + ns] * wscale;
;         u32x2 o = {pk4_fp8(f[0], f[1], f[2], f[3]), pk4_fp8(f[4], f[5], f[6], f[7])};
;         *(u32x2*)((unsigned char*)Wt + (size_t)(n0 + n) * K + k0 + c * 8) = o;
;       } else {
;         u32x4 o;
; #pragma unroll
;         for (int j = 0; j < 4; ++j) o[j] = pk2(tile[(c * 8 + 2 * j) * 65 + ns], tile[(c * 8 + 2 * j + 1) * 65 + ns]);
;         *(u32x4*)(Wt + (size_t)(n0 + n) * K + k0 + c * 8) = o;
;       }
	ds_read2_b32 v[2:3], v6 offset1:65
	ds_read2_b32 v[4:5], v6 offset0:130 offset1:195
	v_add_u32_e32 v6, 0x400, v6
	s_ashr_i32 s9, s8, 31
	s_add_i32 s11, s11, s33
	s_waitcnt lgkmcnt(1)
	v_cvt_pk_bf16_f32 v2, v2, v3
	s_waitcnt lgkmcnt(0)
	v_cvt_pk_bf16_f32 v3, v4, v5
	ds_read2_b32 v[4:5], v6 offset0:4 offset1:69
	ds_read2_b32 v[6:7], v6 offset0:134 offset1:199
	s_add_i32 s10, s10, s92
	s_cmpk_lt_i32 s11, 0x780
	s_waitcnt lgkmcnt(1)
	v_cvt_pk_bf16_f32 v4, v4, v5
	s_waitcnt lgkmcnt(0)
	v_cvt_pk_bf16_f32 v5, v6, v7
	v_add_u32_e32 v6, s12, v11
	v_ashrrev_i32_e32 v7, 31, v6
	v_readlane_b32 s12, v253, 15
	v_lshlrev_b64 v[6:7], 12, v[6:7]
	v_readlane_b32 s13, v253, 16
	s_nop 1
	v_lshl_add_u64 v[6:7], s[12:13], 0, v[6:7]
	v_lshl_add_u64 v[6:7], s[8:9], 1, v[6:7]
	v_lshl_add_u64 v[6:7], v[6:7], 0, v[0:1]
	global_store_dwordx4 v[6:7], v[2:5], off
	s_cbranch_scc0 .Lcw5_x1
	s_ashr_i32 s8, s11, 31
	s_lshr_b32 s8, s8, 27
	s_add_i32 s8, s11, s8
	s_ashr_i32 s8, s8, 5
	s_lshl_b32 s12, s8, 6
	s_lshl_b32 s9, s8, 11
	v_or_b32_e32 v18, s12, v10
	s_movk_i32 s8, 0xe40
	s_sub_i32 s13, 0, s9
	v_cmp_gt_i32_e32 vcc, s8, v18
	s_waitcnt lgkmcnt(0)
	s_barrier
	s_add_i32 s8, s10, s13
	s_and_b32 s9, s11, 0xffffffe0
	s_cmpk_eq_i32 s9, 0x100
	s_cselect_b64 vcc, -1, 0
	s_waitcnt vmcnt(3)
	ds_write2_b32 v16, v106, v107 offset1:1
	ds_write2_b32 v16, v108, v109 offset0:2 offset1:3
	ds_write2_b32 v17, v110, v111 offset1:1
	ds_write2_b32 v17, v112, v113 offset0:2 offset1:3
	v_cndmask_b32_e32 v2, v11, v13, vcc
	v_lshl_add_u32 v6, v2, 2, v15
	s_waitcnt lgkmcnt(0)
	s_barrier
	ds_read2_b32 v[2:3], v6 offset1:65
	ds_read2_b32 v[4:5], v6 offset0:130 offset1:195
	v_add_u32_e32 v6, 0x400, v6
	s_ashr_i32 s9, s8, 31
	s_add_i32 s11, s11, s33
	s_waitcnt lgkmcnt(1)
	v_cvt_pk_bf16_f32 v2, v2, v3
	s_waitcnt lgkmcnt(0)
	v_cvt_pk_bf16_f32 v3, v4, v5
	ds_read2_b32 v[4:5], v6 offset0:4 offset1:69
	ds_read2_b32 v[6:7], v6 offset0:134 offset1:199
	s_add_i32 s10, s10, s92
	s_cmpk_lt_i32 s11, 0x780
	s_waitcnt lgkmcnt(1)
	v_cvt_pk_bf16_f32 v4, v4, v5
	s_waitcnt lgkmcnt(0)
	v_cvt_pk_bf16_f32 v5, v6, v7
	v_add_u32_e32 v6, s12, v11
	v_ashrrev_i32_e32 v7, 31, v6
	v_readlane_b32 s12, v253, 15
	v_lshlrev_b64 v[6:7], 12, v[6:7]
	v_readlane_b32 s13, v253, 16
	s_nop 1
	v_lshl_add_u64 v[6:7], s[12:13], 0, v[6:7]
	v_lshl_add_u64 v[6:7], s[8:9], 1, v[6:7]
	v_lshl_add_u64 v[6:7], v[6:7], 0, v[0:1]
	global_store_dwordx4 v[6:7], v[2:5], off
	s_cbranch_scc0 .Lcw5_x2
	s_ashr_i32 s8, s11, 31
	s_lshr_b32 s8, s8, 27
	s_add_i32 s8, s11, s8
	s_ashr_i32 s8, s8, 5
	s_lshl_b32 s12, s8, 6
	s_lshl_b32 s9, s8, 11
	v_or_b32_e32 v18, s12, v10
	s_movk_i32 s8, 0xe40
	s_sub_i32 s13, 0, s9
	v_cmp_gt_i32_e32 vcc, s8, v18
	s_waitcnt lgkmcnt(0)
	s_barrier
	s_add_i32 s8, s10, s13
	s_and_b32 s9, s11, 0xffffffe0
	s_cmpk_eq_i32 s9, 0x100
	s_cselect_b64 vcc, -1, 0
	s_waitcnt vmcnt(2)
	ds_write2_b32 v16, v208, v209 offset1:1
	ds_write2_b32 v16, v210, v211 offset0:2 offset1:3
	ds_write2_b32 v17, v212, v213 offset1:1
	ds_write2_b32 v17, v214, v215 offset0:2 offset1:3
	v_cndmask_b32_e32 v2, v11, v13, vcc
	v_lshl_add_u32 v6, v2, 2, v15
	s_waitcnt lgkmcnt(0)
	s_barrier
	ds_read2_b32 v[2:3], v6 offset1:65
	ds_read2_b32 v[4:5], v6 offset0:130 offset1:195
	v_add_u32_e32 v6, 0x400, v6
	s_ashr_i32 s9, s8, 31
	s_add_i32 s11, s11, s33
	s_waitcnt lgkmcnt(1)
	v_cvt_pk_bf16_f32 v2, v2, v3
	s_waitcnt lgkmcnt(0)
	v_cvt_pk_bf16_f32 v3, v4, v5
	ds_read2_b32 v[4:5], v6 offset0:4 offset1:69
	ds_read2_b32 v[6:7], v6 offset0:134 offset1:199
	s_add_i32 s10, s10, s92
	s_cmpk_lt_i32 s11, 0x780
	s_waitcnt lgkmcnt(1)
	v_cvt_pk_bf16_f32 v4, v4, v5
	s_waitcnt lgkmcnt(0)
	v_cvt_pk_bf16_f32 v5, v6, v7
	v_add_u32_e32 v6, s12, v11
	v_ashrrev_i32_e32 v7, 31, v6
	v_readlane_b32 s12, v253, 15
	v_lshlrev_b64 v[6:7], 12, v[6:7]
	v_readlane_b32 s13, v253, 16
	s_nop 1
	v_lshl_add_u64 v[6:7], s[12:13], 0, v[6:7]
	v_lshl_add_u64 v[6:7], s[8:9], 1, v[6:7]
	v_lshl_add_u64 v[6:7], v[6:7], 0, v[0:1]
	global_store_dwordx4 v[6:7], v[2:5], off
	s_cbranch_scc0 .LBB0_1461
	s_branch .Lcw5_top

;     ...
;   for (int t = blockIdx.x; t < ntk * ntn; t += gridDim.x) {
;     const int tk = t % ntk, tn = t / ntk, k0 = tk * 64, n0 = tn * 64;
;     __syncthreads();
; #pragma unroll
;     for (int i = 0; i < 2; ++i) {
;       const int id = tid + 512 * i, kr = id >> 4, n4 = (id & 15) * 4;
;       f32x4 v = {0.f, 0.f, 0.f, 0.f};
;       const int nd = n0 + n4, nsrc = (nvalid < 0) ? nd : (nd < csplit ? nd + coff1 : nd + coff2);
;       if (nd < ((nvalid < 0) ? N : nvalid)) v = *(const f32x4*)(W + (size_t)(k0 + kr) * N + nsrc);
;       tile[kr * 65 + n4 + 0] = v[0]; tile[kr * 65 + n4 + 1] = v[1]; tile[kr * 65 + n4 + 2] = v[2]; tile[kr * 65 + n4 + 3] = v[3];
;     }
.Lcw6_top:
	s_mov_b32 s100, s11
	s_mov_b32 s101, s10
	s_ashr_i32 s8, s100, 31
	s_lshr_b32 s8, s8, 27
	s_add_i32 s8, s100, s8
	s_ashr_i32 s8, s8, 5
	s_lshl_b32 s12, s8, 6
	s_lshl_b32 s9, s8, 11
	v_or_b32_e32 v17, s12, v10
	s_movk_i32 s8, 0xa00
	s_sub_i32 s13, 0, s9
	v_cmp_gt_i32_e32 vcc, s8, v17
	v_mov_b32_e32 v98, 0
	v_mov_b32_e32 v99, 0
	v_mov_b32_e32 v100, 0
	v_mov_b32_e32 v101, 0
	v_mov_b32_e32 v102, 0
	v_mov_b32_e32 v103, 0
	v_mov_b32_e32 v104, 0
	v_mov_b32_e32 v105, 0
	s_and_saveexec_b64 s[8:9], vcc
	v_cmp_gt_i32_e32 vcc, s20, v17
	s_add_i32 s16, s13, s101
	v_add_u32_e32 v118, s16, v12
	v_cndmask_b32_e64 v116, v226, 0, vcc
	v_add_u32_e32 v116, v116, v17
	v_ashrrev_i32_e32 v117, 31, v116
	v_lshl_add_u64 v[116:117], v[116:117], 2, s[0:1]
	s_movk_i32 s17, 0x6100
	v_add_u32_e32 v122, s16, v13
	v_mad_i64_i32 v[118:119], s[14:15], v118, s17, v[116:117]
	v_mad_i64_i32 v[116:117], s[14:15], v122, s17, v[116:117]
	global_load_dwordx4 v[98:101], v[118:119], off nt
	s_nop 0
	global_load_dwordx4 v[102:105], v[116:117], off nt
	s_or_b64 exec, exec, s[8:9]
	s_add_i32 s100, s100, s33
	s_add_i32 s101, s101, s92
	s_cmpk_lt_i32 s100, 0x500
	s_cselect_b32 s100, s100, s11
	s_cselect_b32 s101, s101, s10
	s_ashr_i32 s8, s100, 31
	s_lshr_b32 s8, s8, 27
	s_add_i32 s8, s100, s8
	s_ashr_i32 s8, s8, 5
	s_lshl_b32 s12, s8, 6
	s_lshl_b32 s9, s8, 11
	v_or_b32_e32 v17, s12, v10
	s_movk_i32 s8, 0xa00
	s_sub_i32 s13, 0, s9
	v_cmp_gt_i32_e32 vcc, s8, v17
	v_mov_b32_e32 v106, 0
	v_mov_b32_e32 v107, 0
	v_mov_b32_e32 v108, 0
	v_mov_b32_e32 v109, 0
	v_mov_b32_e32 v110, 0
	v_mov_b32_e32 v111, 0
	v_mov_b32_e32 v112, 0
	v_mov_b32_e32 v113, 0
	s_and_saveexec_b64 s[8:9], vcc
	v_cmp_gt_i32_e32 vcc, s20, v17
	s_add_i32 s16, s13, s101
	v_add_u32_e32 v118, s16, v12
	v_cndmask_b32_e64 v116, v226, 0, vcc
	v_add_u32_e32 v116, v116, v17
	v_ashrrev_i32_e32 v117, 31, v116
	v_lshl_add_u64 v[116:117], v[116:117], 2, s[0:1]
	s_movk_i32 s17, 0x6100
	v_add_u32_e32 v122, s16, v13
	v_mad_i64_i32 v[118:119], s[14:15], v118, s17, v[116:117]
	v_mad_i64_i32 v[116:117], s[14:15], v122, s17, v[116:117]
	global_load_dwordx4 v[106:109], v[118:119], off nt
	s_nop 0
	global_load_dwordx4 v[110:113], v[116:117], off nt
	s_or_b64 exec, exec, s[8:9]
	s_add_i32 s100, s100, s33
	s_add_i32 s101, s101, s92
	s_cmpk_lt_i32 s100, 0x500
	s_cselect_b32 s100, s100, s11
	s_cselect_b32 s101, s101, s10
	s_ashr_i32 s8, s100, 31
	s_lshr_b32 s8, s8, 27
	s_add_i32 s8, s100, s8
	s_ashr_i32 s8, s8, 5
	s_lshl_b32 s12, s8, 6
	s_lshl_b32 s9, s8, 11
	v_or_b32_e32 v17, s12, v10
	s_movk_i32 s8, 0xa00
	s_sub_i32 s13, 0, s9
	v_cmp_gt_i32_e32 vcc, s8, v17
	v_mov_b32_e32 v208, 0
	v_mov_b32_e32 v209, 0
	v_mov_b32_e32 v210, 0
	v_mov_b32_e32 v211, 0
	v_mov_b32_e32 v212, 0
	v_mov_b32_e32 v213, 0
	v_mov_b32_e32 v214, 0
	v_mov_b32_e32 v215, 0
	s_and_saveexec_b64 s[8:9], vcc
	v_cmp_gt_i32_e32 vcc, s20, v17
	s_add_i32 s16, s13, s101
	v_add_u32_e32 v118, s16, v12
	v_cndmask_b32_e64 v116, v226, 0, vcc
	v_add_u32_e32 v116, v116, v17
	v_ashrrev_i32_e32 v117, 31, v116
	v_lshl_add_u64 v[116:117], v[116:117], 2, s[0:1]
	s_movk_i32 s17, 0x6100
	v_add_u32_e32 v122, s16, v13
	v_mad_i64_i32 v[118:119], s[14:15], v118, s17, v[116:117]
	v_mad_i64_i32 v[116:117], s[14:15], v122, s17, v[116:117]
	global_load_dwordx4 v[208:211], v[118:119], off nt
	s_nop 0
	global_load_dwordx4 v[212:215], v[116:117], off nt
	s_or_b64 exec, exec, s[8:9]
	s_ashr_i32 s8, s11, 31
	s_lshr_b32 s8, s8, 27
	s_add_i32 s8, s11, s8
	s_ashr_i32 s8, s8, 5
	s_lshl_b32 s12, s8, 6
	s_lshl_b32 s9, s8, 11
	v_or_b32_e32 v17, s12, v10
	s_movk_i32 s8, 0xa00
	s_sub_i32 s13, 0, s9
	v_cmp_gt_i32_e32 vcc, s8, v17
	s_waitcnt lgkmcnt(0)
	s_barrier
	s_waitcnt vmcnt(4)
	ds_write2_b32 v14, v98, v99 offset1:1
	ds_write2_b32 v14, v100, v101 offset0:2 offset1:3
	ds_write2_b32 v15, v102, v103 offset1:1
	ds_write2_b32 v15, v104, v105 offset0:2 offset1:3
	s_waitcnt lgkmcnt(0)
	s_barrier
;     ...
;     __syncthreads();
;     {
;       const int n = tid >> 3, c = tid & 7;
;       bool rot = false;
;       if (PERM == 1) rot = (n0 == rot_n0);
;       if (PERM == 2) rot = ((tn % 3) == 2);
;       const int ns = rot ? ((n >> 1) + 32 * (n & 1)) : n;
;       if (FP8) {
;         float f[8];
; #pragma unroll
;         for (int j = 0; j < 8; ++j) f[j] = tile[(c * 8 + j) * 65 + ns] * wscale;
;         u32x2 o = {pk4_fp8(f[0], f[1], f[2], f[3]), pk4_fp8(f[4], f[5], f[6], f[7])};
;         *(u32x2*)((unsigned char*)Wt + (size_t)(n0 + n) * K + k0 + c * 8) = o;
	ds_read2_b32 v[2:3], v16 offset1:65
	ds_read2_b32 v[4:5], v16 offset0:130 offset1:195
	s_add_i32 s8, s10, s13
	s_ashr_i32 s9, s8, 31
	s_add_i32 s11, s11, s33
	s_waitcnt lgkmcnt(1)
	v_mul_f32_e32 v8, 0x43800000, v2
	v_add_u32_e32 v2, 0x400, v16
	ds_read2_b32 v[6:7], v2 offset0:4 offset1:69
	v_mul_f32_e32 v9, 0x43800000, v3
	ds_read2_b32 v[2:3], v2 offset0:134 offset1:199
	s_waitcnt lgkmcnt(2)
	v_mul_f32_e32 v4, 0x43800000, v4
	v_mul_f32_e32 v5, 0x43800000, v5
	s_waitcnt lgkmcnt(1)
	v_mul_f32_e32 v6, 0x43800000, v6
	v_mul_f32_e32 v7, 0x43800000, v7
	s_waitcnt lgkmcnt(0)
	v_mul_f32_e32 v17, 0x43800000, v2
	v_mul_f32_e32 v18, 0x43800000, v3
	v_med3_f32 v3, v8, s93, v223
	v_med3_f32 v8, v9, s93, v223
	v_mov_b32_e32 v2, v1
	v_cvt_pk_fp8_f32 v2, v3, v8
	v_med3_f32 v6, v6, s93, v223
	v_med3_f32 v7, v7, s93, v223
	v_mov_b32_e32 v3, v1
	v_cvt_pk_fp8_f32 v3, v6, v7
	v_med3_f32 v4, v4, s93, v223
	v_med3_f32 v5, v5, s93, v223
	v_cvt_pk_fp8_f32 v2, v4, v5 op_sel:[0,0,1]
	v_med3_f32 v4, v17, s93, v223
	v_med3_f32 v5, v18, s93, v223
	v_cvt_pk_fp8_f32 v3, v4, v5 op_sel:[0,0,1]
	v_add_u32_e32 v4, s12, v11
	v_ashrrev_i32_e32 v5, 31, v4
	v_lshlrev_b64 v[4:5], 11, v[4:5]
	v_lshl_add_u64 v[4:5], s[6:7], 0, v[4:5]
	v_lshl_add_u64 v[4:5], v[4:5], 0, s[8:9]
	s_add_i32 s10, s10, s92
	v_lshl_add_u64 v[4:5], v[4:5], 0, v[0:1]
	s_cmpk_lt_i32 s11, 0x500
	global_store_dwordx2 v[4:5], v[2:3], off
	s_cbranch_scc0 .Lcw6_x1
	s_ashr_i32 s8, s11, 31
	s_lshr_b32 s8, s8, 27
	s_add_i32 s8, s11, s8
	s_ashr_i32 s8, s8, 5
	s_lshl_b32 s12, s8, 6
	s_lshl_b32 s9, s8, 11
	v_or_b32_e32 v17, s12, v10
	s_movk_i32 s8, 0xa00
	s_sub_i32 s13, 0, s9
	v_cmp_gt_i32_e32 vcc, s8, v17
	s_waitcnt lgkmcnt(0)
	s_barrier
	s_waitcnt vmcnt(3)
	ds_write2_b32 v14, v106, v107 offset1:1
	ds_write2_b32 v14, v108, v109 offset0:2 offset1:3
	ds_write2_b32 v15, v110, v111 offset1:1
	ds_write2_b32 v15, v112, v113 offset0:2 offset1:3
	s_waitcnt lgkmcnt(0)
	s_barrier
	ds_read2_b32 v[2:3], v16 offset1:65
	ds_read2_b32 v[4:5], v16 offset0:130 offset1:195
	s_add_i32 s8, s10, s13
	s_ashr_i32 s9, s8, 31
	s_add_i32 s11, s11, s33
	s_waitcnt lgkmcnt(1)
	v_mul_f32_e32 v8, 0x43800000, v2
	v_add_u32_e32 v2, 0x400, v16
	ds_read2_b32 v[6:7], v2 offset0:4 offset1:69
	v_mul_f32_e32 v9, 0x43800000, v3
	ds_read2_b32 v[2:3], v2 offset0:134 offset1:199
	s_waitcnt lgkmcnt(2)
	v_mul_f32_e32 v4, 0x43800000, v4
	v_mul_f32_e32 v5, 0x43800000, v5
	s_waitcnt lgkmcnt(1)
	v_mul_f32_e32 v6, 0x43800000, v6
	v_mul_f32_e32 v7, 0x43800000, v7
	s_waitcnt lgkmcnt(0)
	v_mul_f32_e32 v17, 0x43800000, v2
	v_mul_f32_e32 v18, 0x43800000, v3
	v_med3_f32 v3, v8, s93, v223
	v_med3_f32 v8, v9, s93, v223
	v_mov_b32_e32 v2, v1
	v_cvt_pk_fp8_f32 v2, v3, v8
	v_med3_f32 v6, v6, s93, v223
	v_med3_f32 v7, v7, s93, v223
	v_mov_b32_e32 v3, v1
	v_cvt_pk_fp8_f32 v3, v6, v7
	v_med3_f32 v4, v4, s93, v223
	v_med3_f32 v5, v5, s93, v223
	v_cvt_pk_fp8_f32 v2, v4, v5 op_sel:[0,0,1]
	v_med3_f32 v4, v17, s93, v223
	v_med3_f32 v5, v18, s93, v223
	v_cvt_pk_fp8_f32 v3, v4, v5 op_sel:[0,0,1]
	v_add_u32_e32 v4, s12, v11
	v_ashrrev_i32_e32 v5, 31, v4
	v_lshlrev_b64 v[4:5], 11, v[4:5]
	v_lshl_add_u64 v[4:5], s[6:7], 0, v[4:5]
	v_lshl_add_u64 v[4:5], v[4:5], 0, s[8:9]
	s_add_i32 s10, s10, s92
	v_lshl_add_u64 v[4:5], v[4:5], 0, v[0:1]
	s_cmpk_lt_i32 s11, 0x500
	global_store_dwordx2 v[4:5], v[2:3], off
	s_cbranch_scc0 .Lcw6_x2
	s_ashr_i32 s8, s11, 31
	s_lshr_b32 s8, s8, 27
	s_add_i32 s8, s11, s8
	s_ashr_i32 s8, s8, 5
	s_lshl_b32 s12, s8, 6
	s_lshl_b32 s9, s8, 11
	v_or_b32_e32 v17, s12, v10
	s_movk_i32 s8, 0xa00
	s_sub_i32 s13, 0, s9
	v_cmp_gt_i32_e32 vcc, s8, v17
	s_waitcnt lgkmcnt(0)
	s_barrier
	s_waitcnt vmcnt(2)
	ds_write2_b32 v14, v208, v209 offset1:1
	ds_write2_b32 v14, v210, v211 offset0:2 offset1:3
	ds_write2_b32 v15, v212, v213 offset1:1
	ds_write2_b32 v15, v214, v215 offset0:2 offset1:3
	s_waitcnt lgkmcnt(0)
	s_barrier
	ds_read2_b32 v[2:3], v16 offset1:65
	ds_read2_b32 v[4:5], v16 offset0:130 offset1:195
	s_add_i32 s8, s10, s13
	s_ashr_i32 s9, s8, 31
	s_add_i32 s11, s11, s33
	s_waitcnt lgkmcnt(1)
	v_mul_f32_e32 v8, 0x43800000, v2
	v_add_u32_e32 v2, 0x400, v16
	ds_read2_b32 v[6:7], v2 offset0:4 offset1:69
	v_mul_f32_e32 v9, 0x43800000, v3
	ds_read2_b32 v[2:3], v2 offset0:134 offset1:199
	s_waitcnt lgkmcnt(2)
	v_mul_f32_e32 v4, 0x43800000, v4
	v_mul_f32_e32 v5, 0x43800000, v5
	s_waitcnt lgkmcnt(1)
	v_mul_f32_e32 v6, 0x43800000, v6
	v_mul_f32_e32 v7, 0x43800000, v7
	s_waitcnt lgkmcnt(0)
	v_mul_f32_e32 v17, 0x43800000, v2
	v_mul_f32_e32 v18, 0x43800000, v3
	v_med3_f32 v3, v8, s93, v223
	v_med3_f32 v8, v9, s93, v223
	v_mov_b32_e32 v2, v1
	v_cvt_pk_fp8_f32 v2, v3, v8
	v_med3_f32 v6, v6, s93, v223
	v_med3_f32 v7, v7, s93, v223
	v_mov_b32_e32 v3, v1
	v_cvt_pk_fp8_f32 v3, v6, v7
	v_med3_f32 v4, v4, s93, v223
	v_med3_f32 v5, v5, s93, v223
	v_cvt_pk_fp8_f32 v2, v4, v5 op_sel:[0,0,1]
	v_med3_f32 v4, v17, s93, v223
	v_med3_f32 v5, v18, s93, v223
	v_cvt_pk_fp8_f32 v3, v4, v5 op_sel:[0,0,1]
	v_add_u32_e32 v4, s12, v11
	v_ashrrev_i32_e32 v5, 31, v4
	v_lshlrev_b64 v[4:5], 11, v[4:5]
	v_lshl_add_u64 v[4:5], s[6:7], 0, v[4:5]
	v_lshl_add_u64 v[4:5], v[4:5], 0, s[8:9]
	s_add_i32 s10, s10, s92
	v_lshl_add_u64 v[4:5], v[4:5], 0, v[0:1]
	s_cmpk_lt_i32 s11, 0x500
	global_store_dwordx2 v[4:5], v[2:3], off
	s_cbranch_scc0 .LBB0_1466
	s_branch .Lcw6_top

;     ...
;   for (int t = blockIdx.x; t < ntk * ntn; t += gridDim.x) {
;     const int tk = t % ntk, tn = t / ntk, k0 = tk * 64, n0 = tn * 64;
;     __syncthreads();
; #pragma unroll
;     for (int i = 0; i < 2; ++i) {
;       const int id = tid + 512 * i, kr = id >> 4, n4 = (id & 15) * 4;
;       f32x4 v = {0.f, 0.f, 0.f, 0.f};
;       const int nd = n0 + n4, nsrc = (nvalid < 0) ? nd : (nd < csplit ? nd + coff1 : nd + coff2);
;       if (nd < ((nvalid < 0) ? N : nvalid)) v = *(const f32x4*)(W + (size_t)(k0 + kr) * N + nsrc);
;       tile[kr * 65 + n4 + 0] = v[0]; tile[kr * 65 + n4 + 1] = v[1]; tile[kr * 65 + n4 + 2] = v[2]; tile[kr * 65 + n4 + 3] = v[3];
;     }
;     __syncthreads();
;     {
;       const int n = tid >> 3, c = tid & 7;
;       bool rot = false;
;       if (PERM == 1) rot = (n0 == rot_n0);
;       if (PERM == 2) rot = ((tn % 3) == 2);
;       const int ns = rot ? ((n >> 1) + 32 * (n & 1)) : n;
;       if (FP8) {
;         float f[8];
; #pragma unroll
;         for (int j = 0; j < 8; ++j) f[j] = tile[(c * 8 + j) * 65 + ns] * wscale;
;         u32x2 o = {pk4_fp8(f[0], f[1], f[2], f[3]), pk4_fp8(f[4], f[5], f[6], f[7])};
;         *(u32x2*)((unsigned char*)Wt + (size_t)(n0 + n) * K + k0 + c * 8) = o;
.LBB0_1468:
	s_mul_hi_i32 s8, s11, 0x2aaaaaab
	s_lshr_b32 s9, s8, 31
	s_ashr_i32 s8, s8, 2
	s_add_i32 s9, s8, s9
	s_lshl_b32 s14, s9, 6
	s_mul_i32 s8, s9, 0xfffffa00
	v_or_b32_e32 v10, s14, v2
	s_add_i32 s8, s10, s8
	v_ashrrev_i32_e32 v11, 31, v10
	v_add_u32_e32 v12, s8, v4
	v_add_u32_e32 v14, s8, v6
	v_lshl_add_u64 v[10:11], v[10:11], 2, s[0:1]
	v_mad_i64_i32 v[12:13], s[12:13], v12, s15, v[10:11]
	v_mad_i64_i32 v[14:15], s[12:13], v14, s15, v[10:11]
	s_waitcnt lgkmcnt(0)
	s_barrier
	global_load_dwordx4 v[10:13], v[12:13], off nt
	s_nop 0
	global_load_dwordx4 v[14:17], v[14:15], off nt
	s_mul_hi_i32 s12, s9, 0x55555556
	s_lshr_b32 s13, s12, 31
	v_add_u32_e32 v22, s14, v3
	s_add_i32 s14, s12, s13
	s_mul_i32 s14, s14, 3
	s_sub_i32 s9, s9, s14
	s_cmp_eq_u32 s9, 2
	v_mov_b64_e32 v[20:21], s[16:17]
	s_cselect_b64 vcc, -1, 0
	v_mad_i64_i32 v[20:21], s[12:13], v22, s20, v[20:21]
	v_cndmask_b32_e32 v22, v3, v5, vcc
	v_lshl_add_u32 v22, v22, 2, v7
	v_add_u32_e32 v23, 0x400, v22
	v_mov_b32_e32 v18, v1
	v_mov_b32_e32 v19, v1
	s_ashr_i32 s9, s8, 31
	s_add_i32 s11, s11, s33
	s_add_i32 s10, s10, s92
	s_cmpk_lt_i32 s11, 0x480
	s_waitcnt vmcnt(1)
	ds_write2_b32 v8, v10, v11 offset1:1
	ds_write2_b32 v8, v12, v13 offset0:2 offset1:3
	s_waitcnt vmcnt(0)
	ds_write2_b32 v9, v14, v15 offset1:1
	ds_write2_b32 v9, v16, v17 offset0:2 offset1:3
	s_waitcnt lgkmcnt(0)
	s_barrier
	ds_read2_b32 v[10:11], v22 offset1:65
	ds_read2_b32 v[12:13], v22 offset0:130 offset1:195
	ds_read2_b32 v[14:15], v23 offset0:4 offset1:69
	ds_read2_b32 v[16:17], v23 offset0:134 offset1:199
	s_waitcnt lgkmcnt(3)
	v_mul_f32_e32 v10, 0x43800000, v10
	v_mul_f32_e32 v11, 0x43800000, v11
	s_waitcnt lgkmcnt(1)
	v_mul_f32_e32 v14, 0x43800000, v14
	v_mul_f32_e32 v15, 0x43800000, v15
	v_med3_f32 v10, v10, s93, v223
	v_med3_f32 v11, v11, s93, v223
	v_med3_f32 v14, v14, s93, v223
	v_med3_f32 v15, v15, s93, v223
	v_cvt_pk_fp8_f32 v18, v10, v11
	v_cvt_pk_fp8_f32 v19, v14, v15
	v_mul_f32_e32 v12, 0x43800000, v12
	v_mul_f32_e32 v13, 0x43800000, v13
	s_waitcnt lgkmcnt(0)
	v_mul_f32_e32 v16, 0x43800000, v16
	v_mul_f32_e32 v17, 0x43800000, v17
	v_med3_f32 v12, v12, s93, v223
	v_med3_f32 v13, v13, s93, v223
	v_med3_f32 v10, v16, s93, v223
	v_med3_f32 v11, v17, s93, v223
	v_cvt_pk_fp8_f32 v18, v12, v13 op_sel:[0,0,1]
	v_cvt_pk_fp8_f32 v19, v10, v11 op_sel:[0,0,1]
	v_lshl_add_u64 v[10:11], v[20:21], 0, s[8:9]
	v_lshl_add_u64 v[10:11], v[10:11], 0, v[0:1]
	global_store_dwordx2 v[10:11], v[18:19], off
	s_cbranch_scc1 .LBB0_1468
	v_readlane_b32 s42, v254, 30
	v_readlane_b32 s43, v254, 31

;     ...
;   for (int t = blockIdx.x; t < ntk * ntn; t += gridDim.x) {
;     const int tk = t % ntk, tn = t / ntk, k0 = tk * 64, n0 = tn * 64;
;     __syncthreads();
; #pragma unroll
;     for (int i = 0; i < 2; ++i) {
;       const int id = tid + 512 * i, kr = id >> 4, n4 = (id & 15) * 4;
;       f32x4 v = {0.f, 0.f, 0.f, 0.f};
;       const int nd = n0 + n4, nsrc = (nvalid < 0) ? nd : (nd < csplit ? nd + coff1 : nd + coff2);
;       if (nd < ((nvalid < 0) ? N : nvalid)) v = *(const f32x4*)(W + (size_t)(k0 + kr) * N + nsrc);
;       tile[kr * 65 + n4 + 0] = v[0]; tile[kr * 65 + n4 + 1] = v[1]; tile[kr * 65 + n4 + 2] = v[2]; tile[kr * 65 + n4 + 3] = v[3];
;     }
.Lcw7_top:
	s_mov_b32 s100, s11
	s_mov_b32 s101, s10
	s_ashr_i32 s8, s100, 31
	s_lshr_b32 s8, s8, 29
	s_add_i32 s8, s100, s8
	s_ashr_i32 s8, s8, 3
	s_lshl_b32 s12, s8, 6
	s_lshl_b32 s9, s8, 9
	v_or_b32_e32 v10, s12, v12
	s_movk_i32 s8, 0x1000
	s_sub_i32 s13, 0, s9
	v_cmp_gt_i32_e32 vcc, s8, v10
	v_mov_b32_e32 v98, 0
	v_mov_b32_e32 v99, 0
	v_mov_b32_e32 v100, 0
	v_mov_b32_e32 v101, 0
	v_mov_b32_e32 v102, 0
	v_mov_b32_e32 v103, 0
	v_mov_b32_e32 v104, 0
	v_mov_b32_e32 v105, 0
	s_and_saveexec_b64 s[8:9], vcc
	s_add_i32 s14, s13, s101
	v_add_u32_e32 v116, s14, v15
	v_add_u32_e32 v122, s14, v16
	v_ashrrev_i32_e32 v117, 31, v116
	v_ashrrev_i32_e32 v123, 31, v122
	v_lshlrev_b64 v[116:117], 14, v[116:117]
	v_ashrrev_i32_e32 v11, 31, v10
	v_lshlrev_b64 v[122:123], 14, v[122:123]
	v_lshl_add_u64 v[116:117], s[0:1], 0, v[116:117]
	v_lshlrev_b64 v[118:119], 2, v[10:11]
	v_lshl_add_u64 v[122:123], s[0:1], 0, v[122:123]
	v_lshl_add_u64 v[116:117], v[116:117], 0, v[118:119]
	v_lshl_add_u64 v[118:119], v[122:123], 0, v[118:119]
	global_load_dwordx4 v[98:101], v[116:117], off nt
	s_nop 0
	global_load_dwordx4 v[102:105], v[118:119], off nt
	s_or_b64 exec, exec, s[8:9]
	s_add_i32 s100, s100, s33
	s_add_i32 s101, s101, s92
	s_cmpk_lt_i32 s100, 0x200
	s_cselect_b32 s100, s100, s11
	s_cselect_b32 s101, s101, s10
	s_ashr_i32 s8, s100, 31
	s_lshr_b32 s8, s8, 29
	s_add_i32 s8, s100, s8
	s_ashr_i32 s8, s8, 3
	s_lshl_b32 s12, s8, 6
	s_lshl_b32 s9, s8, 9
	v_or_b32_e32 v10, s12, v12
	s_movk_i32 s8, 0x1000
	s_sub_i32 s13, 0, s9
	v_cmp_gt_i32_e32 vcc, s8, v10
	v_mov_b32_e32 v106, 0
	v_mov_b32_e32 v107, 0
	v_mov_b32_e32 v108, 0
	v_mov_b32_e32 v109, 0
	v_mov_b32_e32 v110, 0
	v_mov_b32_e32 v111, 0
	v_mov_b32_e32 v112, 0
	v_mov_b32_e32 v113, 0
	s_and_saveexec_b64 s[8:9], vcc
	s_add_i32 s14, s13, s101
	v_add_u32_e32 v116, s14, v15
	v_add_u32_e32 v122, s14, v16
	v_ashrrev_i32_e32 v117, 31, v116
	v_ashrrev_i32_e32 v123, 31, v122
	v_lshlrev_b64 v[116:117], 14, v[116:117]
	v_ashrrev_i32_e32 v11, 31, v10
	v_lshlrev_b64 v[122:123], 14, v[122:123]
	v_lshl_add_u64 v[116:117], s[0:1], 0, v[116:117]
	v_lshlrev_b64 v[118:119], 2, v[10:11]
	v_lshl_add_u64 v[122:123], s[0:1], 0, v[122:123]
	v_lshl_add_u64 v[116:117], v[116:117], 0, v[118:119]
	v_lshl_add_u64 v[118:119], v[122:123], 0, v[118:119]
	global_load_dwordx4 v[106:109], v[116:117], off nt
	s_nop 0
	global_load_dwordx4 v[110:113], v[118:119], off nt
	s_or_b64 exec, exec, s[8:9]
	s_add_i32 s100, s100, s33
	s_add_i32 s101, s101, s92
	s_cmpk_lt_i32 s100, 0x200
	s_cselect_b32 s100, s100, s11
	s_cselect_b32 s101, s101, s10
	s_ashr_i32 s8, s100, 31
	s_lshr_b32 s8, s8, 29
	s_add_i32 s8, s100, s8
	s_ashr_i32 s8, s8, 3
	s_lshl_b32 s12, s8, 6
	s_lshl_b32 s9, s8, 9
	v_or_b32_e32 v10, s12, v12
	s_movk_i32 s8, 0x1000
	s_sub_i32 s13, 0, s9
	v_cmp_gt_i32_e32 vcc, s8, v10
	v_mov_b32_e32 v208, 0
	v_mov_b32_e32 v209, 0
	v_mov_b32_e32 v210, 0
	v_mov_b32_e32 v211, 0
	v_mov_b32_e32 v212, 0
	v_mov_b32_e32 v213, 0
	v_mov_b32_e32 v214, 0
	v_mov_b32_e32 v215, 0
	s_and_saveexec_b64 s[8:9], vcc
	s_add_i32 s14, s13, s101
	v_add_u32_e32 v116, s14, v15
	v_add_u32_e32 v122, s14, v16
	v_ashrrev_i32_e32 v117, 31, v116
	v_ashrrev_i32_e32 v123, 31, v122
	v_lshlrev_b64 v[116:117], 14, v[116:117]
	v_ashrrev_i32_e32 v11, 31, v10
	v_lshlrev_b64 v[122:123], 14, v[122:123]
	v_lshl_add_u64 v[116:117], s[0:1], 0, v[116:117]
	v_lshlrev_b64 v[118:119], 2, v[10:11]
	v_lshl_add_u64 v[122:123], s[0:1], 0, v[122:123]
	v_lshl_add_u64 v[116:117], v[116:117], 0, v[118:119]
	v_lshl_add_u64 v[118:119], v[122:123], 0, v[118:119]
	global_load_dwordx4 v[208:211], v[116:117], off nt
	s_nop 0
	global_load_dwordx4 v[212:215], v[118:119], off nt
	s_or_b64 exec, exec, s[8:9]
	s_ashr_i32 s8, s11, 31
	s_lshr_b32 s8, s8, 29
	s_add_i32 s8, s11, s8
	s_ashr_i32 s8, s8, 3
	s_lshl_b32 s12, s8, 6
	s_lshl_b32 s9, s8, 9
	v_or_b32_e32 v10, s12, v12
	s_movk_i32 s8, 0x1000
	s_sub_i32 s13, 0, s9
	v_cmp_gt_i32_e32 vcc, s8, v10
	s_waitcnt lgkmcnt(0)
	s_barrier
;     ...
;     __syncthreads();
;     {
;       const int n = tid >> 3, c = tid & 7;
;       bool rot = false;
;       if (PERM == 1) rot = (n0 == rot_n0);
;       if (PERM == 2) rot = ((tn % 3) == 2);
;       const int ns = rot ? ((n >> 1) + 32 * (n & 1)) : n;
;       if (FP8) {
;         float f[8];
; #pragma unroll
;         for (int j = 0; j < 8; ++j) f[j] = tile[(c * 8 + j) * 65 + ns] * wscale;
;         u32x2 o = {pk4_fp8(f[0], f[1], f[2], f[3]), pk4_fp8(f[4], f[5], f[6], f[7])};
;         *(u32x2*)((unsigned char*)Wt + (size_t)(n0 + n) * K + k0 + c * 8) = o;
;       } else {
;         u32x4 o;
; #pragma unroll
;         for (int j = 0; j < 4; ++j) o[j] = pk2(tile[(c * 8 + 2 * j) * 65 + ns], tile[(c * 8 + 2 * j + 1) * 65 + ns]);
;         *(u32x4*)(Wt + (size_t)(n0 + n) * K + k0 + c * 8) = o;
;       }
	s_waitcnt vmcnt(4)
	ds_write2_b32 v18, v98, v99 offset1:1
	ds_write2_b32 v18, v100, v101 offset0:2 offset1:3
	ds_write2_b32 v19, v102, v103 offset1:1
	ds_write2_b32 v19, v104, v105 offset0:2 offset1:3
	s_waitcnt lgkmcnt(0)
	s_barrier
	ds_read2_b32 v[2:3], v14 offset1:130
	ds_read2_b32 v[4:5], v17 offset0:65 offset1:195
	v_add_u32_e32 v6, 0x400, v17
	ds_read2_b32 v[6:7], v6 offset0:69 offset1:199
	s_add_i32 s8, s10, s13
	s_ashr_i32 s9, s8, 31
	s_waitcnt lgkmcnt(1)
	v_cvt_pk_bf16_f32 v2, v2, v4
	v_add_u32_e32 v4, 0x400, v14
	v_cvt_pk_bf16_f32 v3, v3, v5
	ds_read2_b32 v[4:5], v4 offset0:4 offset1:134
	s_add_i32 s11, s11, s33
	s_add_i32 s10, s10, s92
	s_cmpk_gt_i32 s11, 0x1ff
	s_waitcnt lgkmcnt(0)
	v_cvt_pk_bf16_f32 v4, v4, v6
	v_add_u32_e32 v6, s12, v13
	v_cvt_pk_bf16_f32 v5, v5, v7
	v_ashrrev_i32_e32 v7, 31, v6
	v_readlane_b32 s12, v253, 53
	v_lshlrev_b64 v[6:7], 10, v[6:7]
	v_readlane_b32 s13, v253, 54
	s_nop 1
	v_lshl_add_u64 v[6:7], s[12:13], 0, v[6:7]
	v_lshl_add_u64 v[6:7], s[8:9], 1, v[6:7]
	v_lshl_add_u64 v[6:7], v[6:7], 0, v[0:1]
	global_store_dwordx4 v[6:7], v[2:5], off
	s_cbranch_scc1 .Lcw7_x1
	s_ashr_i32 s8, s11, 31
	s_lshr_b32 s8, s8, 29
	s_add_i32 s8, s11, s8
	s_ashr_i32 s8, s8, 3
	s_lshl_b32 s12, s8, 6
	s_lshl_b32 s9, s8, 9
	v_or_b32_e32 v10, s12, v12
	s_movk_i32 s8, 0x1000
	s_sub_i32 s13, 0, s9
	v_cmp_gt_i32_e32 vcc, s8, v10
	s_waitcnt lgkmcnt(0)
	s_barrier
	s_waitcnt vmcnt(3)
	ds_write2_b32 v18, v106, v107 offset1:1
	ds_write2_b32 v18, v108, v109 offset0:2 offset1:3
	ds_write2_b32 v19, v110, v111 offset1:1
	ds_write2_b32 v19, v112, v113 offset0:2 offset1:3
	s_waitcnt lgkmcnt(0)
	s_barrier
	ds_read2_b32 v[2:3], v14 offset1:130
	ds_read2_b32 v[4:5], v17 offset0:65 offset1:195
	v_add_u32_e32 v6, 0x400, v17
	ds_read2_b32 v[6:7], v6 offset0:69 offset1:199
	s_add_i32 s8, s10, s13
	s_ashr_i32 s9, s8, 31
	s_waitcnt lgkmcnt(1)
	v_cvt_pk_bf16_f32 v2, v2, v4
	v_add_u32_e32 v4, 0x400, v14
	v_cvt_pk_bf16_f32 v3, v3, v5
	ds_read2_b32 v[4:5], v4 offset0:4 offset1:134
	s_add_i32 s11, s11, s33
	s_add_i32 s10, s10, s92
	s_cmpk_gt_i32 s11, 0x1ff
	s_waitcnt lgkmcnt(0)
	v_cvt_pk_bf16_f32 v4, v4, v6
	v_add_u32_e32 v6, s12, v13
	v_cvt_pk_bf16_f32 v5, v5, v7
	v_ashrrev_i32_e32 v7, 31, v6
	v_readlane_b32 s12, v253, 53
	v_lshlrev_b64 v[6:7], 10, v[6:7]
	v_readlane_b32 s13, v253, 54
	s_nop 1
	v_lshl_add_u64 v[6:7], s[12:13], 0, v[6:7]
	v_lshl_add_u64 v[6:7], s[8:9], 1, v[6:7]
	v_lshl_add_u64 v[6:7], v[6:7], 0, v[0:1]
	global_store_dwordx4 v[6:7], v[2:5], off
	s_cbranch_scc1 .Lcw7_x2
	s_ashr_i32 s8, s11, 31
	s_lshr_b32 s8, s8, 29
	s_add_i32 s8, s11, s8
	s_ashr_i32 s8, s8, 3
	s_lshl_b32 s12, s8, 6
	s_lshl_b32 s9, s8, 9
	v_or_b32_e32 v10, s12, v12
	s_movk_i32 s8, 0x1000
	s_sub_i32 s13, 0, s9
	v_cmp_gt_i32_e32 vcc, s8, v10
	s_waitcnt lgkmcnt(0)
	s_barrier
	s_waitcnt vmcnt(2)
	ds_write2_b32 v18, v208, v209 offset1:1
	ds_write2_b32 v18, v210, v211 offset0:2 offset1:3
	ds_write2_b32 v19, v212, v213 offset1:1
	ds_write2_b32 v19, v214, v215 offset0:2 offset1:3
	s_waitcnt lgkmcnt(0)
	s_barrier
	ds_read2_b32 v[2:3], v14 offset1:130
	ds_read2_b32 v[4:5], v17 offset0:65 offset1:195
	v_add_u32_e32 v6, 0x400, v17
	ds_read2_b32 v[6:7], v6 offset0:69 offset1:199
	s_add_i32 s8, s10, s13
	s_ashr_i32 s9, s8, 31
	s_waitcnt lgkmcnt(1)
	v_cvt_pk_bf16_f32 v2, v2, v4
	v_add_u32_e32 v4, 0x400, v14
	v_cvt_pk_bf16_f32 v3, v3, v5
	ds_read2_b32 v[4:5], v4 offset0:4 offset1:134
	s_add_i32 s11, s11, s33
	s_add_i32 s10, s10, s92
	s_cmpk_gt_i32 s11, 0x1ff
	s_waitcnt lgkmcnt(0)
	v_cvt_pk_bf16_f32 v4, v4, v6
	v_add_u32_e32 v6, s12, v13
	v_cvt_pk_bf16_f32 v5, v5, v7
	v_ashrrev_i32_e32 v7, 31, v6
	v_readlane_b32 s12, v253, 53
	v_lshlrev_b64 v[6:7], 10, v[6:7]
	v_readlane_b32 s13, v253, 54
	s_nop 1
	v_lshl_add_u64 v[6:7], s[12:13], 0, v[6:7]
	v_lshl_add_u64 v[6:7], s[8:9], 1, v[6:7]
	v_lshl_add_u64 v[6:7], v[6:7], 0, v[0:1]
	global_store_dwordx4 v[6:7], v[2:5], off
	s_cbranch_scc1 .LBB0_1475
	s_branch .Lcw7_top

; #define PG8_STAGE(bufoff, gbase, voff) do { _Pragma("unroll") for (int _i = 0; _i < 2; ++_i) \
;         __builtin_amdgcn_global_load_lds((const unsigned*)((const char*)(gbase) + (voff)[_i]), (PG8_LAS unsigned*)(lds + (bufoff) + ldsw + _i * 8192), 16, 0, 0); } while (0)
; #define PG8_LDA(dst, b, h) do { _Pragma("unroll") for (int m = 0; m < 4; ++m) _Pragma("unroll") for (int k = 0; k < 2; ++k) dst[m][k] = *(const PG8_LAS bf16x8*)(lds + PG8_SA(b, h) + aoff + m * 2048 + k * 1024); } while (0)
; #define PG8_LDB(dst, b, h) do { _Pragma("unroll") for (int n = 0; n < 2; ++n) _Pragma("unroll") for (int k = 0; k < 2; ++k) dst[n][k] = *(const PG8_LAS bf16x8*)(lds + PG8_SB(b, h) + boff + n * 2048 + k * 1024); } while (0)
; #define PG8_WAIT_V(n) asm volatile("s_waitcnt vmcnt(" #n ")" ::: "memory")
; #define PG8_WAIT_L(n) asm volatile("s_waitcnt lgkmcnt(" #n ")" ::: "memory")
; #define PG8_BAR __builtin_amdgcn_s_barrier()
; #define PG8_SCHED __builtin_amdgcn_sched_barrier(0)
; template <bool FP8, class Epi, class Sched>
; __device__ __forceinline__ void gemm_phase(PG8_LAS unsigned char* lds, const Gemm g, const Sched& S, const Epi& E) {
;     ...
;             PG8_LDB(B0, 0, 0); PG8_SCHED; PG8_LDA(At, 0, 0); PG8_STAGE(PG8_SA(1, 1), a1 + hstepA, voffA);
;             PG8_WAIT_L(8); PG8_BAR; PG8_WAIT_L(0); PG8_MMA(0, 0, At, B0); PG8_BAR; PG8_SCHED;
;             PG8_LDB(B1, 0, 1); PG8_STAGE(PG8_SB(0, 0), b2, voffB);
;             PG8_BAR; PG8_WAIT_L(0); PG8_MMA(0, 1, At, B1); PG8_BAR;
;             PG8_LDA(At, 0, 1); PG8_STAGE(PG8_SA(0, 0), a2, voffA);
;             PG8_BAR; PG8_WAIT_L(0); PG8_MMA(1, 0, At, B0); PG8_BAR; PG8_SCHED;
;             PG8_STAGE(PG8_SB(0, 1), b2 + hstep, voffB);
;             PG8_WAIT_V(6); PG8_BAR; PG8_MMA(1, 1, At, B1); PG8_BAR;
;             PG8_LDB(B0, 1, 0); PG8_SCHED; PG8_LDA(At, 1, 0); PG8_STAGE(PG8_SA(0, 1), a2 + hstepA, voffA);
;             PG8_WAIT_L(8); PG8_BAR; PG8_WAIT_L(0); PG8_MMA(0, 0, At, B0); PG8_BAR; PG8_SCHED;
;             PG8_LDB(B1, 1, 1); PG8_STAGE(PG8_SB(1, 0), b3, voffB);
.LBB0_1543:
	s_add_u32 s12, s16, 0x100
	s_addc_u32 s13, s17, 0
	s_add_i32 s30, 0, 0x10000
	v_add_u32_e32 v6, s30, v170
	ds_read_b128 v[10:13], v6
	ds_read_b128 v[14:17], v6 offset:1024
	ds_read_b128 v[2:5], v6 offset:2048
	ds_read_b128 v[6:9], v6 offset:3072
	s_cmp_eq_u32 s72, 20
	s_cselect_b32 s19, s1, s13
	s_cselect_b32 s18, s0, s12
	s_cselect_b32 s15, s11, s71
	s_cselect_b32 s14, s10, s70
	v_lshl_add_u64 v[18:19], s[16:17], 0, v[156:157]
	s_add_i32 m0, s24, 0xc000
	ds_read_b128 v[182:185], v172
	ds_read_b128 v[186:189], v172 offset:1024
	ds_read_b128 v[190:193], v172 offset:2048
	ds_read_b128 v[194:197], v172 offset:3072
	ds_read_b128 v[198:201], v172 offset:4096
	ds_read_b128 v[202:205], v172 offset:5120
	ds_read_b128 v[206:209], v172 offset:6144
	ds_read_b128 v[210:213], v172 offset:7168
	global_load_lds_dwordx4 v[18:19], off
	v_lshl_add_u64 v[18:19], s[16:17], 0, v[158:159]
	s_add_i32 m0, s24, 0xe000
	s_nop 0
	global_load_lds_dwordx4 v[18:19], off
	s_waitcnt lgkmcnt(8)
	s_barrier
	s_waitcnt lgkmcnt(0)
	s_setprio 1
	s_waitcnt lgkmcnt(0)
	s_nop 1
	v_mfma_scale_f32_16x16x128_f8f6f4 v[150:153], v[10:17], v[182:189], v[150:153], v168, v168 op_sel_hi:[0,0,0]
	s_nop 1
	v_mfma_scale_f32_16x16x128_f8f6f4 v[146:149], v[2:9], v[182:189], v[146:149], v168, v168 op_sel_hi:[0,0,0]
	s_nop 1
	v_mfma_scale_f32_16x16x128_f8f6f4 v[142:145], v[10:17], v[190:197], v[142:145], v168, v168 op_sel_hi:[0,0,0]
	s_nop 1
	v_mfma_scale_f32_16x16x128_f8f6f4 v[138:141], v[2:9], v[190:197], v[138:141], v168, v168 op_sel_hi:[0,0,0]
	s_nop 1
	v_mfma_scale_f32_16x16x128_f8f6f4 v[118:121], v[10:17], v[198:205], v[118:121], v168, v168 op_sel_hi:[0,0,0]
	s_nop 1
	v_mfma_scale_f32_16x16x128_f8f6f4 v[114:117], v[2:9], v[198:205], v[114:117], v168, v168 op_sel_hi:[0,0,0]
	s_nop 1
	v_mfma_scale_f32_16x16x128_f8f6f4 v[110:113], v[10:17], v[206:213], v[110:113], v168, v168 op_sel_hi:[0,0,0]
	s_nop 1
	v_mfma_scale_f32_16x16x128_f8f6f4 v[106:109], v[2:9], v[206:213], v[106:109], v168, v168 op_sel_hi:[0,0,0]
	s_setprio 0
	s_barrier
	s_add_i32 s31, 0, 0x14000
	s_add_i32 s16, s30, s23
	v_add_u32_e32 v22, s31, v170
	v_lshl_add_u64 v[160:161], s[14:15], 0, v[0:1]
	s_mov_b32 m0, s16
	ds_read_b128 v[236:239], v22
	ds_read_b128 v[240:243], v22 offset:1024
	ds_read_b128 v[18:21], v22 offset:2048
	ds_read_b128 v[22:25], v22 offset:3072
	global_load_lds_dwordx4 v[160:161], off
	v_lshl_add_u64 v[162:163], s[14:15], 0, v[154:155]
	s_add_i32 m0, s16, 0x2000
	s_nop 0
	global_load_lds_dwordx4 v[162:163], off
	s_barrier
	s_waitcnt lgkmcnt(0)
	s_setprio 1
	s_waitcnt lgkmcnt(0)
	s_nop 1
	v_mfma_scale_f32_16x16x128_f8f6f4 v[134:137], v[236:243], v[182:189], v[134:137], v168, v168 op_sel_hi:[0,0,0]
	s_nop 1
	v_mfma_scale_f32_16x16x128_f8f6f4 v[130:133], v[18:25], v[182:189], v[130:133], v168, v168 op_sel_hi:[0,0,0]
	s_nop 1
	v_mfma_scale_f32_16x16x128_f8f6f4 v[126:129], v[236:243], v[190:197], v[126:129], v168, v168 op_sel_hi:[0,0,0]
	s_nop 1
	v_mfma_scale_f32_16x16x128_f8f6f4 v[122:125], v[18:25], v[190:197], v[122:125], v168, v168 op_sel_hi:[0,0,0]
	s_nop 1
	v_mfma_scale_f32_16x16x128_f8f6f4 v[102:105], v[236:243], v[198:205], v[102:105], v168, v168 op_sel_hi:[0,0,0]
	s_nop 1
	v_mfma_scale_f32_16x16x128_f8f6f4 v[98:101], v[18:25], v[198:205], v[98:101], v168, v168 op_sel_hi:[0,0,0]
	s_nop 1
	v_mfma_scale_f32_16x16x128_f8f6f4 v[94:97], v[236:243], v[206:213], v[94:97], v168, v168 op_sel_hi:[0,0,0]
	s_nop 1
	v_mfma_scale_f32_16x16x128_f8f6f4 v[90:93], v[18:25], v[206:213], v[90:93], v168, v168 op_sel_hi:[0,0,0]
	s_setprio 0
	s_mov_b32 m0, s24
	v_lshl_add_u64 v[164:165], s[18:19], 0, v[0:1]
	s_barrier
	ds_read_b128 v[182:185], v172 offset:16384
	ds_read_b128 v[186:189], v172 offset:17408
	ds_read_b128 v[190:193], v172 offset:18432
	ds_read_b128 v[194:197], v172 offset:19456
	ds_read_b128 v[198:201], v172 offset:20480
	ds_read_b128 v[202:205], v172 offset:21504
	ds_read_b128 v[206:209], v172 offset:22528
	ds_read_b128 v[210:213], v172 offset:23552
	global_load_lds_dwordx4 v[164:165], off
	v_lshl_add_u64 v[166:167], s[18:19], 0, v[154:155]
	s_mov_b32 m0, s25
	s_nop 0
	global_load_lds_dwordx4 v[166:167], off
	s_barrier
	s_waitcnt lgkmcnt(0)
	s_setprio 1
	s_waitcnt lgkmcnt(0)
	s_nop 1
	v_mfma_scale_f32_16x16x128_f8f6f4 v[86:89], v[10:17], v[182:189], v[86:89], v168, v168 op_sel_hi:[0,0,0]
	s_nop 1
	v_mfma_scale_f32_16x16x128_f8f6f4 v[82:85], v[2:9], v[182:189], v[82:85], v168, v168 op_sel_hi:[0,0,0]
	s_nop 1
	v_mfma_scale_f32_16x16x128_f8f6f4 v[78:81], v[10:17], v[190:197], v[78:81], v168, v168 op_sel_hi:[0,0,0]
	s_nop 1
	v_mfma_scale_f32_16x16x128_f8f6f4 v[74:77], v[2:9], v[190:197], v[74:77], v168, v168 op_sel_hi:[0,0,0]
	s_nop 1
	v_mfma_scale_f32_16x16x128_f8f6f4 v[54:57], v[10:17], v[198:205], v[54:57], v168, v168 op_sel_hi:[0,0,0]
	s_nop 1
	v_mfma_scale_f32_16x16x128_f8f6f4 v[50:53], v[2:9], v[198:205], v[50:53], v168, v168 op_sel_hi:[0,0,0]
	s_nop 1
	v_mfma_scale_f32_16x16x128_f8f6f4 v[46:49], v[10:17], v[206:213], v[46:49], v168, v168 op_sel_hi:[0,0,0]
	s_nop 1
	v_mfma_scale_f32_16x16x128_f8f6f4 v[42:45], v[2:9], v[206:213], v[42:45], v168, v168 op_sel_hi:[0,0,0]
	s_setprio 0
	s_barrier
	s_add_u32 s16, s14, 0x60000
	s_addc_u32 s17, s15, 0
	s_add_i32 s30, s31, s23
	v_lshl_add_u64 v[2:3], s[16:17], 0, v[0:1]
	s_mov_b32 m0, s30
	s_nop 0
	global_load_lds_dwordx4 v[2:3], off
	v_lshl_add_u64 v[2:3], s[16:17], 0, v[154:155]
	s_add_i32 m0, s30, 0x2000
	s_nop 0
	global_load_lds_dwordx4 v[2:3], off
	s_waitcnt vmcnt(6)
	s_barrier
; #define PG8_STAGE(bufoff, gbase, voff) do { _Pragma("unroll") for (int _i = 0; _i < 2; ++_i) \
;         __builtin_amdgcn_global_load_lds((const unsigned*)((const char*)(gbase) + (voff)[_i]), (PG8_LAS unsigned*)(lds + (bufoff) + ldsw + _i * 8192), 16, 0, 0); } while (0)
; #define PG8_LDA(dst, b, h) do { _Pragma("unroll") for (int m = 0; m < 4; ++m) _Pragma("unroll") for (int k = 0; k < 2; ++k) dst[m][k] = *(const PG8_LAS bf16x8*)(lds + PG8_SA(b, h) + aoff + m * 2048 + k * 1024); } while (0)
; #define PG8_LDB(dst, b, h) do { _Pragma("unroll") for (int n = 0; n < 2; ++n) _Pragma("unroll") for (int k = 0; k < 2; ++k) dst[n][k] = *(const PG8_LAS bf16x8*)(lds + PG8_SB(b, h) + boff + n * 2048 + k * 1024); } while (0)
; #define PG8_WAIT_V(n) asm volatile("s_waitcnt vmcnt(" #n ")" ::: "memory")
; #define PG8_WAIT_L(n) asm volatile("s_waitcnt lgkmcnt(" #n ")" ::: "memory")
; #define PG8_BAR __builtin_amdgcn_s_barrier()
; #define PG8_SCHED __builtin_amdgcn_sched_barrier(0)
; template <bool FP8, class Epi, class Sched>
; __device__ __forceinline__ void gemm_phase(PG8_LAS unsigned char* lds, const Gemm g, const Sched& S, const Epi& E) {
;     ...
;             PG8_WAIT_V(6); PG8_BAR; PG8_MMA(1, 1, At, B1); PG8_BAR;
;             PG8_LDB(B0, 1, 0); PG8_SCHED; PG8_LDA(At, 1, 0); PG8_STAGE(PG8_SA(0, 1), a2 + hstepA, voffA);
;             PG8_WAIT_L(8); PG8_BAR; PG8_WAIT_L(0); PG8_MMA(0, 0, At, B0); PG8_BAR; PG8_SCHED;
;             PG8_LDB(B1, 1, 1); PG8_STAGE(PG8_SB(1, 0), b3, voffB);
;             PG8_BAR; PG8_WAIT_L(0); PG8_MMA(0, 1, At, B1); PG8_BAR;
;             PG8_LDA(At, 1, 1); PG8_STAGE(PG8_SA(1, 0), a3, voffA);
;             PG8_BAR; PG8_WAIT_L(0); PG8_MMA(1, 0, At, B0); PG8_BAR; PG8_SCHED;
	s_setprio 1
	s_nop 1
	v_mfma_scale_f32_16x16x128_f8f6f4 v[70:73], v[236:243], v[182:189], v[70:73], v168, v168 op_sel_hi:[0,0,0]
	s_nop 1
	v_mfma_scale_f32_16x16x128_f8f6f4 v[66:69], v[18:25], v[182:189], v[66:69], v168, v168 op_sel_hi:[0,0,0]
	s_nop 1
	v_mfma_scale_f32_16x16x128_f8f6f4 v[62:65], v[236:243], v[190:197], v[62:65], v168, v168 op_sel_hi:[0,0,0]
	s_nop 1
	v_mfma_scale_f32_16x16x128_f8f6f4 v[58:61], v[18:25], v[190:197], v[58:61], v168, v168 op_sel_hi:[0,0,0]
	s_nop 1
	v_mfma_scale_f32_16x16x128_f8f6f4 v[38:41], v[236:243], v[198:205], v[38:41], v168, v168 op_sel_hi:[0,0,0]
	s_nop 1
	v_mfma_scale_f32_16x16x128_f8f6f4 v[34:37], v[18:25], v[198:205], v[34:37], v168, v168 op_sel_hi:[0,0,0]
	s_nop 1
	v_mfma_scale_f32_16x16x128_f8f6f4 v[30:33], v[236:243], v[206:213], v[30:33], v168, v168 op_sel_hi:[0,0,0]
	s_nop 1
	v_mfma_scale_f32_16x16x128_f8f6f4 v[26:29], v[18:25], v[206:213], v[26:29], v168, v168 op_sel_hi:[0,0,0]
	s_setprio 0
	s_add_i32 s30, 0, 0x18000
	v_add_u32_e32 v14, s30, v170
	s_barrier
	ds_read_b128 v[2:5], v14
	ds_read_b128 v[6:9], v14 offset:1024
	ds_read_b128 v[10:13], v14 offset:2048
	ds_read_b128 v[14:17], v14 offset:3072
	s_add_u32 s16, s18, 0x60000
	s_addc_u32 s17, s19, 0
	s_mov_b32 m0, s26
	v_lshl_add_u64 v[174:175], s[16:17], 0, v[0:1]
	ds_read_b128 v[18:21], v172 offset:32768
	ds_read_b128 v[22:25], v172 offset:33792
	ds_read_b128 v[182:185], v172 offset:34816
	ds_read_b128 v[186:189], v172 offset:35840
	ds_read_b128 v[190:193], v172 offset:36864
	ds_read_b128 v[194:197], v172 offset:37888
	ds_read_b128 v[198:201], v172 offset:38912
	ds_read_b128 v[202:205], v172 offset:39936
	global_load_lds_dwordx4 v[174:175], off
	v_lshl_add_u64 v[174:175], s[16:17], 0, v[154:155]
	s_mov_b32 m0, s27
	s_nop 0
	global_load_lds_dwordx4 v[174:175], off
	s_waitcnt lgkmcnt(8)
	s_barrier
	s_waitcnt lgkmcnt(0)
	s_setprio 1
	s_waitcnt lgkmcnt(0)
	s_nop 1
	v_mfma_scale_f32_16x16x128_f8f6f4 v[150:153], v[2:9], v[18:25], v[150:153], v168, v168 op_sel_hi:[0,0,0]
	s_nop 1
	v_mfma_scale_f32_16x16x128_f8f6f4 v[146:149], v[10:17], v[18:25], v[146:149], v168, v168 op_sel_hi:[0,0,0]
	s_nop 1
	v_mfma_scale_f32_16x16x128_f8f6f4 v[142:145], v[2:9], v[182:189], v[142:145], v168, v168 op_sel_hi:[0,0,0]
	s_nop 1
	v_mfma_scale_f32_16x16x128_f8f6f4 v[138:141], v[10:17], v[182:189], v[138:141], v168, v168 op_sel_hi:[0,0,0]
	s_nop 1
	v_mfma_scale_f32_16x16x128_f8f6f4 v[118:121], v[2:9], v[190:197], v[118:121], v168, v168 op_sel_hi:[0,0,0]
	s_nop 1
	v_mfma_scale_f32_16x16x128_f8f6f4 v[114:117], v[10:17], v[190:197], v[114:117], v168, v168 op_sel_hi:[0,0,0]
	s_nop 1
	v_mfma_scale_f32_16x16x128_f8f6f4 v[110:113], v[2:9], v[198:205], v[110:113], v168, v168 op_sel_hi:[0,0,0]
	s_nop 1
	v_mfma_scale_f32_16x16x128_f8f6f4 v[106:109], v[10:17], v[198:205], v[106:109], v168, v168 op_sel_hi:[0,0,0]
	s_setprio 0
	s_barrier
	s_add_i32 s16, 0, 0x1c000
	s_add_i32 s17, s30, s23
	v_add_u32_e32 v173, s16, v170
	v_lshl_add_u64 v[160:161], v[160:161], 0, s[56:57]
	s_mov_b32 m0, s17
	ds_read_b128 v[206:209], v173
	ds_read_b128 v[210:213], v173 offset:1024
	ds_read_b128 v[236:239], v173 offset:2048
	ds_read_b128 v[240:243], v173 offset:3072
	global_load_lds_dwordx4 v[160:161], off
	v_lshl_add_u64 v[160:161], v[162:163], 0, s[56:57]
	s_add_i32 m0, s17, 0x2000
	s_nop 0
	global_load_lds_dwordx4 v[160:161], off
	s_barrier
	s_waitcnt lgkmcnt(0)
	s_setprio 1
	s_waitcnt lgkmcnt(0)
	s_nop 1
	v_mfma_scale_f32_16x16x128_f8f6f4 v[134:137], v[206:213], v[18:25], v[134:137], v168, v168 op_sel_hi:[0,0,0]
	s_nop 1
	v_mfma_scale_f32_16x16x128_f8f6f4 v[130:133], v[236:243], v[18:25], v[130:133], v168, v168 op_sel_hi:[0,0,0]
	s_nop 1
	v_mfma_scale_f32_16x16x128_f8f6f4 v[126:129], v[206:213], v[182:189], v[126:129], v168, v168 op_sel_hi:[0,0,0]
	s_nop 1
	v_mfma_scale_f32_16x16x128_f8f6f4 v[122:125], v[236:243], v[182:189], v[122:125], v168, v168 op_sel_hi:[0,0,0]
	s_nop 1
	v_mfma_scale_f32_16x16x128_f8f6f4 v[102:105], v[206:213], v[190:197], v[102:105], v168, v168 op_sel_hi:[0,0,0]
	s_nop 1
	v_mfma_scale_f32_16x16x128_f8f6f4 v[98:101], v[236:243], v[190:197], v[98:101], v168, v168 op_sel_hi:[0,0,0]
	s_nop 1
	v_mfma_scale_f32_16x16x128_f8f6f4 v[94:97], v[206:213], v[198:205], v[94:97], v168, v168 op_sel_hi:[0,0,0]
	s_nop 1
	v_mfma_scale_f32_16x16x128_f8f6f4 v[90:93], v[236:243], v[198:205], v[90:93], v168, v168 op_sel_hi:[0,0,0]
	s_setprio 0
	s_mov_b32 m0, s54
	v_lshl_add_u64 v[160:161], v[164:165], 0, s[56:57]
	s_barrier
	ds_read_b128 v[18:21], v172 offset:49152
	ds_read_b128 v[22:25], v172 offset:50176
	ds_read_b128 v[182:185], v172 offset:51200
	ds_read_b128 v[186:189], v172 offset:52224
	ds_read_b128 v[190:193], v172 offset:53248
	ds_read_b128 v[194:197], v172 offset:54272
	ds_read_b128 v[198:201], v172 offset:55296
	ds_read_b128 v[202:205], v172 offset:56320
	global_load_lds_dwordx4 v[160:161], off
	v_lshl_add_u64 v[160:161], v[166:167], 0, s[56:57]
	s_mov_b32 m0, s66
	s_nop 0
	global_load_lds_dwordx4 v[160:161], off
	s_barrier
	s_waitcnt lgkmcnt(0)
	s_setprio 1
	s_waitcnt lgkmcnt(0)
	s_nop 1
	v_mfma_scale_f32_16x16x128_f8f6f4 v[86:89], v[2:9], v[18:25], v[86:89], v168, v168 op_sel_hi:[0,0,0]
	s_nop 1
	v_mfma_scale_f32_16x16x128_f8f6f4 v[82:85], v[10:17], v[18:25], v[82:85], v168, v168 op_sel_hi:[0,0,0]
	s_nop 1
	v_mfma_scale_f32_16x16x128_f8f6f4 v[78:81], v[2:9], v[182:189], v[78:81], v168, v168 op_sel_hi:[0,0,0]
	s_nop 1
	v_mfma_scale_f32_16x16x128_f8f6f4 v[74:77], v[10:17], v[182:189], v[74:77], v168, v168 op_sel_hi:[0,0,0]
	s_nop 1
	v_mfma_scale_f32_16x16x128_f8f6f4 v[54:57], v[2:9], v[190:197], v[54:57], v168, v168 op_sel_hi:[0,0,0]
	s_nop 1
	v_mfma_scale_f32_16x16x128_f8f6f4 v[50:53], v[10:17], v[190:197], v[50:53], v168, v168 op_sel_hi:[0,0,0]
	s_nop 1
	v_mfma_scale_f32_16x16x128_f8f6f4 v[46:49], v[2:9], v[198:205], v[46:49], v168, v168 op_sel_hi:[0,0,0]
	s_nop 1
	v_mfma_scale_f32_16x16x128_f8f6f4 v[42:45], v[10:17], v[198:205], v[42:45], v168, v168 op_sel_hi:[0,0,0]
	s_setprio 0
	s_barrier
; #define PG8_STAGE(bufoff, gbase, voff) do { _Pragma("unroll") for (int _i = 0; _i < 2; ++_i) \
;         __builtin_amdgcn_global_load_lds((const unsigned*)((const char*)(gbase) + (voff)[_i]), (PG8_LAS unsigned*)(lds + (bufoff) + ldsw + _i * 8192), 16, 0, 0); } while (0)
; #define PG8_WAIT_V(n) asm volatile("s_waitcnt vmcnt(" #n ")" ::: "memory")
; #define PG8_BAR __builtin_amdgcn_s_barrier()
; template <bool FP8, class Epi, class Sched>
; __device__ __forceinline__ void gemm_phase(PG8_LAS unsigned char* lds, const Gemm g, const Sched& S, const Epi& E) {
;     ...
;             PG8_STAGE(PG8_SB(1, 1), b3 + hstep, voffB);
;             PG8_WAIT_V(6); PG8_BAR; PG8_MMA(1, 1, At, B1); PG8_BAR;
;   DI void operator()(const f32x4 (&acc)[2][2][4][2], const pg8::Unit& u, int wr, int wc, int fr, int fq) const {
;     const int row0 = u.pm * 256 + wr * 64 + fr, col0 = u.pn * 256 + wc * 32 + 4 * fq;
; #pragma unroll
;     for (int ai = 0; ai < 2; ++ai)
; #pragma unroll
;       for (int mp = 0; mp < 2; ++mp) {
;         f32x4 xv[2][2][2];
; #pragma unroll
;         for (int mm = 0; mm < 2; ++mm)
; #pragma unroll
;           for (int bj = 0; bj < 2; ++bj)
; #pragma unroll
;             for (int n = 0; n < 2; ++n)
;               xv[mm][bj][n] = *(const f32x4*)(xin + (size_t)(row0 + ai * 128 + (mp * 2 + mm) * 16) * 2048 + col0 + bj * 128 + n * 16);
; #pragma unroll
;         for (int mm = 0; mm < 2; ++mm)
; #pragma unroll
;           for (int bj = 0; bj < 2; ++bj)
; #pragma unroll
;             for (int n = 0; n < 2; ++n)
;               *(f32x4*)(xout + (size_t)(row0 + ai * 128 + (mp * 2 + mm) * 16) * 2048 + col0 + bj * 128 + n * 16) = xv[mm][bj][n] + acc[ai][bj][mp * 2 + mm][n] * sc;
;         asm volatile("" ::: "memory");
;       }
	s_add_u32 s14, s14, 0x60080
	s_addc_u32 s15, s15, 0
	s_add_i32 s16, s16, s23
	v_lshl_add_u64 v[2:3], s[14:15], 0, v[0:1]
	s_mov_b32 m0, s16
	s_nop 0
	global_load_lds_dwordx4 v[2:3], off
	v_lshl_add_u64 v[2:3], s[14:15], 0, v[154:155]
	s_add_i32 m0, s16, 0x2000
	s_nop 0
	global_load_lds_dwordx4 v[2:3], off
	s_waitcnt vmcnt(6)
	s_barrier
	s_setprio 1
	s_nop 1
	v_mfma_scale_f32_16x16x128_f8f6f4 v[70:73], v[206:213], v[18:25], v[70:73], v168, v168 op_sel_hi:[0,0,0]
	s_nop 1
	v_mfma_scale_f32_16x16x128_f8f6f4 v[66:69], v[236:243], v[18:25], v[66:69], v168, v168 op_sel_hi:[0,0,0]
	s_nop 1
	v_mfma_scale_f32_16x16x128_f8f6f4 v[62:65], v[206:213], v[182:189], v[62:65], v168, v168 op_sel_hi:[0,0,0]
	s_nop 1
	v_mfma_scale_f32_16x16x128_f8f6f4 v[58:61], v[236:243], v[182:189], v[58:61], v168, v168 op_sel_hi:[0,0,0]
	s_nop 1
	v_mfma_scale_f32_16x16x128_f8f6f4 v[38:41], v[206:213], v[190:197], v[38:41], v168, v168 op_sel_hi:[0,0,0]
	s_nop 1
	v_mfma_scale_f32_16x16x128_f8f6f4 v[34:37], v[236:243], v[190:197], v[34:37], v168, v168 op_sel_hi:[0,0,0]
	s_nop 1
	v_mfma_scale_f32_16x16x128_f8f6f4 v[30:33], v[206:213], v[198:205], v[30:33], v168, v168 op_sel_hi:[0,0,0]
	s_nop 1
	v_mfma_scale_f32_16x16x128_f8f6f4 v[26:29], v[236:243], v[198:205], v[26:29], v168, v168 op_sel_hi:[0,0,0]
	s_setprio 0
	s_add_i32 s72, s72, 2
	s_add_u32 s70, s70, 0x100
	s_addc_u32 s71, s71, 0
	s_cmp_gt_u32 s72, 21
	s_mov_b64 s[16:17], s[12:13]
	s_barrier
	s_cbranch_scc0 .LBB0_1543
	v_lshl_or_b32 v2, s28, 8, v171
	v_lshl_add_u32 v8, s29, 8, v169
	v_ashrrev_i32_e32 v3, 31, v2
	v_readlane_b32 s12, v254, 47
	v_lshlrev_b64 v[2:3], 2, v[2:3]
	v_readlane_b32 s13, v254, 48
	v_ashrrev_i32_e32 v9, 31, v8
	v_lshlrev_b64 v[6:7], 13, v[8:9]
	v_lshl_add_u64 v[4:5], s[12:13], 0, v[2:3]
	s_nop 15
	s_nop 15
	v_lshl_add_u64 v[22:23], v[4:5], 0, v[6:7]
	global_load_dwordx4 v[10:13], v[22:23], off nt
	global_load_dwordx4 v[14:17], v[22:23], off offset:64 nt
	global_load_dwordx4 v[18:21], v[22:23], off offset:512 nt
	s_nop 0
	global_load_dwordx4 v[22:25], v[22:23], off offset:576 nt
	v_or_b32_e32 v160, 16, v8
	v_ashrrev_i32_e32 v161, 31, v160
	v_lshlrev_b64 v[174:175], 13, v[160:161]
	v_lshl_add_u64 v[186:187], v[4:5], 0, v[174:175]
	global_load_dwordx4 v[160:163], v[186:187], off nt
	global_load_dwordx4 v[164:167], v[186:187], off offset:64 nt
	global_load_dwordx4 v[182:185], v[186:187], off offset:512 nt
	s_nop 0
	global_load_dwordx4 v[186:189], v[186:187], off offset:576 nt
	s_mov_b64 s[12:13], 0x120000
	s_and_b64 vcc, exec, s[8:9]
	s_mov_b32 s28, s68
	s_mov_b32 s29, s69
	s_mov_b64 s[16:17], s[0:1]
	s_waitcnt vmcnt(0)
	v_pk_fma_f32 v[10:11], v[150:151], s[88:89], v[10:11] op_sel_hi:[1,0,1]
	v_lshl_add_u64 v[150:151], s[80:81], 0, v[6:7]
	v_pk_fma_f32 v[12:13], v[152:153], s[88:89], v[12:13] op_sel_hi:[1,0,1]
	v_lshl_add_u64 v[150:151], v[150:151], 0, v[2:3]
	global_store_dwordx4 v[150:151], v[10:13], off
	s_nop 1
	v_pk_fma_f32 v[12:13], v[148:149], s[88:89], v[16:17] op_sel_hi:[1,0,1]
	v_pk_fma_f32 v[10:11], v[146:147], s[88:89], v[14:15] op_sel_hi:[1,0,1]
	global_store_dwordx4 v[150:151], v[10:13], off offset:64
	v_lshl_add_u64 v[14:15], s[80:81], 0, v[174:175]
	v_lshl_add_u64 v[14:15], v[14:15], 0, v[2:3]
	v_pk_fma_f32 v[12:13], v[136:137], s[88:89], v[20:21] op_sel_hi:[1,0,1]
	v_pk_fma_f32 v[10:11], v[134:135], s[88:89], v[18:19] op_sel_hi:[1,0,1]
	global_store_dwordx4 v[150:151], v[10:13], off offset:512
	s_nop 1
	v_pk_fma_f32 v[12:13], v[132:133], s[88:89], v[24:25] op_sel_hi:[1,0,1]
	v_pk_fma_f32 v[10:11], v[130:131], s[88:89], v[22:23] op_sel_hi:[1,0,1]
	global_store_dwordx4 v[150:151], v[10:13], off offset:576
	s_nop 1
	v_pk_fma_f32 v[12:13], v[144:145], s[88:89], v[162:163] op_sel_hi:[1,0,1]
	v_pk_fma_f32 v[10:11], v[142:143], s[88:89], v[160:161] op_sel_hi:[1,0,1]
	global_store_dwordx4 v[14:15], v[10:13], off
	s_nop 1
	v_pk_fma_f32 v[12:13], v[140:141], s[88:89], v[166:167] op_sel_hi:[1,0,1]
	v_pk_fma_f32 v[10:11], v[138:139], s[88:89], v[164:165] op_sel_hi:[1,0,1]
	global_store_dwordx4 v[14:15], v[10:13], off offset:64
	s_nop 1
	v_pk_fma_f32 v[12:13], v[128:129], s[88:89], v[184:185] op_sel_hi:[1,0,1]
	v_pk_fma_f32 v[10:11], v[126:127], s[88:89], v[182:183] op_sel_hi:[1,0,1]
	global_store_dwordx4 v[14:15], v[10:13], off offset:512
	s_nop 1
	v_pk_fma_f32 v[12:13], v[124:125], s[88:89], v[188:189] op_sel_hi:[1,0,1]
	v_pk_fma_f32 v[10:11], v[122:123], s[88:89], v[186:187] op_sel_hi:[1,0,1]
	global_store_dwordx4 v[14:15], v[10:13], off offset:576
	s_nop 1
	v_or_b32_e32 v10, 32, v8
	v_ashrrev_i32_e32 v11, 31, v10
	v_lshlrev_b64 v[138:139], 13, v[10:11]
	v_lshl_add_u64 v[22:23], v[4:5], 0, v[138:139]
	global_load_dwordx4 v[10:13], v[22:23], off nt
	global_load_dwordx4 v[14:17], v[22:23], off offset:64 nt
	global_load_dwordx4 v[18:21], v[22:23], off offset:512 nt
	s_nop 0
	global_load_dwordx4 v[22:25], v[22:23], off offset:576 nt
	v_or_b32_e32 v8, 48, v8
	v_ashrrev_i32_e32 v9, 31, v8
	v_lshlrev_b64 v[140:141], 13, v[8:9]
	v_lshl_add_u64 v[8:9], v[4:5], 0, v[140:141]
	global_load_dwordx4 v[122:125], v[8:9], off nt
	global_load_dwordx4 v[126:129], v[8:9], off offset:64 nt
	global_load_dwordx4 v[130:133], v[8:9], off offset:512 nt
	global_load_dwordx4 v[134:137], v[8:9], off offset:576 nt
	v_lshl_add_u64 v[8:9], s[80:81], 0, v[138:139]
	s_waitcnt vmcnt(0)
;   DI void operator()(const f32x4 (&acc)[2][2][4][2], const pg8::Unit& u, int wr, int wc, int fr, int fq) const {
;     const int row0 = u.pm * 256 + wr * 64 + fr, col0 = u.pn * 256 + wc * 32 + 4 * fq;
; #pragma unroll
;     for (int ai = 0; ai < 2; ++ai)
; #pragma unroll
;       for (int mp = 0; mp < 2; ++mp) {
;         f32x4 xv[2][2][2];
; #pragma unroll
;         for (int mm = 0; mm < 2; ++mm)
; #pragma unroll
;           for (int bj = 0; bj < 2; ++bj)
; #pragma unroll
;             for (int n = 0; n < 2; ++n)
;               xv[mm][bj][n] = *(const f32x4*)(xin + (size_t)(row0 + ai * 128 + (mp * 2 + mm) * 16) * 2048 + col0 + bj * 128 + n * 16);
; #pragma unroll
;         for (int mm = 0; mm < 2; ++mm)
; #pragma unroll
;           for (int bj = 0; bj < 2; ++bj)
; #pragma unroll
;             for (int n = 0; n < 2; ++n)
;               *(f32x4*)(xout + (size_t)(row0 + ai * 128 + (mp * 2 + mm) * 16) * 2048 + col0 + bj * 128 + n * 16) = xv[mm][bj][n] + acc[ai][bj][mp * 2 + mm][n] * sc;
;         asm volatile("" ::: "memory");
;       }
;   }
	v_pk_fma_f32 v[12:13], v[120:121], s[88:89], v[12:13] op_sel_hi:[1,0,1]
	v_pk_fma_f32 v[10:11], v[118:119], s[88:89], v[10:11] op_sel_hi:[1,0,1]
	v_lshl_add_u64 v[118:119], v[8:9], 0, v[2:3]
	global_store_dwordx4 v[118:119], v[10:13], off
	v_pk_fma_f32 v[8:9], v[114:115], s[88:89], v[14:15] op_sel_hi:[1,0,1]
	s_nop 0
	v_pk_fma_f32 v[10:11], v[116:117], s[88:89], v[16:17] op_sel_hi:[1,0,1]
	global_store_dwordx4 v[118:119], v[8:11], off offset:64
	v_lshl_add_u64 v[12:13], s[80:81], 0, v[140:141]
	v_lshl_add_u64 v[12:13], v[12:13], 0, v[2:3]
	v_pk_fma_f32 v[10:11], v[104:105], s[88:89], v[20:21] op_sel_hi:[1,0,1]
	v_pk_fma_f32 v[8:9], v[102:103], s[88:89], v[18:19] op_sel_hi:[1,0,1]
	global_store_dwordx4 v[118:119], v[8:11], off offset:512
	s_nop 1
	v_pk_fma_f32 v[10:11], v[100:101], s[88:89], v[24:25] op_sel_hi:[1,0,1]
	v_pk_fma_f32 v[8:9], v[98:99], s[88:89], v[22:23] op_sel_hi:[1,0,1]
	global_store_dwordx4 v[118:119], v[8:11], off offset:576
	v_lshl_add_u64 v[24:25], v[6:7], 0, s[60:61]
	v_lshl_add_u64 v[20:21], v[4:5], 0, v[24:25]
	v_pk_fma_f32 v[10:11], v[112:113], s[88:89], v[124:125] op_sel_hi:[1,0,1]
	v_pk_fma_f32 v[8:9], v[110:111], s[88:89], v[122:123] op_sel_hi:[1,0,1]
	global_store_dwordx4 v[12:13], v[8:11], off
	v_lshl_add_u64 v[24:25], s[80:81], 0, v[24:25]
	v_lshl_add_u64 v[24:25], v[24:25], 0, v[2:3]
	v_pk_fma_f32 v[10:11], v[108:109], s[88:89], v[128:129] op_sel_hi:[1,0,1]
	v_pk_fma_f32 v[8:9], v[106:107], s[88:89], v[126:127] op_sel_hi:[1,0,1]
	global_store_dwordx4 v[12:13], v[8:11], off offset:64
	v_lshl_add_u64 v[106:107], v[6:7], 0, s[12:13]
	v_lshl_add_u64 v[102:103], v[4:5], 0, v[106:107]
	v_pk_fma_f32 v[10:11], v[96:97], s[88:89], v[132:133] op_sel_hi:[1,0,1]
	v_pk_fma_f32 v[8:9], v[94:95], s[88:89], v[130:131] op_sel_hi:[1,0,1]
	global_store_dwordx4 v[12:13], v[8:11], off offset:512
	s_mov_b64 s[12:13], 0x140000
	s_nop 0
	v_pk_fma_f32 v[10:11], v[92:93], s[88:89], v[136:137] op_sel_hi:[1,0,1]
	v_pk_fma_f32 v[8:9], v[90:91], s[88:89], v[134:135] op_sel_hi:[1,0,1]
	global_store_dwordx4 v[12:13], v[8:11], off offset:576
	global_load_dwordx4 v[8:11], v[20:21], off nt
	global_load_dwordx4 v[12:15], v[20:21], off offset:64 nt
	global_load_dwordx4 v[16:19], v[20:21], off offset:512 nt
	s_nop 0
	global_load_dwordx4 v[20:23], v[20:21], off offset:576 nt
	s_nop 0
	global_load_dwordx4 v[90:93], v[102:103], off nt
	global_load_dwordx4 v[94:97], v[102:103], off offset:64 nt
	global_load_dwordx4 v[98:101], v[102:103], off offset:512 nt
	s_nop 0
	global_load_dwordx4 v[102:105], v[102:103], off offset:576 nt
	s_waitcnt vmcnt(0)
	v_pk_fma_f32 v[10:11], v[88:89], s[88:89], v[10:11] op_sel_hi:[1,0,1]
	v_pk_fma_f32 v[8:9], v[86:87], s[88:89], v[8:9] op_sel_hi:[1,0,1]
	global_store_dwordx4 v[24:25], v[8:11], off
	s_nop 1
	v_pk_fma_f32 v[10:11], v[84:85], s[88:89], v[14:15] op_sel_hi:[1,0,1]
	v_pk_fma_f32 v[8:9], v[82:83], s[88:89], v[12:13] op_sel_hi:[1,0,1]
	global_store_dwordx4 v[24:25], v[8:11], off offset:64
	v_lshl_add_u64 v[12:13], s[80:81], 0, v[106:107]
	v_lshl_add_u64 v[12:13], v[12:13], 0, v[2:3]
	v_pk_fma_f32 v[10:11], v[72:73], s[88:89], v[18:19] op_sel_hi:[1,0,1]
	v_pk_fma_f32 v[8:9], v[70:71], s[88:89], v[16:17] op_sel_hi:[1,0,1]
	global_store_dwordx4 v[24:25], v[8:11], off offset:512
	s_nop 1
	v_pk_fma_f32 v[10:11], v[68:69], s[88:89], v[22:23] op_sel_hi:[1,0,1]
	v_pk_fma_f32 v[8:9], v[66:67], s[88:89], v[20:21] op_sel_hi:[1,0,1]
	global_store_dwordx4 v[24:25], v[8:11], off offset:576
	v_lshl_add_u64 v[24:25], v[6:7], 0, s[12:13]
	v_lshl_add_u64 v[20:21], v[4:5], 0, v[24:25]
	v_pk_fma_f32 v[10:11], v[80:81], s[88:89], v[92:93] op_sel_hi:[1,0,1]
	v_pk_fma_f32 v[8:9], v[78:79], s[88:89], v[90:91] op_sel_hi:[1,0,1]
	global_store_dwordx4 v[12:13], v[8:11], off
	s_mov_b64 s[12:13], 0x160000
	v_lshl_add_u64 v[70:71], v[6:7], 0, s[12:13]
	v_pk_fma_f32 v[10:11], v[76:77], s[88:89], v[96:97] op_sel_hi:[1,0,1]
	v_pk_fma_f32 v[8:9], v[74:75], s[88:89], v[94:95] op_sel_hi:[1,0,1]
	global_store_dwordx4 v[12:13], v[8:11], off offset:64
	v_lshl_add_u64 v[66:67], v[4:5], 0, v[70:71]
	v_lshl_add_u64 v[24:25], s[80:81], 0, v[24:25]
	v_pk_fma_f32 v[10:11], v[64:65], s[88:89], v[100:101] op_sel_hi:[1,0,1]
	v_pk_fma_f32 v[8:9], v[62:63], s[88:89], v[98:99] op_sel_hi:[1,0,1]
	global_store_dwordx4 v[12:13], v[8:11], off offset:512
	v_lshl_add_u64 v[24:25], v[24:25], 0, v[2:3]
	s_mov_b64 s[12:13], s[10:11]
	v_pk_fma_f32 v[10:11], v[60:61], s[88:89], v[104:105] op_sel_hi:[1,0,1]
	v_pk_fma_f32 v[8:9], v[58:59], s[88:89], v[102:103] op_sel_hi:[1,0,1]
	global_store_dwordx4 v[12:13], v[8:11], off offset:576
	global_load_dwordx4 v[8:11], v[20:21], off nt
	global_load_dwordx4 v[12:15], v[20:21], off offset:64 nt
	global_load_dwordx4 v[16:19], v[20:21], off offset:512 nt
	s_nop 0
	global_load_dwordx4 v[20:23], v[20:21], off offset:576 nt
	s_nop 0
	global_load_dwordx4 v[4:7], v[66:67], off nt
	global_load_dwordx4 v[58:61], v[66:67], off offset:64 nt
	global_load_dwordx4 v[62:65], v[66:67], off offset:512 nt
	s_nop 0
	global_load_dwordx4 v[66:69], v[66:67], off offset:576 nt
	s_waitcnt vmcnt(0)
	v_pk_fma_f32 v[10:11], v[56:57], s[88:89], v[10:11] op_sel_hi:[1,0,1]
	v_pk_fma_f32 v[8:9], v[54:55], s[88:89], v[8:9] op_sel_hi:[1,0,1]
	global_store_dwordx4 v[24:25], v[8:11], off
	v_pk_fma_f32 v[6:7], v[48:49], s[88:89], v[6:7] op_sel_hi:[1,0,1]
	v_pk_fma_f32 v[4:5], v[46:47], s[88:89], v[4:5] op_sel_hi:[1,0,1]
	v_pk_fma_f32 v[10:11], v[52:53], s[88:89], v[14:15] op_sel_hi:[1,0,1]
	v_pk_fma_f32 v[8:9], v[50:51], s[88:89], v[12:13] op_sel_hi:[1,0,1]
	global_store_dwordx4 v[24:25], v[8:11], off offset:64
	s_nop 1
	v_pk_fma_f32 v[10:11], v[40:41], s[88:89], v[18:19] op_sel_hi:[1,0,1]
	v_pk_fma_f32 v[8:9], v[38:39], s[88:89], v[16:17] op_sel_hi:[1,0,1]
	global_store_dwordx4 v[24:25], v[8:11], off offset:512
	s_nop 1
	v_pk_fma_f32 v[10:11], v[36:37], s[88:89], v[22:23] op_sel_hi:[1,0,1]
	v_pk_fma_f32 v[8:9], v[34:35], s[88:89], v[20:21] op_sel_hi:[1,0,1]
	global_store_dwordx4 v[24:25], v[8:11], off offset:576
	s_nop 1
	v_lshl_add_u64 v[8:9], s[80:81], 0, v[70:71]
	v_lshl_add_u64 v[8:9], v[8:9], 0, v[2:3]
	global_store_dwordx4 v[8:9], v[4:7], off
	v_pk_fma_f32 v[2:3], v[42:43], s[88:89], v[58:59] op_sel_hi:[1,0,1]
	s_nop 0
	v_pk_fma_f32 v[4:5], v[44:45], s[88:89], v[60:61] op_sel_hi:[1,0,1]
	global_store_dwordx4 v[8:9], v[2:5], off offset:64
	s_nop 1
	v_pk_fma_f32 v[4:5], v[32:33], s[88:89], v[64:65] op_sel_hi:[1,0,1]
	v_pk_fma_f32 v[2:3], v[30:31], s[88:89], v[62:63] op_sel_hi:[1,0,1]
	global_store_dwordx4 v[8:9], v[2:5], off offset:512
	s_nop 1
	v_pk_fma_f32 v[4:5], v[28:29], s[88:89], v[68:69] op_sel_hi:[1,0,1]
	v_pk_fma_f32 v[2:3], v[26:27], s[88:89], v[66:67] op_sel_hi:[1,0,1]
	global_store_dwordx4 v[8:9], v[2:5], off offset:576
	s_cbranch_vccz .LBB0_1532
	s_waitcnt vmcnt(0)
	s_cmpk_gt_u32 s22, 0xff
	v_readlane_b32 s28, v254, 27
	v_readlane_b32 s29, v254, 28
	s_cbranch_scc1 .LBB0_1547
	s_barrier

; template <bool F32OUT>
; DI void rmsnorm_rows(const float* X, const float* __restrict__ g, void* outp, int nrows, unsigned char* __restrict__ out8 = nullptr) {
;     ...
;   for (int row = gw; row < nrows; row += nw) {
;     const f32x4* xr = (const f32x4*)(X + (size_t)row * 2048);
;     f32x4 v[8];
;     float ss = 0.f;
; #pragma unroll
;     for (int i = 0; i < 8; ++i) { v[i] = xr[lane + 64 * i]; ss += v[i][0] * v[i][0] + v[i][1] * v[i][1] + v[i][2] * v[i][2] + v[i][3] * v[i][3]; }
;     ss = wave_sum(ss);
;     const float r = rsqrtf(ss * (1.f / 2048.f) + 1e-6f);
; #pragma unroll
;     for (int i = 0; i < 8; ++i) {
;       const f32x4 gg = ((const f32x4*)g)[lane + 64 * i];
;       f32x4 o = {v[i][0] * r * gg[0], v[i][1] * r * gg[1], v[i][2] * r * gg[2], v[i][3] * r * gg[3]};
;       if (F32OUT) ((f32x4*)((float*)outp + (size_t)row * 2048))[lane + 64 * i] = o;
;       else { u32x2 pk = {pk2(o[0], o[1]), pk2(o[2], o[3])}; ((u32x2*)((u16*)outp + (size_t)row * 2048))[lane + 64 * i] = pk; }
.LBB0_1609:
	global_load_dwordx4 v[42:45], v[34:35], off offset:-4096 nt
	global_load_dwordx4 v[46:49], v[34:35], off offset:-3072 nt
	global_load_dwordx4 v[50:53], v[34:35], off offset:-2048 nt
	global_load_dwordx4 v[54:57], v[34:35], off offset:-1024 nt
	global_load_dwordx4 v[58:61], v[34:35], off nt
	global_load_dwordx4 v[62:65], v[34:35], off offset:1024 nt
	global_load_dwordx4 v[66:69], v[34:35], off offset:2048 nt
	global_load_dwordx4 v[70:73], v[34:35], off offset:3072 nt
	v_add_u32_e32 v32, s28, v32
	v_cmp_lt_i32_e64 s[0:1], s5, v32
	s_or_b64 s[2:3], s[0:1], s[2:3]
	s_waitcnt vmcnt(7)
	v_mul_f32_e32 v90, v43, v43
	s_waitcnt vmcnt(6)
	v_mul_f32_e32 v91, v47, v47
	s_waitcnt vmcnt(5)
	v_mul_f32_e32 v92, v51, v51
	v_fmac_f32_e32 v90, v42, v42
	s_waitcnt vmcnt(3)
	v_mov_b32_e32 v76, v59
	s_waitcnt vmcnt(2)
	v_mov_b32_e32 v77, v63
	v_fmac_f32_e32 v91, v46, v46
	v_mul_f32_e32 v93, v55, v55
	v_mov_b32_e32 v74, v58
	v_mov_b32_e32 v75, v62
	v_pk_mul_f32 v[76:77], v[76:77], v[76:77]
	v_fmac_f32_e32 v92, v50, v50
	v_fmac_f32_e32 v90, v44, v44
	v_fmac_f32_e32 v91, v48, v48
	v_mov_b32_e32 v78, v60
	v_mov_b32_e32 v79, v64
	v_fmac_f32_e32 v93, v54, v54
	v_pk_fma_f32 v[74:75], v[74:75], v[74:75], v[76:77]
	v_fmac_f32_e32 v92, v52, v52
	v_fmac_f32_e32 v90, v45, v45
	v_fmac_f32_e32 v91, v49, v49
	s_waitcnt vmcnt(1)
	v_mov_b32_e32 v84, v67
	s_waitcnt vmcnt(0)
	v_mov_b32_e32 v85, v71
	v_fmac_f32_e32 v93, v56, v56
	v_fmac_f32_e32 v92, v53, v53
	v_pk_fma_f32 v[74:75], v[78:79], v[78:79], v[74:75]
	v_add_f32_e32 v78, v90, v91
	v_mov_b32_e32 v80, v61
	v_mov_b32_e32 v81, v65
	v_mov_b32_e32 v82, v66
	v_mov_b32_e32 v83, v70
	v_pk_mul_f32 v[84:85], v[84:85], v[84:85]
	v_fmac_f32_e32 v93, v57, v57
	v_add_f32_e32 v78, v78, v92
	v_mov_b32_e32 v86, v68
	v_mov_b32_e32 v87, v72
	v_pk_fma_f32 v[76:77], v[82:83], v[82:83], v[84:85]
	v_pk_fma_f32 v[74:75], v[80:81], v[80:81], v[74:75]
	v_add_f32_e32 v78, v78, v93
	v_mov_b32_e32 v88, v69
	v_mov_b32_e32 v89, v73
	v_pk_fma_f32 v[76:77], v[86:87], v[86:87], v[76:77]
	v_add_f32_e32 v74, v78, v74
	v_pk_fma_f32 v[76:77], v[88:89], v[88:89], v[76:77]
	v_add_f32_e32 v74, v74, v75
	v_add_f32_e32 v74, v74, v76
	v_add_f32_e32 v74, v74, v77
	s_nop 1
	v_add_f32_dpp v74, v74, v74 quad_perm:[1,0,3,2] row_mask:0xf bank_mask:0xf
	s_nop 1
	v_add_f32_dpp v74, v74, v74 quad_perm:[2,3,0,1] row_mask:0xf bank_mask:0xf
	s_nop 1
	v_add_f32_dpp v74, v74, v74 row_half_mirror row_mask:0xf bank_mask:0xf
	s_nop 1
	v_add_f32_dpp v74, v74, v74 row_mirror row_mask:0xf bank_mask:0xf
	v_mov_b32_e32 v75, v74
	s_nop 1
	v_permlane16_swap_b32_e32 v75, v74
	v_add_f32_e32 v74, v74, v75
	v_mov_b32_e32 v75, v74
	s_nop 1
	v_permlane32_swap_b32_e32 v75, v74
	v_add_f32_e32 v74, v74, v75
	v_fmamk_f32 v74, v74, 0x3a000000, v33
	v_mul_f32_e32 v75, 0x4b800000, v74
	v_cmp_gt_f32_e32 vcc, s4, v74
	s_nop 1
	v_cndmask_b32_e32 v74, v74, v75, vcc
	v_rsq_f32_e32 v74, v74
	s_nop 0
	v_mul_f32_e32 v75, 0x45800000, v74
	v_cndmask_b32_e32 v74, v74, v75, vcc
	v_pk_mul_f32 v[42:43], v[42:43], v[74:75] op_sel_hi:[1,0]
	v_pk_mul_f32 v[44:45], v[44:45], v[74:75] op_sel_hi:[1,0]
	v_pk_mul_f32 v[46:47], v[46:47], v[74:75] op_sel_hi:[1,0]
	v_pk_mul_f32 v[48:49], v[48:49], v[74:75] op_sel_hi:[1,0]
	v_pk_mul_f32 v[50:51], v[50:51], v[74:75] op_sel_hi:[1,0]
	v_pk_mul_f32 v[52:53], v[52:53], v[74:75] op_sel_hi:[1,0]
	v_pk_mul_f32 v[54:55], v[54:55], v[74:75] op_sel_hi:[1,0]
	v_pk_mul_f32 v[56:57], v[56:57], v[74:75] op_sel_hi:[1,0]
	v_pk_mul_f32 v[58:59], v[58:59], v[74:75] op_sel_hi:[1,0]
	v_pk_mul_f32 v[60:61], v[60:61], v[74:75] op_sel_hi:[1,0]
	v_pk_mul_f32 v[62:63], v[62:63], v[74:75] op_sel_hi:[1,0]
	v_pk_mul_f32 v[64:65], v[64:65], v[74:75] op_sel_hi:[1,0]
	v_pk_mul_f32 v[66:67], v[66:67], v[74:75] op_sel_hi:[1,0]
	v_pk_mul_f32 v[68:69], v[68:69], v[74:75] op_sel_hi:[1,0]
	v_pk_mul_f32 v[70:71], v[70:71], v[74:75] op_sel_hi:[1,0]
	v_pk_mul_f32 v[72:73], v[72:73], v[74:75] op_sel_hi:[1,0]
	v_pk_mul_f32 v[44:45], v[2:3], v[44:45]
	v_pk_mul_f32 v[42:43], v[0:1], v[42:43]
	v_pk_mul_f32 v[48:49], v[6:7], v[48:49]
	v_pk_mul_f32 v[46:47], v[4:5], v[46:47]
	v_pk_mul_f32 v[52:53], v[10:11], v[52:53]
	v_pk_mul_f32 v[50:51], v[8:9], v[50:51]
	v_pk_mul_f32 v[56:57], v[14:15], v[56:57]
	v_pk_mul_f32 v[54:55], v[12:13], v[54:55]
	v_pk_mul_f32 v[60:61], v[18:19], v[60:61]
	v_pk_mul_f32 v[58:59], v[16:17], v[58:59]
	v_pk_mul_f32 v[64:65], v[22:23], v[64:65]
	v_pk_mul_f32 v[62:63], v[20:21], v[62:63]
	v_pk_mul_f32 v[68:69], v[26:27], v[68:69]
	v_pk_mul_f32 v[66:67], v[24:25], v[66:67]
	v_pk_mul_f32 v[72:73], v[30:31], v[72:73]
	v_pk_mul_f32 v[70:71], v[28:29], v[70:71]
	global_store_dwordx4 v[34:35], v[42:45], off offset:-4096
	global_store_dwordx4 v[34:35], v[46:49], off offset:-3072
	global_store_dwordx4 v[34:35], v[50:53], off offset:-2048
	global_store_dwordx4 v[34:35], v[54:57], off offset:-1024
	global_store_dwordx4 v[34:35], v[58:61], off
	global_store_dwordx4 v[34:35], v[62:65], off offset:1024
	global_store_dwordx4 v[34:35], v[66:69], off offset:2048
	global_store_dwordx4 v[34:35], v[70:73], off offset:3072
	v_lshl_add_u64 v[34:35], v[34:35], 0, s[24:25]
	s_andn2_b64 exec, exec, s[2:3]
	s_cbranch_execnz .LBB0_1609
